# K-loop: SALU/VALU address ops between last MFMA and post-MMA s_barrier moved after the barrier (68 blocks)
# speedup vs baseline: 1.0157x; 1.0157x over previous
; #define PG8_STAGE(bufoff, gbase, voff) do { _Pragma("unroll") for (int _i = 0; _i < 2; ++_i) \
;         __builtin_amdgcn_global_load_lds((const unsigned*)((const char*)(gbase) + (voff)[_i]), (LAS unsigned*)(lds + (bufoff) + ldsw + _i * 8192), 16, 0, 0); } while (0)
; #define PG8_LDA(dst, b, h) do { _Pragma("unroll") for (int m = 0; m < 4; ++m) _Pragma("unroll") for (int k = 0; k < 2; ++k) dst[m][k] = *(const LAS bf16x8*)(lds + PG8_SA(b, h) + aoff + m * 2048 + k * 1024); } while (0)
; #define PG8_LDB(dst, b, h) do { _Pragma("unroll") for (int n = 0; n < 2; ++n) _Pragma("unroll") for (int k = 0; k < 2; ++k) dst[n][k] = *(const LAS bf16x8*)(lds + PG8_SB(b, h) + boff + n * 2048 + k * 1024); } while (0)
; #define PG8_MMA(ai, bj, At, Bt) do { __builtin_amdgcn_s_setprio(1); _Pragma("unroll") for (int m = 0; m < 4; ++m) _Pragma("unroll") for (int n = 0; n < 2; ++n) _Pragma("unroll") for (int k = 0; k < 2; ++k) \
;         acc[ai][bj][m][n] = __builtin_amdgcn_mfma_f32_16x16x32_bf16(Bt[n][k], At[m][k], acc[ai][bj][m][n], 0, 0, 0); __builtin_amdgcn_s_setprio(0); } while (0)
; #define PG8_WAIT_L(n) asm volatile("s_waitcnt lgkmcnt(" #n ")" ::: "memory")
; #define PG8_BAR __builtin_amdgcn_s_barrier()
; #define PG8_SCHED __builtin_amdgcn_sched_barrier(0)
; template <class Epi, class Sched, bool ATILE = false>
; __device__ __forceinline__ void gemm_phase(LAS unsigned char* lds, const Gemm g, const Sched& S, const Epi& E) {
;     ...
;             const bool last = (t == nt - 2);
;             const char* a1 = cA + (size_t)(t + 1) * kstepA;
;             const char* a2 = last ? nA : cA + (size_t)(t + 2) * kstepA; const char* b2 = last ? nB : cB + (size_t)(t + 2) * kstep;
;             const char* a3 = a2 + kstepA; const char* b3 = b2 + kstep;
;             PG8_LDB(B0, 0, 0); PG8_SCHED; PG8_LDA(At, 0, 0); PG8_STAGE(PG8_SA(1, 1), a1 + hstepA, voffA);
;             PG8_WAIT_L(8); PG8_BAR; PG8_WAIT_L(0); PG8_MMA(0, 0, At, B0); PG8_BAR; PG8_SCHED;
;             PG8_LDB(B1, 0, 1); PG8_STAGE(PG8_SB(0, 0), b2, voffB);
;             PG8_BAR; PG8_WAIT_L(0); PG8_MMA(0, 1, At, B1); PG8_BAR;
;             PG8_LDA(At, 0, 1); PG8_STAGE(PG8_SA(0, 0), a2, voffA);
;             PG8_BAR; PG8_WAIT_L(0); PG8_MMA(1, 0, At, B0); PG8_BAR; PG8_SCHED;
.LBB0_625:
	ds_read_b128 v[182:185], v139
	ds_read_b128 v[186:189], v139 offset:1024
	ds_read_b128 v[190:193], v139 offset:2048
	ds_read_b128 v[194:197], v139 offset:3072
	s_add_i32 s62, s28, 2
	s_add_u32 s29, s26, 0xfff80080
	s_addc_u32 s30, s27, -1
	s_cmp_eq_u32 s59, s28
	s_cselect_b32 s28, s58, s60
	s_cselect_b32 s31, s13, s30
	s_cselect_b32 s30, s56, s29
	s_cselect_b32 s29, s57, s61
	v_lshl_add_u64 v[230:231], s[26:27], 0, v[172:173]
	s_add_i32 m0, s35, 0xc000
	ds_read_b128 v[198:201], v163
	ds_read_b128 v[202:205], v163 offset:1024
	ds_read_b128 v[206:209], v163 offset:2048
	ds_read_b128 v[210:213], v163 offset:3072
	ds_read_b128 v[214:217], v163 offset:4096
	ds_read_b128 v[218:221], v163 offset:5120
	ds_read_b128 v[222:225], v163 offset:6144
	ds_read_b128 v[226:229], v163 offset:7168
	global_load_lds_dwordx4 v[230:231], off
	v_lshl_add_u64 v[230:231], s[26:27], 0, v[174:175]
	s_add_i32 m0, s35, 0xe000
	s_nop 0
	global_load_lds_dwordx4 v[230:231], off
	s_waitcnt lgkmcnt(8)
	s_barrier
	s_waitcnt lgkmcnt(0)
	s_setprio 1
	s_waitcnt lgkmcnt(0)
	v_mfma_f32_16x16x32_bf16 v[120:123], v[182:185], v[198:201], v[120:123]
	v_mfma_f32_16x16x32_bf16 v[112:115], v[190:193], v[198:201], v[112:115]
	v_mfma_f32_16x16x32_bf16 v[104:107], v[182:185], v[206:209], v[104:107]
	v_mfma_f32_16x16x32_bf16 v[96:99], v[190:193], v[206:209], v[96:99]
	v_mfma_f32_16x16x32_bf16 v[88:91], v[182:185], v[214:217], v[88:91]
	v_mfma_f32_16x16x32_bf16 v[80:83], v[190:193], v[214:217], v[80:83]
	v_mfma_f32_16x16x32_bf16 v[72:75], v[182:185], v[222:225], v[72:75]
	v_mfma_f32_16x16x32_bf16 v[64:67], v[190:193], v[222:225], v[64:67]
	v_mfma_f32_16x16x32_bf16 v[120:123], v[186:189], v[202:205], v[120:123]
	v_mfma_f32_16x16x32_bf16 v[112:115], v[194:197], v[202:205], v[112:115]
	v_mfma_f32_16x16x32_bf16 v[104:107], v[186:189], v[210:213], v[104:107]
	v_mfma_f32_16x16x32_bf16 v[96:99], v[194:197], v[210:213], v[96:99]
	v_mfma_f32_16x16x32_bf16 v[88:91], v[186:189], v[218:221], v[88:91]
	v_mfma_f32_16x16x32_bf16 v[80:83], v[194:197], v[218:221], v[80:83]
	v_mfma_f32_16x16x32_bf16 v[72:75], v[186:189], v[226:229], v[72:75]
	v_mfma_f32_16x16x32_bf16 v[64:67], v[194:197], v[226:229], v[64:67]
	s_setprio 0
	s_barrier
	s_add_i32 s63, s53, s34
	v_lshl_add_u64 v[246:247], s[28:29], 0, v[130:131]
	s_mov_b32 m0, s63
	ds_read_b128 v[230:233], v167
	ds_read_b128 v[234:237], v167 offset:1024
	ds_read_b128 v[238:241], v167 offset:2048
	ds_read_b128 v[242:245], v167 offset:3072
	global_load_lds_dwordx4 v[246:247], off
	v_lshl_add_u64 v[248:249], s[28:29], 0, v[134:135]
	s_add_i32 m0, s63, 0x2000
	s_nop 0
	global_load_lds_dwordx4 v[248:249], off
	s_barrier
	s_waitcnt lgkmcnt(0)
	s_setprio 1
	s_waitcnt lgkmcnt(0)
	v_mfma_f32_16x16x32_bf16 v[124:127], v[230:233], v[198:201], v[124:127]
	v_mfma_f32_16x16x32_bf16 v[116:119], v[238:241], v[198:201], v[116:119]
	v_mfma_f32_16x16x32_bf16 v[108:111], v[230:233], v[206:209], v[108:111]
	v_mfma_f32_16x16x32_bf16 v[100:103], v[238:241], v[206:209], v[100:103]
	v_mfma_f32_16x16x32_bf16 v[92:95], v[230:233], v[214:217], v[92:95]
	v_mfma_f32_16x16x32_bf16 v[84:87], v[238:241], v[214:217], v[84:87]
	v_mfma_f32_16x16x32_bf16 v[76:79], v[230:233], v[222:225], v[76:79]
	v_mfma_f32_16x16x32_bf16 v[68:71], v[238:241], v[222:225], v[68:71]
	v_mfma_f32_16x16x32_bf16 v[124:127], v[234:237], v[202:205], v[124:127]
	v_mfma_f32_16x16x32_bf16 v[116:119], v[242:245], v[202:205], v[116:119]
	v_mfma_f32_16x16x32_bf16 v[108:111], v[234:237], v[210:213], v[108:111]
	v_mfma_f32_16x16x32_bf16 v[100:103], v[242:245], v[210:213], v[100:103]
	v_mfma_f32_16x16x32_bf16 v[92:95], v[234:237], v[218:221], v[92:95]
	v_mfma_f32_16x16x32_bf16 v[84:87], v[242:245], v[218:221], v[84:87]
	v_mfma_f32_16x16x32_bf16 v[76:79], v[234:237], v[226:229], v[76:79]
	v_mfma_f32_16x16x32_bf16 v[68:71], v[242:245], v[226:229], v[68:71]
	s_setprio 0
	s_barrier
	s_mov_b32 m0, s35
	v_lshl_add_u64 v[250:251], s[30:31], 0, v[128:129]
	ds_read_b128 v[198:201], v163 offset:16384
	ds_read_b128 v[202:205], v163 offset:17408
	ds_read_b128 v[206:209], v163 offset:18432
	ds_read_b128 v[210:213], v163 offset:19456
	ds_read_b128 v[214:217], v163 offset:20480
	ds_read_b128 v[218:221], v163 offset:21504
	ds_read_b128 v[222:225], v163 offset:22528
	ds_read_b128 v[226:229], v163 offset:23552
	global_load_lds_dwordx4 v[250:251], off
	v_lshl_add_u64 v[252:253], s[30:31], 0, v[132:133]
	s_mov_b32 m0, s36
	s_nop 0
	global_load_lds_dwordx4 v[252:253], off
	s_barrier
	s_waitcnt lgkmcnt(0)
	s_setprio 1
	s_waitcnt lgkmcnt(0)
	v_mfma_f32_16x16x32_bf16 v[56:59], v[182:185], v[198:201], v[56:59]
	v_mfma_f32_16x16x32_bf16 v[48:51], v[190:193], v[198:201], v[48:51]
	v_mfma_f32_16x16x32_bf16 v[40:43], v[182:185], v[206:209], v[40:43]
	v_mfma_f32_16x16x32_bf16 v[32:35], v[190:193], v[206:209], v[32:35]
	v_mfma_f32_16x16x32_bf16 v[24:27], v[182:185], v[214:217], v[24:27]
	v_mfma_f32_16x16x32_bf16 v[16:19], v[190:193], v[214:217], v[16:19]
	v_mfma_f32_16x16x32_bf16 v[8:11], v[182:185], v[222:225], v[8:11]
	v_mfma_f32_16x16x32_bf16 v[4:7], v[190:193], v[222:225], v[4:7]
	v_mfma_f32_16x16x32_bf16 v[56:59], v[186:189], v[202:205], v[56:59]
	v_mfma_f32_16x16x32_bf16 v[48:51], v[194:197], v[202:205], v[48:51]
	v_mfma_f32_16x16x32_bf16 v[40:43], v[186:189], v[210:213], v[40:43]
	v_mfma_f32_16x16x32_bf16 v[32:35], v[194:197], v[210:213], v[32:35]
	v_mfma_f32_16x16x32_bf16 v[24:27], v[186:189], v[218:221], v[24:27]
	v_mfma_f32_16x16x32_bf16 v[16:19], v[194:197], v[218:221], v[16:19]
	v_mfma_f32_16x16x32_bf16 v[8:11], v[186:189], v[226:229], v[8:11]
	v_mfma_f32_16x16x32_bf16 v[4:7], v[194:197], v[226:229], v[4:7]
	s_setprio 0
	s_barrier
; #define PG8_STAGE(bufoff, gbase, voff) do { _Pragma("unroll") for (int _i = 0; _i < 2; ++_i) \
;         __builtin_amdgcn_global_load_lds((const unsigned*)((const char*)(gbase) + (voff)[_i]), (LAS unsigned*)(lds + (bufoff) + ldsw + _i * 8192), 16, 0, 0); } while (0)
; #define PG8_LDA(dst, b, h) do { _Pragma("unroll") for (int m = 0; m < 4; ++m) _Pragma("unroll") for (int k = 0; k < 2; ++k) dst[m][k] = *(const LAS bf16x8*)(lds + PG8_SA(b, h) + aoff + m * 2048 + k * 1024); } while (0)
; #define PG8_LDB(dst, b, h) do { _Pragma("unroll") for (int n = 0; n < 2; ++n) _Pragma("unroll") for (int k = 0; k < 2; ++k) dst[n][k] = *(const LAS bf16x8*)(lds + PG8_SB(b, h) + boff + n * 2048 + k * 1024); } while (0)
; #define PG8_MMA(ai, bj, At, Bt) do { __builtin_amdgcn_s_setprio(1); _Pragma("unroll") for (int m = 0; m < 4; ++m) _Pragma("unroll") for (int n = 0; n < 2; ++n) _Pragma("unroll") for (int k = 0; k < 2; ++k) \
;         acc[ai][bj][m][n] = __builtin_amdgcn_mfma_f32_16x16x32_bf16(Bt[n][k], At[m][k], acc[ai][bj][m][n], 0, 0, 0); __builtin_amdgcn_s_setprio(0); } while (0)
; #define PG8_WAIT_V(n) asm volatile("s_waitcnt vmcnt(" #n ")" ::: "memory")
; #define PG8_WAIT_L(n) asm volatile("s_waitcnt lgkmcnt(" #n ")" ::: "memory")
; #define PG8_BAR __builtin_amdgcn_s_barrier()
; #define PG8_SCHED __builtin_amdgcn_sched_barrier(0)
; template <class Epi, class Sched, bool ATILE = false>
; __device__ __forceinline__ void gemm_phase(LAS unsigned char* lds, const Gemm g, const Sched& S, const Epi& E) {
;     ...
;             PG8_STAGE(PG8_SB(0, 1), b2 + hstepB, voffB);
;             PG8_WAIT_V(6); PG8_BAR; PG8_MMA(1, 1, At, B1); PG8_BAR;
;             PG8_LDB(B0, 1, 0); PG8_SCHED; PG8_LDA(At, 1, 0); PG8_STAGE(PG8_SA(0, 1), a2 + hstepA, voffA);
;             PG8_WAIT_L(8); PG8_BAR; PG8_WAIT_L(0); PG8_MMA(0, 0, At, B0); PG8_BAR; PG8_SCHED;
;             PG8_LDB(B1, 1, 1); PG8_STAGE(PG8_SB(1, 0), b3, voffB);
;             PG8_BAR; PG8_WAIT_L(0); PG8_MMA(0, 1, At, B1); PG8_BAR;
	s_add_u32 s64, s28, 0x80000
	s_addc_u32 s65, s29, 0
	s_add_i32 s63, s54, s34
	v_lshl_add_u64 v[182:183], s[64:65], 0, v[130:131]
	s_mov_b32 m0, s63
	s_nop 0
	global_load_lds_dwordx4 v[182:183], off
	v_lshl_add_u64 v[182:183], s[64:65], 0, v[134:135]
	s_add_i32 m0, s63, 0x2000
	s_nop 0
	global_load_lds_dwordx4 v[182:183], off
	s_waitcnt vmcnt(6)
	s_barrier
	s_setprio 1
	v_mfma_f32_16x16x32_bf16 v[60:63], v[230:233], v[198:201], v[60:63]
	v_mfma_f32_16x16x32_bf16 v[52:55], v[238:241], v[198:201], v[52:55]
	v_mfma_f32_16x16x32_bf16 v[44:47], v[230:233], v[206:209], v[44:47]
	v_mfma_f32_16x16x32_bf16 v[36:39], v[238:241], v[206:209], v[36:39]
	v_mfma_f32_16x16x32_bf16 v[28:31], v[230:233], v[214:217], v[28:31]
	v_mfma_f32_16x16x32_bf16 v[20:23], v[238:241], v[214:217], v[20:23]
	v_mfma_f32_16x16x32_bf16 v[12:15], v[230:233], v[222:225], v[12:15]
	v_mfma_f32_16x16x32_bf16 v[0:3], v[238:241], v[222:225], v[0:3]
	v_mfma_f32_16x16x32_bf16 v[60:63], v[234:237], v[202:205], v[60:63]
	v_mfma_f32_16x16x32_bf16 v[52:55], v[242:245], v[202:205], v[52:55]
	v_mfma_f32_16x16x32_bf16 v[44:47], v[234:237], v[210:213], v[44:47]
	v_mfma_f32_16x16x32_bf16 v[36:39], v[242:245], v[210:213], v[36:39]
	v_mfma_f32_16x16x32_bf16 v[28:31], v[234:237], v[218:221], v[28:31]
	v_mfma_f32_16x16x32_bf16 v[20:23], v[242:245], v[218:221], v[20:23]
	v_mfma_f32_16x16x32_bf16 v[12:15], v[234:237], v[226:229], v[12:15]
	v_mfma_f32_16x16x32_bf16 v[0:3], v[242:245], v[226:229], v[0:3]
	s_setprio 0
	s_barrier
	s_add_i32 s63, 0, 0x18000
	v_add_u32_e32 v176, s63, v161
	ds_read_b128 v[182:185], v176
	ds_read_b128 v[186:189], v176 offset:1024
	ds_read_b128 v[190:193], v176 offset:2048
	ds_read_b128 v[194:197], v176 offset:3072
	s_add_u32 s30, s30, 0x80000
	s_addc_u32 s31, s31, 0
	s_mov_b32 m0, s37
	v_lshl_add_u64 v[230:231], s[30:31], 0, v[128:129]
	ds_read_b128 v[198:201], v163 offset:32768
	ds_read_b128 v[202:205], v163 offset:33792
	ds_read_b128 v[206:209], v163 offset:34816
	ds_read_b128 v[210:213], v163 offset:35840
	ds_read_b128 v[214:217], v163 offset:36864
	ds_read_b128 v[218:221], v163 offset:37888
	ds_read_b128 v[222:225], v163 offset:38912
	ds_read_b128 v[226:229], v163 offset:39936
	global_load_lds_dwordx4 v[230:231], off
	v_lshl_add_u64 v[230:231], s[30:31], 0, v[132:133]
	s_mov_b32 m0, s38
	s_nop 0
	global_load_lds_dwordx4 v[230:231], off
	s_waitcnt lgkmcnt(8)
	s_barrier
	s_waitcnt lgkmcnt(0)
	s_setprio 1
	s_waitcnt lgkmcnt(0)
	v_mfma_f32_16x16x32_bf16 v[120:123], v[182:185], v[198:201], v[120:123]
	v_mfma_f32_16x16x32_bf16 v[112:115], v[190:193], v[198:201], v[112:115]
	v_mfma_f32_16x16x32_bf16 v[104:107], v[182:185], v[206:209], v[104:107]
	v_mfma_f32_16x16x32_bf16 v[96:99], v[190:193], v[206:209], v[96:99]
	v_mfma_f32_16x16x32_bf16 v[88:91], v[182:185], v[214:217], v[88:91]
	v_mfma_f32_16x16x32_bf16 v[80:83], v[190:193], v[214:217], v[80:83]
	v_mfma_f32_16x16x32_bf16 v[72:75], v[182:185], v[222:225], v[72:75]
	v_mfma_f32_16x16x32_bf16 v[64:67], v[190:193], v[222:225], v[64:67]
	v_mfma_f32_16x16x32_bf16 v[120:123], v[186:189], v[202:205], v[120:123]
	v_mfma_f32_16x16x32_bf16 v[112:115], v[194:197], v[202:205], v[112:115]
	v_mfma_f32_16x16x32_bf16 v[104:107], v[186:189], v[210:213], v[104:107]
	v_mfma_f32_16x16x32_bf16 v[96:99], v[194:197], v[210:213], v[96:99]
	v_mfma_f32_16x16x32_bf16 v[88:91], v[186:189], v[218:221], v[88:91]
	v_mfma_f32_16x16x32_bf16 v[80:83], v[194:197], v[218:221], v[80:83]
	v_mfma_f32_16x16x32_bf16 v[72:75], v[186:189], v[226:229], v[72:75]
	v_mfma_f32_16x16x32_bf16 v[64:67], v[194:197], v[226:229], v[64:67]
	s_setprio 0
	s_barrier
	s_add_i32 s30, 0, 0x1c000
	s_add_i32 s31, s63, s34
	v_add_u32_e32 v176, s30, v161
	v_lshl_add_u64 v[246:247], v[246:247], 0, s[0:1]
	s_mov_b32 m0, s31
	ds_read_b128 v[230:233], v176
	ds_read_b128 v[234:237], v176 offset:1024
	ds_read_b128 v[238:241], v176 offset:2048
	ds_read_b128 v[242:245], v176 offset:3072
	global_load_lds_dwordx4 v[246:247], off
	v_lshl_add_u64 v[246:247], v[248:249], 0, s[0:1]
	s_add_i32 m0, s31, 0x2000
	s_nop 0
	global_load_lds_dwordx4 v[246:247], off
	s_barrier
; #define PG8_STAGE(bufoff, gbase, voff) do { _Pragma("unroll") for (int _i = 0; _i < 2; ++_i) \
;         __builtin_amdgcn_global_load_lds((const unsigned*)((const char*)(gbase) + (voff)[_i]), (LAS unsigned*)(lds + (bufoff) + ldsw + _i * 8192), 16, 0, 0); } while (0)
; #define PG8_LDA(dst, b, h) do { _Pragma("unroll") for (int m = 0; m < 4; ++m) _Pragma("unroll") for (int k = 0; k < 2; ++k) dst[m][k] = *(const LAS bf16x8*)(lds + PG8_SA(b, h) + aoff + m * 2048 + k * 1024); } while (0)
; #define PG8_MMA(ai, bj, At, Bt) do { __builtin_amdgcn_s_setprio(1); _Pragma("unroll") for (int m = 0; m < 4; ++m) _Pragma("unroll") for (int n = 0; n < 2; ++n) _Pragma("unroll") for (int k = 0; k < 2; ++k) \
;         acc[ai][bj][m][n] = __builtin_amdgcn_mfma_f32_16x16x32_bf16(Bt[n][k], At[m][k], acc[ai][bj][m][n], 0, 0, 0); __builtin_amdgcn_s_setprio(0); } while (0)
; #define PG8_WAIT_V(n) asm volatile("s_waitcnt vmcnt(" #n ")" ::: "memory")
; #define PG8_WAIT_L(n) asm volatile("s_waitcnt lgkmcnt(" #n ")" ::: "memory")
; #define PG8_BAR __builtin_amdgcn_s_barrier()
; #define PG8_SCHED __builtin_amdgcn_sched_barrier(0)
; template <class Epi, class Sched, bool ATILE = false>
; __device__ __forceinline__ void gemm_phase(LAS unsigned char* lds, const Gemm g, const Sched& S, const Epi& E) {
;     ...
;             PG8_BAR; PG8_WAIT_L(0); PG8_MMA(0, 1, At, B1); PG8_BAR;
;             PG8_LDA(At, 1, 1); PG8_STAGE(PG8_SA(1, 0), a3, voffA);
;             PG8_BAR; PG8_WAIT_L(0); PG8_MMA(1, 0, At, B0); PG8_BAR; PG8_SCHED;
;             PG8_STAGE(PG8_SB(1, 1), b3 + hstepB, voffB);
;             PG8_WAIT_V(6); PG8_BAR; PG8_MMA(1, 1, At, B1); PG8_BAR;
	s_waitcnt lgkmcnt(0)
	s_setprio 1
	s_waitcnt lgkmcnt(0)
	v_mfma_f32_16x16x32_bf16 v[124:127], v[230:233], v[198:201], v[124:127]
	v_mfma_f32_16x16x32_bf16 v[116:119], v[238:241], v[198:201], v[116:119]
	v_mfma_f32_16x16x32_bf16 v[108:111], v[230:233], v[206:209], v[108:111]
	v_mfma_f32_16x16x32_bf16 v[100:103], v[238:241], v[206:209], v[100:103]
	v_mfma_f32_16x16x32_bf16 v[92:95], v[230:233], v[214:217], v[92:95]
	v_mfma_f32_16x16x32_bf16 v[84:87], v[238:241], v[214:217], v[84:87]
	v_mfma_f32_16x16x32_bf16 v[76:79], v[230:233], v[222:225], v[76:79]
	v_mfma_f32_16x16x32_bf16 v[68:71], v[238:241], v[222:225], v[68:71]
	v_mfma_f32_16x16x32_bf16 v[124:127], v[234:237], v[202:205], v[124:127]
	v_mfma_f32_16x16x32_bf16 v[116:119], v[242:245], v[202:205], v[116:119]
	v_mfma_f32_16x16x32_bf16 v[108:111], v[234:237], v[210:213], v[108:111]
	v_mfma_f32_16x16x32_bf16 v[100:103], v[242:245], v[210:213], v[100:103]
	v_mfma_f32_16x16x32_bf16 v[92:95], v[234:237], v[218:221], v[92:95]
	v_mfma_f32_16x16x32_bf16 v[84:87], v[242:245], v[218:221], v[84:87]
	v_mfma_f32_16x16x32_bf16 v[76:79], v[234:237], v[226:229], v[76:79]
	v_mfma_f32_16x16x32_bf16 v[68:71], v[242:245], v[226:229], v[68:71]
	s_setprio 0
	s_barrier
	s_mov_b32 m0, s41
	v_lshl_add_u64 v[246:247], v[250:251], 0, s[0:1]
	ds_read_b128 v[198:201], v163 offset:49152
	ds_read_b128 v[202:205], v163 offset:50176
	ds_read_b128 v[206:209], v163 offset:51200
	ds_read_b128 v[210:213], v163 offset:52224
	ds_read_b128 v[214:217], v163 offset:53248
	ds_read_b128 v[218:221], v163 offset:54272
	ds_read_b128 v[222:225], v163 offset:55296
	ds_read_b128 v[226:229], v163 offset:56320
	global_load_lds_dwordx4 v[246:247], off
	v_lshl_add_u64 v[246:247], v[252:253], 0, s[0:1]
	s_mov_b32 m0, s42
	s_nop 0
	global_load_lds_dwordx4 v[246:247], off
	s_barrier
	s_waitcnt lgkmcnt(0)
	s_setprio 1
	s_waitcnt lgkmcnt(0)
	v_mfma_f32_16x16x32_bf16 v[56:59], v[182:185], v[198:201], v[56:59]
	v_mfma_f32_16x16x32_bf16 v[48:51], v[190:193], v[198:201], v[48:51]
	v_mfma_f32_16x16x32_bf16 v[40:43], v[182:185], v[206:209], v[40:43]
	v_mfma_f32_16x16x32_bf16 v[32:35], v[190:193], v[206:209], v[32:35]
	v_mfma_f32_16x16x32_bf16 v[24:27], v[182:185], v[214:217], v[24:27]
	v_mfma_f32_16x16x32_bf16 v[16:19], v[190:193], v[214:217], v[16:19]
	v_mfma_f32_16x16x32_bf16 v[8:11], v[182:185], v[222:225], v[8:11]
	v_mfma_f32_16x16x32_bf16 v[4:7], v[190:193], v[222:225], v[4:7]
	v_mfma_f32_16x16x32_bf16 v[56:59], v[186:189], v[202:205], v[56:59]
	v_mfma_f32_16x16x32_bf16 v[48:51], v[194:197], v[202:205], v[48:51]
	v_mfma_f32_16x16x32_bf16 v[40:43], v[186:189], v[210:213], v[40:43]
	v_mfma_f32_16x16x32_bf16 v[32:35], v[194:197], v[210:213], v[32:35]
	v_mfma_f32_16x16x32_bf16 v[24:27], v[186:189], v[218:221], v[24:27]
	v_mfma_f32_16x16x32_bf16 v[16:19], v[194:197], v[218:221], v[16:19]
	v_mfma_f32_16x16x32_bf16 v[8:11], v[186:189], v[226:229], v[8:11]
	v_mfma_f32_16x16x32_bf16 v[4:7], v[194:197], v[226:229], v[4:7]
	s_setprio 0
	s_barrier
	s_add_u32 s28, s28, 0x80080
	s_addc_u32 s29, s29, 0
	s_add_i32 s30, s30, s34
	v_lshl_add_u64 v[182:183], s[28:29], 0, v[130:131]
	s_mov_b32 m0, s30
	s_nop 0
	global_load_lds_dwordx4 v[182:183], off
	v_lshl_add_u64 v[182:183], s[28:29], 0, v[134:135]
	s_add_i32 m0, s30, 0x2000
	s_nop 0
	global_load_lds_dwordx4 v[182:183], off
	s_waitcnt vmcnt(6)
	s_barrier
	s_setprio 1
	v_mfma_f32_16x16x32_bf16 v[60:63], v[230:233], v[198:201], v[60:63]
	v_mfma_f32_16x16x32_bf16 v[52:55], v[238:241], v[198:201], v[52:55]
	v_mfma_f32_16x16x32_bf16 v[44:47], v[230:233], v[206:209], v[44:47]
	v_mfma_f32_16x16x32_bf16 v[36:39], v[238:241], v[206:209], v[36:39]
	v_mfma_f32_16x16x32_bf16 v[28:31], v[230:233], v[214:217], v[28:31]
	v_mfma_f32_16x16x32_bf16 v[20:23], v[238:241], v[214:217], v[20:23]
	v_mfma_f32_16x16x32_bf16 v[12:15], v[230:233], v[222:225], v[12:15]
	v_mfma_f32_16x16x32_bf16 v[0:3], v[238:241], v[222:225], v[0:3]
	v_mfma_f32_16x16x32_bf16 v[60:63], v[234:237], v[202:205], v[60:63]
	v_mfma_f32_16x16x32_bf16 v[52:55], v[242:245], v[202:205], v[52:55]
	v_mfma_f32_16x16x32_bf16 v[44:47], v[234:237], v[210:213], v[44:47]
	v_mfma_f32_16x16x32_bf16 v[36:39], v[242:245], v[210:213], v[36:39]
	v_mfma_f32_16x16x32_bf16 v[28:31], v[234:237], v[218:221], v[28:31]
	v_mfma_f32_16x16x32_bf16 v[20:23], v[242:245], v[218:221], v[20:23]
	v_mfma_f32_16x16x32_bf16 v[12:15], v[234:237], v[226:229], v[12:15]
	v_mfma_f32_16x16x32_bf16 v[0:3], v[242:245], v[226:229], v[0:3]
	s_setprio 0
	s_barrier
	s_add_u32 s26, s26, 0x100
	s_addc_u32 s27, s27, 0
	s_add_u32 s60, s60, 0x100
	s_addc_u32 s61, s61, 0
	s_cmp_ge_i32 s62, s11
	s_mov_b32 s28, s62
	s_cbranch_scc0 .LBB0_625
	s_branch .LBB0_616

; #define PG8_STAGE(bufoff, gbase, voff) do { _Pragma("unroll") for (int _i = 0; _i < 2; ++_i) \
;         __builtin_amdgcn_global_load_lds((const unsigned*)((const char*)(gbase) + (voff)[_i]), (LAS unsigned*)(lds + (bufoff) + ldsw + _i * 8192), 16, 0, 0); } while (0)
; #define PG8_LDA(dst, b, h) do { _Pragma("unroll") for (int m = 0; m < 4; ++m) _Pragma("unroll") for (int k = 0; k < 2; ++k) dst[m][k] = *(const LAS bf16x8*)(lds + PG8_SA(b, h) + aoff + m * 2048 + k * 1024); } while (0)
; #define PG8_LDB(dst, b, h) do { _Pragma("unroll") for (int n = 0; n < 2; ++n) _Pragma("unroll") for (int k = 0; k < 2; ++k) dst[n][k] = *(const LAS bf16x8*)(lds + PG8_SB(b, h) + boff + n * 2048 + k * 1024); } while (0)
; #define PG8_MMA(ai, bj, At, Bt) do { __builtin_amdgcn_s_setprio(1); _Pragma("unroll") for (int m = 0; m < 4; ++m) _Pragma("unroll") for (int n = 0; n < 2; ++n) _Pragma("unroll") for (int k = 0; k < 2; ++k) \
;         acc[ai][bj][m][n] = __builtin_amdgcn_mfma_f32_16x16x32_bf16(Bt[n][k], At[m][k], acc[ai][bj][m][n], 0, 0, 0); __builtin_amdgcn_s_setprio(0); } while (0)
; #define PG8_WAIT_L(n) asm volatile("s_waitcnt lgkmcnt(" #n ")" ::: "memory")
; #define PG8_BAR __builtin_amdgcn_s_barrier()
; #define PG8_SCHED __builtin_amdgcn_sched_barrier(0)
; template <class Epi, class Sched, bool ATILE = false>
; __device__ __forceinline__ void gemm_phase(LAS unsigned char* lds, const Gemm g, const Sched& S, const Epi& E) {
;     ...
;             const bool last = (t == nt - 2);
;             const char* a1 = cA + (size_t)(t + 1) * kstepA;
;             const char* a2 = last ? nA : cA + (size_t)(t + 2) * kstepA; const char* b2 = last ? nB : cB + (size_t)(t + 2) * kstep;
;             const char* a3 = a2 + kstepA; const char* b3 = b2 + kstep;
;             PG8_LDB(B0, 0, 0); PG8_SCHED; PG8_LDA(At, 0, 0); PG8_STAGE(PG8_SA(1, 1), a1 + hstepA, voffA);
;             PG8_WAIT_L(8); PG8_BAR; PG8_WAIT_L(0); PG8_MMA(0, 0, At, B0); PG8_BAR; PG8_SCHED;
;             PG8_LDB(B1, 0, 1); PG8_STAGE(PG8_SB(0, 0), b2, voffB);
;             PG8_BAR; PG8_WAIT_L(0); PG8_MMA(0, 1, At, B1); PG8_BAR;
;             PG8_LDA(At, 0, 1); PG8_STAGE(PG8_SA(0, 0), a2, voffA);
;             PG8_BAR; PG8_WAIT_L(0); PG8_MMA(1, 0, At, B0); PG8_BAR; PG8_SCHED;
.LBB0_739:
	ds_read_b128 v[20:23], v165
	ds_read_b128 v[28:31], v165 offset:1024
	ds_read_b128 v[136:139], v165 offset:2048
	ds_read_b128 v[140:143], v165 offset:3072
	s_add_i32 s62, s26, 2
	s_add_u32 s27, s24, 0x4000
	s_addc_u32 s28, s25, 0
	s_cmp_eq_u32 s11, s26
	s_cselect_b32 s30, s20, s27
	s_cselect_b32 s31, s21, s28
	s_cselect_b32 s26, s22, s60
	s_cselect_b32 s27, s23, s61
	s_add_u32 s28, s30, 0x8000
	s_addc_u32 s29, s31, 0
	v_lshl_add_u64 v[216:217], s[24:25], 0, v[194:195]
	s_add_i32 m0, s34, 0xc000
	ds_read_b128 v[144:147], v167
	ds_read_b128 v[148:151], v167 offset:1024
	ds_read_b128 v[200:203], v167 offset:2048
	ds_read_b128 v[204:207], v167 offset:3072
	ds_read_b128 v[208:211], v167 offset:4096
	ds_read_b128 v[212:215], v167 offset:5120
	ds_read_b128 v[220:223], v167 offset:6144
	ds_read_b128 v[224:227], v167 offset:7168
	global_load_lds_dwordx4 v[216:217], off
	v_lshl_add_u64 v[216:217], s[24:25], 0, v[196:197]
	s_add_i32 m0, s34, 0xe000
	s_nop 0
	global_load_lds_dwordx4 v[216:217], off
	s_waitcnt lgkmcnt(8)
	s_barrier
	s_waitcnt lgkmcnt(0)
	s_setprio 1
	s_waitcnt lgkmcnt(0)
	v_mfma_f32_16x16x32_bf16 v[0:3], v[20:23], v[144:147], v[0:3]
	v_mfma_f32_16x16x32_bf16 v[4:7], v[136:139], v[144:147], v[4:7]
	v_mfma_f32_16x16x32_bf16 v[44:47], v[20:23], v[200:203], v[44:47]
	v_mfma_f32_16x16x32_bf16 v[36:39], v[136:139], v[200:203], v[36:39]
	v_mfma_f32_16x16x32_bf16 v[52:55], v[20:23], v[208:211], v[52:55]
	v_mfma_f32_16x16x32_bf16 v[48:51], v[136:139], v[208:211], v[48:51]
	v_mfma_f32_16x16x32_bf16 v[92:95], v[20:23], v[220:223], v[92:95]
	v_mfma_f32_16x16x32_bf16 v[84:87], v[136:139], v[220:223], v[84:87]
	v_mfma_f32_16x16x32_bf16 v[0:3], v[28:31], v[148:151], v[0:3]
	v_mfma_f32_16x16x32_bf16 v[4:7], v[140:143], v[148:151], v[4:7]
	v_mfma_f32_16x16x32_bf16 v[44:47], v[28:31], v[204:207], v[44:47]
	v_mfma_f32_16x16x32_bf16 v[36:39], v[140:143], v[204:207], v[36:39]
	v_mfma_f32_16x16x32_bf16 v[52:55], v[28:31], v[212:215], v[52:55]
	v_mfma_f32_16x16x32_bf16 v[48:51], v[140:143], v[212:215], v[48:51]
	v_mfma_f32_16x16x32_bf16 v[92:95], v[28:31], v[224:227], v[92:95]
	v_mfma_f32_16x16x32_bf16 v[84:87], v[140:143], v[224:227], v[84:87]
	s_setprio 0
	s_barrier
	s_add_i32 s63, s52, s33
	v_lshl_add_u64 v[216:217], s[26:27], 0, v[170:171]
	s_mov_b32 m0, s63
	ds_read_b128 v[228:231], v177
	ds_read_b128 v[232:235], v177 offset:1024
	ds_read_b128 v[236:239], v177 offset:2048
	ds_read_b128 v[240:243], v177 offset:3072
	global_load_lds_dwordx4 v[216:217], off
	v_lshl_add_u64 v[244:245], s[26:27], 0, v[174:175]
	s_add_i32 m0, s63, 0x2000
	s_nop 0
	global_load_lds_dwordx4 v[244:245], off
	s_barrier
	s_waitcnt lgkmcnt(0)
	s_setprio 1
	s_waitcnt lgkmcnt(0)
	v_mfma_f32_16x16x32_bf16 v[12:15], v[228:231], v[144:147], v[12:15]
	v_mfma_f32_16x16x32_bf16 v[8:11], v[236:239], v[144:147], v[8:11]
	v_mfma_f32_16x16x32_bf16 v[24:27], v[228:231], v[200:203], v[24:27]
	v_mfma_f32_16x16x32_bf16 v[16:19], v[236:239], v[200:203], v[16:19]
	v_mfma_f32_16x16x32_bf16 v[40:43], v[228:231], v[208:211], v[40:43]
	v_mfma_f32_16x16x32_bf16 v[32:35], v[236:239], v[208:211], v[32:35]
	v_mfma_f32_16x16x32_bf16 v[56:59], v[228:231], v[220:223], v[56:59]
	v_mfma_f32_16x16x32_bf16 v[60:63], v[236:239], v[220:223], v[60:63]
	v_mfma_f32_16x16x32_bf16 v[12:15], v[232:235], v[148:151], v[12:15]
	v_mfma_f32_16x16x32_bf16 v[8:11], v[240:243], v[148:151], v[8:11]
	v_mfma_f32_16x16x32_bf16 v[24:27], v[232:235], v[204:207], v[24:27]
	v_mfma_f32_16x16x32_bf16 v[16:19], v[240:243], v[204:207], v[16:19]
	v_mfma_f32_16x16x32_bf16 v[40:43], v[232:235], v[212:215], v[40:43]
	v_mfma_f32_16x16x32_bf16 v[32:35], v[240:243], v[212:215], v[32:35]
	v_mfma_f32_16x16x32_bf16 v[56:59], v[232:235], v[224:227], v[56:59]
	v_mfma_f32_16x16x32_bf16 v[60:63], v[240:243], v[224:227], v[60:63]
	s_setprio 0
	s_barrier
	s_mov_b32 m0, s34
	v_lshl_add_u64 v[246:247], s[30:31], 0, v[168:169]
	ds_read_b128 v[144:147], v167 offset:16384
	ds_read_b128 v[148:151], v167 offset:17408
	ds_read_b128 v[200:203], v167 offset:18432
	ds_read_b128 v[204:207], v167 offset:19456
	ds_read_b128 v[208:211], v167 offset:20480
	ds_read_b128 v[212:215], v167 offset:21504
	ds_read_b128 v[220:223], v167 offset:22528
	ds_read_b128 v[224:227], v167 offset:23552
	global_load_lds_dwordx4 v[246:247], off
	v_lshl_add_u64 v[246:247], s[30:31], 0, v[172:173]
	s_mov_b32 m0, s35
	s_nop 0
	global_load_lds_dwordx4 v[246:247], off
	s_barrier
	s_waitcnt lgkmcnt(0)
	s_setprio 1
	s_waitcnt lgkmcnt(0)
	v_mfma_f32_16x16x32_bf16 v[64:67], v[20:23], v[144:147], v[64:67]
	v_mfma_f32_16x16x32_bf16 v[68:71], v[136:139], v[144:147], v[68:71]
	v_mfma_f32_16x16x32_bf16 v[108:111], v[20:23], v[200:203], v[108:111]
	v_mfma_f32_16x16x32_bf16 v[100:103], v[136:139], v[200:203], v[100:103]
	v_mfma_f32_16x16x32_bf16 v[116:119], v[20:23], v[208:211], v[116:119]
	v_mfma_f32_16x16x32_bf16 v[112:115], v[136:139], v[208:211], v[112:115]
	v_mfma_f32_16x16x32_bf16 v[20:23], v[20:23], v[220:223], v[132:135]
	v_mfma_f32_16x16x32_bf16 v[64:67], v[28:31], v[148:151], v[64:67]
	v_mfma_f32_16x16x32_bf16 v[68:71], v[140:143], v[148:151], v[68:71]
	v_mfma_f32_16x16x32_bf16 v[108:111], v[28:31], v[204:207], v[108:111]
	v_mfma_f32_16x16x32_bf16 v[100:103], v[140:143], v[204:207], v[100:103]
	v_mfma_f32_16x16x32_bf16 v[116:119], v[28:31], v[212:215], v[116:119]
	v_mfma_f32_16x16x32_bf16 v[112:115], v[140:143], v[212:215], v[112:115]
	v_mfma_f32_16x16x32_bf16 v[20:23], v[28:31], v[224:227], v[20:23]
	v_mfma_f32_16x16x32_bf16 v[28:31], v[136:139], v[220:223], v[128:131]
	v_mfma_f32_16x16x32_bf16 v[28:31], v[140:143], v[224:227], v[28:31]
	s_setprio 0
	s_barrier
; #define PG8_STAGE(bufoff, gbase, voff) do { _Pragma("unroll") for (int _i = 0; _i < 2; ++_i) \
;         __builtin_amdgcn_global_load_lds((const unsigned*)((const char*)(gbase) + (voff)[_i]), (LAS unsigned*)(lds + (bufoff) + ldsw + _i * 8192), 16, 0, 0); } while (0)
; #define PG8_LDA(dst, b, h) do { _Pragma("unroll") for (int m = 0; m < 4; ++m) _Pragma("unroll") for (int k = 0; k < 2; ++k) dst[m][k] = *(const LAS bf16x8*)(lds + PG8_SA(b, h) + aoff + m * 2048 + k * 1024); } while (0)
; #define PG8_LDB(dst, b, h) do { _Pragma("unroll") for (int n = 0; n < 2; ++n) _Pragma("unroll") for (int k = 0; k < 2; ++k) dst[n][k] = *(const LAS bf16x8*)(lds + PG8_SB(b, h) + boff + n * 2048 + k * 1024); } while (0)
; #define PG8_MMA(ai, bj, At, Bt) do { __builtin_amdgcn_s_setprio(1); _Pragma("unroll") for (int m = 0; m < 4; ++m) _Pragma("unroll") for (int n = 0; n < 2; ++n) _Pragma("unroll") for (int k = 0; k < 2; ++k) \
;         acc[ai][bj][m][n] = __builtin_amdgcn_mfma_f32_16x16x32_bf16(Bt[n][k], At[m][k], acc[ai][bj][m][n], 0, 0, 0); __builtin_amdgcn_s_setprio(0); } while (0)
; #define PG8_WAIT_V(n) asm volatile("s_waitcnt vmcnt(" #n ")" ::: "memory")
; #define PG8_WAIT_L(n) asm volatile("s_waitcnt lgkmcnt(" #n ")" ::: "memory")
; #define PG8_BAR __builtin_amdgcn_s_barrier()
; #define PG8_SCHED __builtin_amdgcn_sched_barrier(0)
; template <class Epi, class Sched, bool ATILE = false>
; __device__ __forceinline__ void gemm_phase(LAS unsigned char* lds, const Gemm g, const Sched& S, const Epi& E) {
;     ...
;             PG8_STAGE(PG8_SB(0, 1), b2 + hstepB, voffB);
;             PG8_WAIT_V(6); PG8_BAR; PG8_MMA(1, 1, At, B1); PG8_BAR;
;             PG8_LDB(B0, 1, 0); PG8_SCHED; PG8_LDA(At, 1, 0); PG8_STAGE(PG8_SA(0, 1), a2 + hstepA, voffA);
;             PG8_WAIT_L(8); PG8_BAR; PG8_WAIT_L(0); PG8_MMA(0, 0, At, B0); PG8_BAR; PG8_SCHED;
;             PG8_LDB(B1, 1, 1); PG8_STAGE(PG8_SB(1, 0), b3, voffB);
;             PG8_BAR; PG8_WAIT_L(0); PG8_MMA(0, 1, At, B1); PG8_BAR;
;             PG8_LDA(At, 1, 1); PG8_STAGE(PG8_SA(1, 0), a3, voffA);
	s_add_u32 s64, s26, 0x158000
	s_addc_u32 s65, s27, 0
	s_add_i32 s63, s53, s33
	v_lshl_add_u64 v[128:129], s[64:65], 0, v[170:171]
	s_mov_b32 m0, s63
	s_nop 0
	global_load_lds_dwordx4 v[128:129], off
	v_lshl_add_u64 v[128:129], s[64:65], 0, v[174:175]
	s_add_i32 m0, s63, 0x2000
	s_nop 0
	global_load_lds_dwordx4 v[128:129], off
	s_waitcnt vmcnt(6)
	s_barrier
	s_setprio 1
	v_mfma_f32_16x16x32_bf16 v[76:79], v[228:231], v[144:147], v[76:79]
	v_mfma_f32_16x16x32_bf16 v[72:75], v[236:239], v[144:147], v[72:75]
	v_mfma_f32_16x16x32_bf16 v[88:91], v[228:231], v[200:203], v[88:91]
	v_mfma_f32_16x16x32_bf16 v[80:83], v[236:239], v[200:203], v[80:83]
	v_mfma_f32_16x16x32_bf16 v[104:107], v[228:231], v[208:211], v[104:107]
	v_mfma_f32_16x16x32_bf16 v[96:99], v[236:239], v[208:211], v[96:99]
	v_mfma_f32_16x16x32_bf16 v[120:123], v[228:231], v[220:223], v[120:123]
	v_mfma_f32_16x16x32_bf16 v[124:127], v[236:239], v[220:223], v[124:127]
	v_mfma_f32_16x16x32_bf16 v[76:79], v[232:235], v[148:151], v[76:79]
	v_mfma_f32_16x16x32_bf16 v[72:75], v[240:243], v[148:151], v[72:75]
	v_mfma_f32_16x16x32_bf16 v[88:91], v[232:235], v[204:207], v[88:91]
	v_mfma_f32_16x16x32_bf16 v[80:83], v[240:243], v[204:207], v[80:83]
	v_mfma_f32_16x16x32_bf16 v[104:107], v[232:235], v[212:215], v[104:107]
	v_mfma_f32_16x16x32_bf16 v[96:99], v[240:243], v[212:215], v[96:99]
	v_mfma_f32_16x16x32_bf16 v[120:123], v[232:235], v[224:227], v[120:123]
	v_mfma_f32_16x16x32_bf16 v[124:127], v[240:243], v[224:227], v[124:127]
	s_setprio 0
	s_barrier
	s_add_i32 s63, 0, 0x18000
	v_add_u32_e32 v140, s63, v161
	ds_read_b128 v[128:131], v140
	ds_read_b128 v[132:135], v140 offset:1024
	ds_read_b128 v[136:139], v140 offset:2048
	ds_read_b128 v[140:143], v140 offset:3072
	s_add_u32 s30, s30, 0x4000
	s_addc_u32 s31, s31, 0
	s_mov_b32 m0, s36
	v_lshl_add_u64 v[228:229], s[30:31], 0, v[168:169]
	ds_read_b128 v[144:147], v167 offset:32768
	ds_read_b128 v[148:151], v167 offset:33792
	ds_read_b128 v[200:203], v167 offset:34816
	ds_read_b128 v[204:207], v167 offset:35840
	ds_read_b128 v[208:211], v167 offset:36864
	ds_read_b128 v[212:215], v167 offset:37888
	ds_read_b128 v[220:223], v167 offset:38912
	ds_read_b128 v[224:227], v167 offset:39936
	global_load_lds_dwordx4 v[228:229], off
	v_lshl_add_u64 v[228:229], s[30:31], 0, v[172:173]
	s_mov_b32 m0, s37
	s_nop 0
	global_load_lds_dwordx4 v[228:229], off
	s_waitcnt lgkmcnt(8)
	s_barrier
	s_waitcnt lgkmcnt(0)
	s_setprio 1
	s_waitcnt lgkmcnt(0)
	v_mfma_f32_16x16x32_bf16 v[0:3], v[128:131], v[144:147], v[0:3]
	v_mfma_f32_16x16x32_bf16 v[4:7], v[136:139], v[144:147], v[4:7]
	v_mfma_f32_16x16x32_bf16 v[44:47], v[128:131], v[200:203], v[44:47]
	v_mfma_f32_16x16x32_bf16 v[36:39], v[136:139], v[200:203], v[36:39]
	v_mfma_f32_16x16x32_bf16 v[52:55], v[128:131], v[208:211], v[52:55]
	v_mfma_f32_16x16x32_bf16 v[48:51], v[136:139], v[208:211], v[48:51]
	v_mfma_f32_16x16x32_bf16 v[92:95], v[128:131], v[220:223], v[92:95]
	v_mfma_f32_16x16x32_bf16 v[84:87], v[136:139], v[220:223], v[84:87]
	v_mfma_f32_16x16x32_bf16 v[0:3], v[132:135], v[148:151], v[0:3]
	v_mfma_f32_16x16x32_bf16 v[4:7], v[140:143], v[148:151], v[4:7]
	v_mfma_f32_16x16x32_bf16 v[44:47], v[132:135], v[204:207], v[44:47]
	v_mfma_f32_16x16x32_bf16 v[36:39], v[140:143], v[204:207], v[36:39]
	v_mfma_f32_16x16x32_bf16 v[52:55], v[132:135], v[212:215], v[52:55]
	v_mfma_f32_16x16x32_bf16 v[48:51], v[140:143], v[212:215], v[48:51]
	v_mfma_f32_16x16x32_bf16 v[92:95], v[132:135], v[224:227], v[92:95]
	v_mfma_f32_16x16x32_bf16 v[84:87], v[140:143], v[224:227], v[84:87]
	s_setprio 0
	s_barrier
	s_add_i32 s30, 0, 0x1c000
	s_add_i32 s31, s63, s33
	v_add_u32_e32 v219, s30, v161
	v_lshl_add_u64 v[216:217], v[216:217], 0, s[6:7]
	s_mov_b32 m0, s31
	ds_read_b128 v[228:231], v219
	ds_read_b128 v[232:235], v219 offset:1024
	ds_read_b128 v[236:239], v219 offset:2048
	ds_read_b128 v[240:243], v219 offset:3072
	global_load_lds_dwordx4 v[216:217], off
	v_lshl_add_u64 v[216:217], v[244:245], 0, s[6:7]
	s_add_i32 m0, s31, 0x2000
	s_nop 0
	global_load_lds_dwordx4 v[216:217], off
	s_barrier
	s_waitcnt lgkmcnt(0)
	s_setprio 1
	s_waitcnt lgkmcnt(0)
	v_mfma_f32_16x16x32_bf16 v[12:15], v[228:231], v[144:147], v[12:15]
	v_mfma_f32_16x16x32_bf16 v[8:11], v[236:239], v[144:147], v[8:11]
	v_mfma_f32_16x16x32_bf16 v[24:27], v[228:231], v[200:203], v[24:27]
	v_mfma_f32_16x16x32_bf16 v[16:19], v[236:239], v[200:203], v[16:19]
	v_mfma_f32_16x16x32_bf16 v[40:43], v[228:231], v[208:211], v[40:43]
	v_mfma_f32_16x16x32_bf16 v[32:35], v[236:239], v[208:211], v[32:35]
	v_mfma_f32_16x16x32_bf16 v[56:59], v[228:231], v[220:223], v[56:59]
	v_mfma_f32_16x16x32_bf16 v[60:63], v[236:239], v[220:223], v[60:63]
	v_mfma_f32_16x16x32_bf16 v[12:15], v[232:235], v[148:151], v[12:15]
	v_mfma_f32_16x16x32_bf16 v[8:11], v[240:243], v[148:151], v[8:11]
	v_mfma_f32_16x16x32_bf16 v[24:27], v[232:235], v[204:207], v[24:27]
	v_mfma_f32_16x16x32_bf16 v[16:19], v[240:243], v[204:207], v[16:19]
	v_mfma_f32_16x16x32_bf16 v[40:43], v[232:235], v[212:215], v[40:43]
	v_mfma_f32_16x16x32_bf16 v[32:35], v[240:243], v[212:215], v[32:35]
	v_mfma_f32_16x16x32_bf16 v[56:59], v[232:235], v[224:227], v[56:59]
	v_mfma_f32_16x16x32_bf16 v[60:63], v[240:243], v[224:227], v[60:63]
	s_setprio 0
	s_barrier
	s_mov_b32 m0, s39
	v_lshl_add_u64 v[216:217], s[28:29], 0, v[168:169]
	ds_read_b128 v[144:147], v167 offset:49152
	ds_read_b128 v[148:151], v167 offset:50176
	ds_read_b128 v[200:203], v167 offset:51200
	ds_read_b128 v[204:207], v167 offset:52224
	ds_read_b128 v[208:211], v167 offset:53248
	ds_read_b128 v[212:215], v167 offset:54272
	ds_read_b128 v[220:223], v167 offset:55296
	ds_read_b128 v[224:227], v167 offset:56320
	global_load_lds_dwordx4 v[216:217], off
	v_lshl_add_u64 v[216:217], s[28:29], 0, v[172:173]
	s_mov_b32 m0, s40
	s_nop 0
	global_load_lds_dwordx4 v[216:217], off
	s_barrier
; __device__ __forceinline__ float bflo(unsigned w) { return __uint_as_float(w << 16); }
; __device__ __forceinline__ float bfhi(unsigned w) { return __uint_as_float(w & 0xffff0000u); }
; #define PG8_STAGE(bufoff, gbase, voff) do { _Pragma("unroll") for (int _i = 0; _i < 2; ++_i) \
;         __builtin_amdgcn_global_load_lds((const unsigned*)((const char*)(gbase) + (voff)[_i]), (LAS unsigned*)(lds + (bufoff) + ldsw + _i * 8192), 16, 0, 0); } while (0)
; #define PG8_MMA(ai, bj, At, Bt) do { __builtin_amdgcn_s_setprio(1); _Pragma("unroll") for (int m = 0; m < 4; ++m) _Pragma("unroll") for (int n = 0; n < 2; ++n) _Pragma("unroll") for (int k = 0; k < 2; ++k) \
;         acc[ai][bj][m][n] = __builtin_amdgcn_mfma_f32_16x16x32_bf16(Bt[n][k], At[m][k], acc[ai][bj][m][n], 0, 0, 0); __builtin_amdgcn_s_setprio(0); } while (0)
; #define PG8_WAIT_V(n) asm volatile("s_waitcnt vmcnt(" #n ")" ::: "memory")
; #define PG8_WAIT_L(n) asm volatile("s_waitcnt lgkmcnt(" #n ")" ::: "memory")
; #define PG8_BAR __builtin_amdgcn_s_barrier()
; #define PG8_SCHED __builtin_amdgcn_sched_barrier(0)
; template <class Epi, class Sched, bool ATILE = false>
; __device__ __forceinline__ void gemm_phase(LAS unsigned char* lds, const Gemm g, const Sched& S, const Epi& E) {
;     ...
;             PG8_BAR; PG8_WAIT_L(0); PG8_MMA(1, 0, At, B0); PG8_BAR; PG8_SCHED;
;             PG8_STAGE(PG8_SB(1, 1), b3 + hstepB, voffB);
;             PG8_WAIT_V(6); PG8_BAR; PG8_MMA(1, 1, At, B1); PG8_BAR;
;     __device__ __forceinline__ void operator()(const f32x4 (&acc)[2][2][4][2], const Unit& u, int wr, int wc, int fr, int fq) const {
;     ...
;                     const f32x4 v0 = (f32x4){bflo(x.x), bfhi(x.x), bflo(x.y), bfhi(x.y)} + alpha * acc[ai][bj][m][0];
;                     const f32x4 v1 = (f32x4){bflo(x.z), bfhi(x.z), bflo(x.w), bfhi(x.w)} + alpha * acc[ai][bj][m][1];
	s_waitcnt lgkmcnt(0)
	s_setprio 1
	s_waitcnt lgkmcnt(0)
	v_mfma_f32_16x16x32_bf16 v[64:67], v[128:131], v[144:147], v[64:67]
	v_mfma_f32_16x16x32_bf16 v[108:111], v[128:131], v[200:203], v[108:111]
	v_mfma_f32_16x16x32_bf16 v[116:119], v[128:131], v[208:211], v[116:119]
	v_mfma_f32_16x16x32_bf16 v[20:23], v[128:131], v[220:223], v[20:23]
	v_mfma_f32_16x16x32_bf16 v[64:67], v[132:135], v[148:151], v[64:67]
	v_mfma_f32_16x16x32_bf16 v[68:71], v[136:139], v[144:147], v[68:71]
	v_mfma_f32_16x16x32_bf16 v[108:111], v[132:135], v[204:207], v[108:111]
	v_mfma_f32_16x16x32_bf16 v[100:103], v[136:139], v[200:203], v[100:103]
	v_mfma_f32_16x16x32_bf16 v[116:119], v[132:135], v[212:215], v[116:119]
	v_mfma_f32_16x16x32_bf16 v[112:115], v[136:139], v[208:211], v[112:115]
	v_mfma_f32_16x16x32_bf16 v[132:135], v[132:135], v[224:227], v[20:23]
	v_mfma_f32_16x16x32_bf16 v[20:23], v[136:139], v[220:223], v[28:31]
	v_mfma_f32_16x16x32_bf16 v[68:71], v[140:143], v[148:151], v[68:71]
	v_mfma_f32_16x16x32_bf16 v[100:103], v[140:143], v[204:207], v[100:103]
	v_mfma_f32_16x16x32_bf16 v[112:115], v[140:143], v[212:215], v[112:115]
	v_mfma_f32_16x16x32_bf16 v[128:131], v[140:143], v[224:227], v[20:23]
	s_setprio 0
	s_barrier
	s_add_u32 s26, s26, 0x158080
	s_addc_u32 s27, s27, 0
	s_add_i32 s28, s30, s33
	v_lshl_add_u64 v[20:21], s[26:27], 0, v[170:171]
	s_mov_b32 m0, s28
	s_nop 0
	global_load_lds_dwordx4 v[20:21], off
	v_lshl_add_u64 v[20:21], s[26:27], 0, v[174:175]
	s_add_i32 m0, s28, 0x2000
	s_nop 0
	global_load_lds_dwordx4 v[20:21], off
	s_waitcnt vmcnt(6)
	s_barrier
	s_setprio 1
	v_mfma_f32_16x16x32_bf16 v[20:23], v[228:231], v[144:147], v[76:79]
	v_mfma_f32_16x16x32_bf16 v[76:79], v[232:235], v[148:151], v[20:23]
	v_mfma_f32_16x16x32_bf16 v[20:23], v[236:239], v[144:147], v[72:75]
	v_mfma_f32_16x16x32_bf16 v[72:75], v[240:243], v[148:151], v[20:23]
	v_mfma_f32_16x16x32_bf16 v[20:23], v[228:231], v[200:203], v[88:91]
	v_mfma_f32_16x16x32_bf16 v[88:91], v[232:235], v[204:207], v[20:23]
	v_mfma_f32_16x16x32_bf16 v[20:23], v[236:239], v[200:203], v[80:83]
	v_mfma_f32_16x16x32_bf16 v[80:83], v[240:243], v[204:207], v[20:23]
	v_mfma_f32_16x16x32_bf16 v[20:23], v[228:231], v[208:211], v[104:107]
	v_mfma_f32_16x16x32_bf16 v[104:107], v[232:235], v[212:215], v[20:23]
	v_mfma_f32_16x16x32_bf16 v[20:23], v[236:239], v[208:211], v[96:99]
	v_mfma_f32_16x16x32_bf16 v[96:99], v[240:243], v[212:215], v[20:23]
	v_mfma_f32_16x16x32_bf16 v[20:23], v[228:231], v[220:223], v[120:123]
	v_mfma_f32_16x16x32_bf16 v[120:123], v[232:235], v[224:227], v[20:23]
	v_mfma_f32_16x16x32_bf16 v[20:23], v[236:239], v[220:223], v[124:127]
	v_mfma_f32_16x16x32_bf16 v[124:127], v[240:243], v[224:227], v[20:23]
	s_setprio 0
	s_barrier
	s_add_u32 s60, s60, 0x100
	s_addc_u32 s61, s61, 0
	s_add_u32 s24, s24, 0x10000
	s_addc_u32 s25, s25, 0
	s_cmp_ge_i32 s62, s59
	s_mov_b32 s26, s62
	s_cbranch_scc0 .LBB0_739
	v_pk_mul_f32 v[2:3], v[2:3], 0.5 op_sel_hi:[1,0]
	v_pk_mul_f32 v[0:1], v[0:1], 0.5 op_sel_hi:[1,0]
	v_pk_mul_f32 v[6:7], v[6:7], 0.5 op_sel_hi:[1,0]
	v_pk_mul_f32 v[4:5], v[4:5], 0.5 op_sel_hi:[1,0]
	v_pk_mul_f32 v[22:23], v[14:15], 0.5 op_sel_hi:[1,0]
	v_pk_mul_f32 v[20:21], v[12:13], 0.5 op_sel_hi:[1,0]
	v_pk_mul_f32 v[30:31], v[10:11], 0.5 op_sel_hi:[1,0]
	v_pk_mul_f32 v[28:29], v[8:9], 0.5 op_sel_hi:[1,0]
	v_pk_mul_f32 v[10:11], v[46:47], 0.5 op_sel_hi:[1,0]
	v_pk_mul_f32 v[8:9], v[44:45], 0.5 op_sel_hi:[1,0]
	v_pk_mul_f32 v[14:15], v[38:39], 0.5 op_sel_hi:[1,0]
	v_pk_mul_f32 v[12:13], v[36:37], 0.5 op_sel_hi:[1,0]
	v_pk_mul_f32 v[38:39], v[26:27], 0.5 op_sel_hi:[1,0]
	v_pk_mul_f32 v[36:37], v[24:25], 0.5 op_sel_hi:[1,0]
	v_pk_mul_f32 v[46:47], v[18:19], 0.5 op_sel_hi:[1,0]
	v_pk_mul_f32 v[44:45], v[16:17], 0.5 op_sel_hi:[1,0]
	v_pk_mul_f32 v[18:19], v[54:55], 0.5 op_sel_hi:[1,0]
	v_pk_mul_f32 v[16:17], v[52:53], 0.5 op_sel_hi:[1,0]
	v_pk_mul_f32 v[26:27], v[50:51], 0.5 op_sel_hi:[1,0]
	v_pk_mul_f32 v[24:25], v[48:49], 0.5 op_sel_hi:[1,0]
	v_pk_mul_f32 v[50:51], v[42:43], 0.5 op_sel_hi:[1,0]
	v_pk_mul_f32 v[48:49], v[40:41], 0.5 op_sel_hi:[1,0]
	v_pk_mul_f32 v[54:55], v[34:35], 0.5 op_sel_hi:[1,0]
	v_pk_mul_f32 v[52:53], v[32:33], 0.5 op_sel_hi:[1,0]
	v_pk_mul_f32 v[34:35], v[94:95], 0.5 op_sel_hi:[1,0]
	v_pk_mul_f32 v[32:33], v[92:93], 0.5 op_sel_hi:[1,0]
	v_pk_mul_f32 v[42:43], v[86:87], 0.5 op_sel_hi:[1,0]
	v_pk_mul_f32 v[40:41], v[84:85], 0.5 op_sel_hi:[1,0]
	v_pk_mul_f32 v[58:59], v[58:59], 0.5 op_sel_hi:[1,0]
	v_pk_mul_f32 v[56:57], v[56:57], 0.5 op_sel_hi:[1,0]
	v_pk_mul_f32 v[62:63], v[62:63], 0.5 op_sel_hi:[1,0]
	v_pk_mul_f32 v[60:61], v[60:61], 0.5 op_sel_hi:[1,0]
	v_pk_mul_f32 v[66:67], v[66:67], 0.5 op_sel_hi:[1,0]
	v_pk_mul_f32 v[64:65], v[64:65], 0.5 op_sel_hi:[1,0]
	v_pk_mul_f32 v[70:71], v[70:71], 0.5 op_sel_hi:[1,0]
	v_pk_mul_f32 v[68:69], v[68:69], 0.5 op_sel_hi:[1,0]
	v_pk_mul_f32 v[86:87], v[78:79], 0.5 op_sel_hi:[1,0]
	v_pk_mul_f32 v[84:85], v[76:77], 0.5 op_sel_hi:[1,0]
	v_pk_mul_f32 v[94:95], v[74:75], 0.5 op_sel_hi:[1,0]
	v_pk_mul_f32 v[92:93], v[72:73], 0.5 op_sel_hi:[1,0]
	v_pk_mul_f32 v[74:75], v[110:111], 0.5 op_sel_hi:[1,0]
	v_pk_mul_f32 v[72:73], v[108:109], 0.5 op_sel_hi:[1,0]
	v_pk_mul_f32 v[78:79], v[102:103], 0.5 op_sel_hi:[1,0]
	v_pk_mul_f32 v[76:77], v[100:101], 0.5 op_sel_hi:[1,0]
	v_pk_mul_f32 v[102:103], v[90:91], 0.5 op_sel_hi:[1,0]
	v_pk_mul_f32 v[100:101], v[88:89], 0.5 op_sel_hi:[1,0]
	v_pk_mul_f32 v[110:111], v[82:83], 0.5 op_sel_hi:[1,0]
	v_pk_mul_f32 v[108:109], v[80:81], 0.5 op_sel_hi:[1,0]
	v_pk_mul_f32 v[82:83], v[118:119], 0.5 op_sel_hi:[1,0]
	v_pk_mul_f32 v[80:81], v[116:117], 0.5 op_sel_hi:[1,0]
	v_pk_mul_f32 v[90:91], v[114:115], 0.5 op_sel_hi:[1,0]
	v_pk_mul_f32 v[88:89], v[112:113], 0.5 op_sel_hi:[1,0]
	v_pk_mul_f32 v[114:115], v[106:107], 0.5 op_sel_hi:[1,0]
	v_pk_mul_f32 v[112:113], v[104:105], 0.5 op_sel_hi:[1,0]
	v_pk_mul_f32 v[118:119], v[98:99], 0.5 op_sel_hi:[1,0]
	v_pk_mul_f32 v[116:117], v[96:97], 0.5 op_sel_hi:[1,0]
	v_pk_mul_f32 v[98:99], v[134:135], 0.5 op_sel_hi:[1,0]
	v_pk_mul_f32 v[96:97], v[132:133], 0.5 op_sel_hi:[1,0]
	v_pk_mul_f32 v[106:107], v[130:131], 0.5 op_sel_hi:[1,0]
	v_pk_mul_f32 v[104:105], v[128:129], 0.5 op_sel_hi:[1,0]
	v_pk_mul_f32 v[122:123], v[122:123], 0.5 op_sel_hi:[1,0]
	v_pk_mul_f32 v[120:121], v[120:121], 0.5 op_sel_hi:[1,0]
	v_pk_mul_f32 v[126:127], v[126:127], 0.5 op_sel_hi:[1,0]
	v_pk_mul_f32 v[124:125], v[124:125], 0.5 op_sel_hi:[1,0]
	s_branch .LBB0_744

; #define PG8_STAGE(bufoff, gbase, voff) do { _Pragma("unroll") for (int _i = 0; _i < 2; ++_i) \
;         __builtin_amdgcn_global_load_lds((const unsigned*)((const char*)(gbase) + (voff)[_i]), (LAS unsigned*)(lds + (bufoff) + ldsw + _i * 8192), 16, 0, 0); } while (0)
; #define PG8_LDA(dst, b, h) do { _Pragma("unroll") for (int m = 0; m < 4; ++m) _Pragma("unroll") for (int k = 0; k < 2; ++k) dst[m][k] = *(const LAS bf16x8*)(lds + PG8_SA(b, h) + aoff + m * 2048 + k * 1024); } while (0)
; #define PG8_LDB(dst, b, h) do { _Pragma("unroll") for (int n = 0; n < 2; ++n) _Pragma("unroll") for (int k = 0; k < 2; ++k) dst[n][k] = *(const LAS bf16x8*)(lds + PG8_SB(b, h) + boff + n * 2048 + k * 1024); } while (0)
; #define PG8_MMA(ai, bj, At, Bt) do { __builtin_amdgcn_s_setprio(1); _Pragma("unroll") for (int m = 0; m < 4; ++m) _Pragma("unroll") for (int n = 0; n < 2; ++n) _Pragma("unroll") for (int k = 0; k < 2; ++k) \
;         acc[ai][bj][m][n] = __builtin_amdgcn_mfma_f32_16x16x32_bf16(Bt[n][k], At[m][k], acc[ai][bj][m][n], 0, 0, 0); __builtin_amdgcn_s_setprio(0); } while (0)
; #define PG8_WAIT_L(n) asm volatile("s_waitcnt lgkmcnt(" #n ")" ::: "memory")
; #define PG8_BAR __builtin_amdgcn_s_barrier()
; #define PG8_SCHED __builtin_amdgcn_sched_barrier(0)
; template <class Epi, class Sched, bool ATILE = false>
; __device__ __forceinline__ void gemm_phase(LAS unsigned char* lds, const Gemm g, const Sched& S, const Epi& E) {
;     ...
;             const bool last = (t == nt - 2);
;             const char* a1 = cA + (size_t)(t + 1) * kstepA;
;             const char* a2 = last ? nA : cA + (size_t)(t + 2) * kstepA; const char* b2 = last ? nB : cB + (size_t)(t + 2) * kstep;
;             const char* a3 = a2 + kstepA; const char* b3 = b2 + kstep;
;             PG8_LDB(B0, 0, 0); PG8_SCHED; PG8_LDA(At, 0, 0); PG8_STAGE(PG8_SA(1, 1), a1 + hstepA, voffA);
;             PG8_WAIT_L(8); PG8_BAR; PG8_WAIT_L(0); PG8_MMA(0, 0, At, B0); PG8_BAR; PG8_SCHED;
;             PG8_LDB(B1, 0, 1); PG8_STAGE(PG8_SB(0, 0), b2, voffB);
;             PG8_BAR; PG8_WAIT_L(0); PG8_MMA(0, 1, At, B1); PG8_BAR;
;             PG8_LDA(At, 0, 1); PG8_STAGE(PG8_SA(0, 0), a2, voffA);
;             PG8_BAR; PG8_WAIT_L(0); PG8_MMA(1, 0, At, B0); PG8_BAR; PG8_SCHED;
.LBB0_895:
	ds_read_b128 v[32:35], v165
	ds_read_b128 v[36:39], v165 offset:1024
	ds_read_b128 v[178:181], v165 offset:2048
	ds_read_b128 v[182:185], v165 offset:3072
	s_add_i32 s88, s73, 2
	s_add_u32 s84, s12, 0xfff80080
	s_addc_u32 s85, s13, -1
	s_cmp_eq_u32 s53, s73
	s_cselect_b32 s87, s11, s85
	s_cselect_b32 s86, s20, s84
	s_cselect_b32 s85, s41, s63
	s_cselect_b32 s84, s52, s62
	v_lshl_add_u64 v[224:225], s[12:13], 0, v[170:171]
	s_add_i32 m0, s35, 0xc000
	ds_read_b128 v[192:195], v167
	ds_read_b128 v[196:199], v167 offset:1024
	ds_read_b128 v[200:203], v167 offset:2048
	ds_read_b128 v[204:207], v167 offset:3072
	ds_read_b128 v[208:211], v167 offset:4096
	ds_read_b128 v[212:215], v167 offset:5120
	ds_read_b128 v[216:219], v167 offset:6144
	ds_read_b128 v[220:223], v167 offset:7168
	global_load_lds_dwordx4 v[224:225], off
	v_lshl_add_u64 v[224:225], s[12:13], 0, v[172:173]
	s_add_i32 m0, s35, 0xe000
	s_nop 0
	global_load_lds_dwordx4 v[224:225], off
	s_waitcnt lgkmcnt(8)
	s_barrier
	s_waitcnt lgkmcnt(0)
	s_setprio 1
	s_waitcnt lgkmcnt(0)
	v_mfma_f32_16x16x32_bf16 v[132:135], v[32:35], v[192:195], v[132:135]
	v_mfma_f32_16x16x32_bf16 v[128:131], v[178:181], v[192:195], v[128:131]
	v_mfma_f32_16x16x32_bf16 v[116:119], v[32:35], v[200:203], v[116:119]
	v_mfma_f32_16x16x32_bf16 v[112:115], v[178:181], v[200:203], v[112:115]
	v_mfma_f32_16x16x32_bf16 v[100:103], v[32:35], v[208:211], v[100:103]
	v_mfma_f32_16x16x32_bf16 v[96:99], v[178:181], v[208:211], v[96:99]
	v_mfma_f32_16x16x32_bf16 v[84:87], v[32:35], v[216:219], v[84:87]
	v_mfma_f32_16x16x32_bf16 v[80:83], v[178:181], v[216:219], v[80:83]
	v_mfma_f32_16x16x32_bf16 v[132:135], v[36:39], v[196:199], v[132:135]
	v_mfma_f32_16x16x32_bf16 v[128:131], v[182:185], v[196:199], v[128:131]
	v_mfma_f32_16x16x32_bf16 v[116:119], v[36:39], v[204:207], v[116:119]
	v_mfma_f32_16x16x32_bf16 v[112:115], v[182:185], v[204:207], v[112:115]
	v_mfma_f32_16x16x32_bf16 v[100:103], v[36:39], v[212:215], v[100:103]
	v_mfma_f32_16x16x32_bf16 v[96:99], v[182:185], v[212:215], v[96:99]
	v_mfma_f32_16x16x32_bf16 v[84:87], v[36:39], v[220:223], v[84:87]
	v_mfma_f32_16x16x32_bf16 v[80:83], v[182:185], v[220:223], v[80:83]
	s_setprio 0
	s_barrier
	s_add_i32 s73, s43, s31
	v_lshl_add_u64 v[240:241], s[84:85], 0, v[138:139]
	s_mov_b32 m0, s73
	ds_read_b128 v[224:227], v186
	ds_read_b128 v[228:231], v186 offset:1024
	ds_read_b128 v[232:235], v186 offset:2048
	ds_read_b128 v[236:239], v186 offset:3072
	global_load_lds_dwordx4 v[240:241], off
	v_lshl_add_u64 v[242:243], s[84:85], 0, v[142:143]
	s_add_i32 m0, s73, 0x2000
	s_nop 0
	global_load_lds_dwordx4 v[242:243], off
	s_barrier
	s_waitcnt lgkmcnt(0)
	s_setprio 1
	s_waitcnt lgkmcnt(0)
	v_mfma_f32_16x16x32_bf16 v[124:127], v[224:227], v[192:195], v[124:127]
	v_mfma_f32_16x16x32_bf16 v[120:123], v[232:235], v[192:195], v[120:123]
	v_mfma_f32_16x16x32_bf16 v[108:111], v[224:227], v[200:203], v[108:111]
	v_mfma_f32_16x16x32_bf16 v[104:107], v[232:235], v[200:203], v[104:107]
	v_mfma_f32_16x16x32_bf16 v[92:95], v[224:227], v[208:211], v[92:95]
	v_mfma_f32_16x16x32_bf16 v[88:91], v[232:235], v[208:211], v[88:91]
	v_mfma_f32_16x16x32_bf16 v[76:79], v[224:227], v[216:219], v[76:79]
	v_mfma_f32_16x16x32_bf16 v[72:75], v[232:235], v[216:219], v[72:75]
	v_mfma_f32_16x16x32_bf16 v[124:127], v[228:231], v[196:199], v[124:127]
	v_mfma_f32_16x16x32_bf16 v[120:123], v[236:239], v[196:199], v[120:123]
	v_mfma_f32_16x16x32_bf16 v[108:111], v[228:231], v[204:207], v[108:111]
	v_mfma_f32_16x16x32_bf16 v[104:107], v[236:239], v[204:207], v[104:107]
	v_mfma_f32_16x16x32_bf16 v[92:95], v[228:231], v[212:215], v[92:95]
	v_mfma_f32_16x16x32_bf16 v[88:91], v[236:239], v[212:215], v[88:91]
	v_mfma_f32_16x16x32_bf16 v[76:79], v[228:231], v[220:223], v[76:79]
	v_mfma_f32_16x16x32_bf16 v[72:75], v[236:239], v[220:223], v[72:75]
	s_setprio 0
	s_barrier
	s_mov_b32 m0, s35
	v_lshl_add_u64 v[244:245], s[86:87], 0, v[136:137]
	ds_read_b128 v[192:195], v167 offset:16384
	ds_read_b128 v[196:199], v167 offset:17408
	ds_read_b128 v[200:203], v167 offset:18432
	ds_read_b128 v[204:207], v167 offset:19456
	ds_read_b128 v[208:211], v167 offset:20480
	ds_read_b128 v[212:215], v167 offset:21504
	ds_read_b128 v[216:219], v167 offset:22528
	ds_read_b128 v[220:223], v167 offset:23552
	global_load_lds_dwordx4 v[244:245], off
	v_lshl_add_u64 v[246:247], s[86:87], 0, v[140:141]
	s_mov_b32 m0, s37
	s_nop 0
	global_load_lds_dwordx4 v[246:247], off
	s_barrier
	s_waitcnt lgkmcnt(0)
	s_setprio 1
	s_waitcnt lgkmcnt(0)
	v_mfma_f32_16x16x32_bf16 v[68:71], v[32:35], v[192:195], v[68:71]
	v_mfma_f32_16x16x32_bf16 v[64:67], v[178:181], v[192:195], v[64:67]
	v_mfma_f32_16x16x32_bf16 v[52:55], v[32:35], v[200:203], v[52:55]
	v_mfma_f32_16x16x32_bf16 v[48:51], v[178:181], v[200:203], v[48:51]
	v_mfma_f32_16x16x32_bf16 v[28:31], v[32:35], v[208:211], v[28:31]
	v_mfma_f32_16x16x32_bf16 v[24:27], v[178:181], v[208:211], v[24:27]
	v_mfma_f32_16x16x32_bf16 v[12:15], v[32:35], v[216:219], v[12:15]
	v_mfma_f32_16x16x32_bf16 v[8:11], v[178:181], v[216:219], v[8:11]
	v_mfma_f32_16x16x32_bf16 v[68:71], v[36:39], v[196:199], v[68:71]
	v_mfma_f32_16x16x32_bf16 v[64:67], v[182:185], v[196:199], v[64:67]
	v_mfma_f32_16x16x32_bf16 v[52:55], v[36:39], v[204:207], v[52:55]
	v_mfma_f32_16x16x32_bf16 v[48:51], v[182:185], v[204:207], v[48:51]
	v_mfma_f32_16x16x32_bf16 v[28:31], v[36:39], v[212:215], v[28:31]
	v_mfma_f32_16x16x32_bf16 v[24:27], v[182:185], v[212:215], v[24:27]
	v_mfma_f32_16x16x32_bf16 v[12:15], v[36:39], v[220:223], v[12:15]
	v_mfma_f32_16x16x32_bf16 v[8:11], v[182:185], v[220:223], v[8:11]
	s_setprio 0
	s_barrier
; #define PG8_STAGE(bufoff, gbase, voff) do { _Pragma("unroll") for (int _i = 0; _i < 2; ++_i) \
;         __builtin_amdgcn_global_load_lds((const unsigned*)((const char*)(gbase) + (voff)[_i]), (LAS unsigned*)(lds + (bufoff) + ldsw + _i * 8192), 16, 0, 0); } while (0)
; #define PG8_LDA(dst, b, h) do { _Pragma("unroll") for (int m = 0; m < 4; ++m) _Pragma("unroll") for (int k = 0; k < 2; ++k) dst[m][k] = *(const LAS bf16x8*)(lds + PG8_SA(b, h) + aoff + m * 2048 + k * 1024); } while (0)
; #define PG8_LDB(dst, b, h) do { _Pragma("unroll") for (int n = 0; n < 2; ++n) _Pragma("unroll") for (int k = 0; k < 2; ++k) dst[n][k] = *(const LAS bf16x8*)(lds + PG8_SB(b, h) + boff + n * 2048 + k * 1024); } while (0)
; #define PG8_MMA(ai, bj, At, Bt) do { __builtin_amdgcn_s_setprio(1); _Pragma("unroll") for (int m = 0; m < 4; ++m) _Pragma("unroll") for (int n = 0; n < 2; ++n) _Pragma("unroll") for (int k = 0; k < 2; ++k) \
;         acc[ai][bj][m][n] = __builtin_amdgcn_mfma_f32_16x16x32_bf16(Bt[n][k], At[m][k], acc[ai][bj][m][n], 0, 0, 0); __builtin_amdgcn_s_setprio(0); } while (0)
; #define PG8_WAIT_V(n) asm volatile("s_waitcnt vmcnt(" #n ")" ::: "memory")
; #define PG8_WAIT_L(n) asm volatile("s_waitcnt lgkmcnt(" #n ")" ::: "memory")
; #define PG8_BAR __builtin_amdgcn_s_barrier()
; #define PG8_SCHED __builtin_amdgcn_sched_barrier(0)
; template <class Epi, class Sched, bool ATILE = false>
; __device__ __forceinline__ void gemm_phase(LAS unsigned char* lds, const Gemm g, const Sched& S, const Epi& E) {
;     ...
;             PG8_STAGE(PG8_SB(0, 1), b2 + hstepB, voffB);
;             PG8_WAIT_V(6); PG8_BAR; PG8_MMA(1, 1, At, B1); PG8_BAR;
;             PG8_LDB(B0, 1, 0); PG8_SCHED; PG8_LDA(At, 1, 0); PG8_STAGE(PG8_SA(0, 1), a2 + hstepA, voffA);
;             PG8_WAIT_L(8); PG8_BAR; PG8_WAIT_L(0); PG8_MMA(0, 0, At, B0); PG8_BAR; PG8_SCHED;
;             PG8_LDB(B1, 1, 1); PG8_STAGE(PG8_SB(1, 0), b3, voffB);
;             PG8_BAR; PG8_WAIT_L(0); PG8_MMA(0, 1, At, B1); PG8_BAR;
	s_add_u32 vcc_lo, s84, 0x80000
	s_addc_u32 vcc_hi, s85, 0
	s_add_i32 s73, s56, s31
	v_lshl_add_u64 v[32:33], vcc, 0, v[138:139]
	s_mov_b32 m0, s73
	s_nop 0
	global_load_lds_dwordx4 v[32:33], off
	v_lshl_add_u64 v[32:33], vcc, 0, v[142:143]
	s_add_i32 m0, s73, 0x2000
	s_nop 0
	global_load_lds_dwordx4 v[32:33], off
	s_waitcnt vmcnt(6)
	s_barrier
	s_setprio 1
	v_mfma_f32_16x16x32_bf16 v[44:47], v[224:227], v[200:203], v[44:47]
	v_mfma_f32_16x16x32_bf16 v[40:43], v[232:235], v[200:203], v[40:43]
	v_mfma_f32_16x16x32_bf16 v[20:23], v[224:227], v[208:211], v[20:23]
	v_mfma_f32_16x16x32_bf16 v[16:19], v[232:235], v[208:211], v[16:19]
	v_mfma_f32_16x16x32_bf16 v[4:7], v[224:227], v[216:219], v[4:7]
	v_mfma_f32_16x16x32_bf16 v[0:3], v[232:235], v[216:219], v[0:3]
	v_mfma_f32_16x16x32_bf16 v[32:35], v[224:227], v[192:195], v[60:63]
	v_mfma_f32_16x16x32_bf16 v[36:39], v[232:235], v[192:195], v[56:59]
	v_mfma_f32_16x16x32_bf16 v[44:47], v[228:231], v[204:207], v[44:47]
	v_mfma_f32_16x16x32_bf16 v[40:43], v[236:239], v[204:207], v[40:43]
	v_mfma_f32_16x16x32_bf16 v[20:23], v[228:231], v[212:215], v[20:23]
	v_mfma_f32_16x16x32_bf16 v[16:19], v[236:239], v[212:215], v[16:19]
	v_mfma_f32_16x16x32_bf16 v[4:7], v[228:231], v[220:223], v[4:7]
	v_mfma_f32_16x16x32_bf16 v[0:3], v[236:239], v[220:223], v[0:3]
	v_mfma_f32_16x16x32_bf16 v[32:35], v[228:231], v[196:199], v[32:35]
	v_mfma_f32_16x16x32_bf16 v[36:39], v[236:239], v[196:199], v[36:39]
	s_setprio 0
	s_barrier
	s_add_i32 s73, 0, 0x18000
	v_add_u32_e32 v144, s73, v161
	ds_read_b128 v[56:59], v144
	ds_read_b128 v[60:63], v144 offset:1024
	ds_read_b128 v[178:181], v144 offset:2048
	ds_read_b128 v[182:185], v144 offset:3072
	s_add_u32 s86, s86, 0x80000
	s_addc_u32 s87, s87, 0
	s_mov_b32 m0, s39
	v_lshl_add_u64 v[224:225], s[86:87], 0, v[136:137]
	ds_read_b128 v[192:195], v167 offset:32768
	ds_read_b128 v[196:199], v167 offset:33792
	ds_read_b128 v[200:203], v167 offset:34816
	ds_read_b128 v[204:207], v167 offset:35840
	ds_read_b128 v[208:211], v167 offset:36864
	ds_read_b128 v[212:215], v167 offset:37888
	ds_read_b128 v[216:219], v167 offset:38912
	ds_read_b128 v[220:223], v167 offset:39936
	global_load_lds_dwordx4 v[224:225], off
	v_lshl_add_u64 v[224:225], s[86:87], 0, v[140:141]
	s_mov_b32 m0, s97
	s_nop 0
	global_load_lds_dwordx4 v[224:225], off
	s_waitcnt lgkmcnt(8)
	s_barrier
	s_waitcnt lgkmcnt(0)
	s_setprio 1
	s_waitcnt lgkmcnt(0)
	v_mfma_f32_16x16x32_bf16 v[132:135], v[56:59], v[192:195], v[132:135]
	v_mfma_f32_16x16x32_bf16 v[128:131], v[178:181], v[192:195], v[128:131]
	v_mfma_f32_16x16x32_bf16 v[116:119], v[56:59], v[200:203], v[116:119]
	v_mfma_f32_16x16x32_bf16 v[112:115], v[178:181], v[200:203], v[112:115]
	v_mfma_f32_16x16x32_bf16 v[100:103], v[56:59], v[208:211], v[100:103]
	v_mfma_f32_16x16x32_bf16 v[96:99], v[178:181], v[208:211], v[96:99]
	v_mfma_f32_16x16x32_bf16 v[84:87], v[56:59], v[216:219], v[84:87]
	v_mfma_f32_16x16x32_bf16 v[80:83], v[178:181], v[216:219], v[80:83]
	v_mfma_f32_16x16x32_bf16 v[132:135], v[60:63], v[196:199], v[132:135]
	v_mfma_f32_16x16x32_bf16 v[128:131], v[182:185], v[196:199], v[128:131]
	v_mfma_f32_16x16x32_bf16 v[116:119], v[60:63], v[204:207], v[116:119]
	v_mfma_f32_16x16x32_bf16 v[112:115], v[182:185], v[204:207], v[112:115]
	v_mfma_f32_16x16x32_bf16 v[100:103], v[60:63], v[212:215], v[100:103]
	v_mfma_f32_16x16x32_bf16 v[96:99], v[182:185], v[212:215], v[96:99]
	v_mfma_f32_16x16x32_bf16 v[84:87], v[60:63], v[220:223], v[84:87]
	v_mfma_f32_16x16x32_bf16 v[80:83], v[182:185], v[220:223], v[80:83]
	s_setprio 0
	s_barrier
	s_add_i32 s86, 0, 0x1c000
	s_add_i32 s73, s73, s31
	v_add_u32_e32 v144, s86, v161
	v_lshl_add_u64 v[240:241], v[240:241], 0, s[22:23]
	s_mov_b32 m0, s73
	ds_read_b128 v[224:227], v144
	ds_read_b128 v[228:231], v144 offset:1024
	ds_read_b128 v[232:235], v144 offset:2048
	ds_read_b128 v[236:239], v144 offset:3072
	global_load_lds_dwordx4 v[240:241], off
	v_lshl_add_u64 v[240:241], v[242:243], 0, s[22:23]
	s_add_i32 m0, s73, 0x2000
	s_nop 0
	global_load_lds_dwordx4 v[240:241], off
	s_barrier
; #define PG8_STAGE(bufoff, gbase, voff) do { _Pragma("unroll") for (int _i = 0; _i < 2; ++_i) \
;         __builtin_amdgcn_global_load_lds((const unsigned*)((const char*)(gbase) + (voff)[_i]), (LAS unsigned*)(lds + (bufoff) + ldsw + _i * 8192), 16, 0, 0); } while (0)
; #define PG8_LDA(dst, b, h) do { _Pragma("unroll") for (int m = 0; m < 4; ++m) _Pragma("unroll") for (int k = 0; k < 2; ++k) dst[m][k] = *(const LAS bf16x8*)(lds + PG8_SA(b, h) + aoff + m * 2048 + k * 1024); } while (0)
; #define PG8_MMA(ai, bj, At, Bt) do { __builtin_amdgcn_s_setprio(1); _Pragma("unroll") for (int m = 0; m < 4; ++m) _Pragma("unroll") for (int n = 0; n < 2; ++n) _Pragma("unroll") for (int k = 0; k < 2; ++k) \
;         acc[ai][bj][m][n] = __builtin_amdgcn_mfma_f32_16x16x32_bf16(Bt[n][k], At[m][k], acc[ai][bj][m][n], 0, 0, 0); __builtin_amdgcn_s_setprio(0); } while (0)
; #define PG8_WAIT_V(n) asm volatile("s_waitcnt vmcnt(" #n ")" ::: "memory")
; #define PG8_WAIT_L(n) asm volatile("s_waitcnt lgkmcnt(" #n ")" ::: "memory")
; #define PG8_BAR __builtin_amdgcn_s_barrier()
; #define PG8_SCHED __builtin_amdgcn_sched_barrier(0)
; template <class Epi, class Sched, bool ATILE = false>
; __device__ __forceinline__ void gemm_phase(LAS unsigned char* lds, const Gemm g, const Sched& S, const Epi& E) {
;     ...
;             PG8_BAR; PG8_WAIT_L(0); PG8_MMA(0, 1, At, B1); PG8_BAR;
;             PG8_LDA(At, 1, 1); PG8_STAGE(PG8_SA(1, 0), a3, voffA);
;             PG8_BAR; PG8_WAIT_L(0); PG8_MMA(1, 0, At, B0); PG8_BAR; PG8_SCHED;
;             PG8_STAGE(PG8_SB(1, 1), b3 + hstepB, voffB);
;             PG8_WAIT_V(6); PG8_BAR; PG8_MMA(1, 1, At, B1); PG8_BAR;
	s_waitcnt lgkmcnt(0)
	s_setprio 1
	s_waitcnt lgkmcnt(0)
	v_mfma_f32_16x16x32_bf16 v[124:127], v[224:227], v[192:195], v[124:127]
	v_mfma_f32_16x16x32_bf16 v[120:123], v[232:235], v[192:195], v[120:123]
	v_mfma_f32_16x16x32_bf16 v[108:111], v[224:227], v[200:203], v[108:111]
	v_mfma_f32_16x16x32_bf16 v[104:107], v[232:235], v[200:203], v[104:107]
	v_mfma_f32_16x16x32_bf16 v[92:95], v[224:227], v[208:211], v[92:95]
	v_mfma_f32_16x16x32_bf16 v[88:91], v[232:235], v[208:211], v[88:91]
	v_mfma_f32_16x16x32_bf16 v[76:79], v[224:227], v[216:219], v[76:79]
	v_mfma_f32_16x16x32_bf16 v[72:75], v[232:235], v[216:219], v[72:75]
	v_mfma_f32_16x16x32_bf16 v[124:127], v[228:231], v[196:199], v[124:127]
	v_mfma_f32_16x16x32_bf16 v[120:123], v[236:239], v[196:199], v[120:123]
	v_mfma_f32_16x16x32_bf16 v[108:111], v[228:231], v[204:207], v[108:111]
	v_mfma_f32_16x16x32_bf16 v[104:107], v[236:239], v[204:207], v[104:107]
	v_mfma_f32_16x16x32_bf16 v[92:95], v[228:231], v[212:215], v[92:95]
	v_mfma_f32_16x16x32_bf16 v[88:91], v[236:239], v[212:215], v[88:91]
	v_mfma_f32_16x16x32_bf16 v[76:79], v[228:231], v[220:223], v[76:79]
	v_mfma_f32_16x16x32_bf16 v[72:75], v[236:239], v[220:223], v[72:75]
	s_setprio 0
	s_barrier
	s_mov_b32 m0, s4
	v_lshl_add_u64 v[240:241], v[244:245], 0, s[22:23]
	ds_read_b128 v[192:195], v167 offset:49152
	ds_read_b128 v[196:199], v167 offset:50176
	ds_read_b128 v[200:203], v167 offset:51200
	ds_read_b128 v[204:207], v167 offset:52224
	ds_read_b128 v[208:211], v167 offset:53248
	ds_read_b128 v[212:215], v167 offset:54272
	ds_read_b128 v[216:219], v167 offset:55296
	ds_read_b128 v[220:223], v167 offset:56320
	global_load_lds_dwordx4 v[240:241], off
	v_lshl_add_u64 v[240:241], v[246:247], 0, s[22:23]
	s_mov_b32 m0, s5
	s_nop 0
	global_load_lds_dwordx4 v[240:241], off
	s_barrier
	s_waitcnt lgkmcnt(0)
	s_setprio 1
	s_waitcnt lgkmcnt(0)
	v_mfma_f32_16x16x32_bf16 v[68:71], v[56:59], v[192:195], v[68:71]
	v_mfma_f32_16x16x32_bf16 v[64:67], v[178:181], v[192:195], v[64:67]
	v_mfma_f32_16x16x32_bf16 v[52:55], v[56:59], v[200:203], v[52:55]
	v_mfma_f32_16x16x32_bf16 v[48:51], v[178:181], v[200:203], v[48:51]
	v_mfma_f32_16x16x32_bf16 v[28:31], v[56:59], v[208:211], v[28:31]
	v_mfma_f32_16x16x32_bf16 v[24:27], v[178:181], v[208:211], v[24:27]
	v_mfma_f32_16x16x32_bf16 v[12:15], v[56:59], v[216:219], v[12:15]
	v_mfma_f32_16x16x32_bf16 v[8:11], v[178:181], v[216:219], v[8:11]
	v_mfma_f32_16x16x32_bf16 v[68:71], v[60:63], v[196:199], v[68:71]
	v_mfma_f32_16x16x32_bf16 v[64:67], v[182:185], v[196:199], v[64:67]
	v_mfma_f32_16x16x32_bf16 v[52:55], v[60:63], v[204:207], v[52:55]
	v_mfma_f32_16x16x32_bf16 v[48:51], v[182:185], v[204:207], v[48:51]
	v_mfma_f32_16x16x32_bf16 v[28:31], v[60:63], v[212:215], v[28:31]
	v_mfma_f32_16x16x32_bf16 v[24:27], v[182:185], v[212:215], v[24:27]
	v_mfma_f32_16x16x32_bf16 v[12:15], v[60:63], v[220:223], v[12:15]
	v_mfma_f32_16x16x32_bf16 v[8:11], v[182:185], v[220:223], v[8:11]
	s_setprio 0
	s_barrier
	s_add_u32 s84, s84, 0x80080
	s_addc_u32 s85, s85, 0
	s_add_i32 s73, s86, s31
	v_lshl_add_u64 v[56:57], s[84:85], 0, v[138:139]
	s_mov_b32 m0, s73
	s_nop 0
	global_load_lds_dwordx4 v[56:57], off
	v_lshl_add_u64 v[56:57], s[84:85], 0, v[142:143]
	s_add_i32 m0, s73, 0x2000
	s_nop 0
	global_load_lds_dwordx4 v[56:57], off
	s_waitcnt vmcnt(6)
	s_barrier
	s_setprio 1
	v_mfma_f32_16x16x32_bf16 v[32:35], v[224:227], v[192:195], v[32:35]
	v_mfma_f32_16x16x32_bf16 v[60:63], v[228:231], v[196:199], v[32:35]
	v_mfma_f32_16x16x32_bf16 v[32:35], v[232:235], v[192:195], v[36:39]
	v_mfma_f32_16x16x32_bf16 v[56:59], v[236:239], v[196:199], v[32:35]
	v_mfma_f32_16x16x32_bf16 v[32:35], v[224:227], v[200:203], v[44:47]
	v_mfma_f32_16x16x32_bf16 v[44:47], v[228:231], v[204:207], v[32:35]
	v_mfma_f32_16x16x32_bf16 v[32:35], v[232:235], v[200:203], v[40:43]
	v_mfma_f32_16x16x32_bf16 v[20:23], v[224:227], v[208:211], v[20:23]
	v_mfma_f32_16x16x32_bf16 v[16:19], v[232:235], v[208:211], v[16:19]
	v_mfma_f32_16x16x32_bf16 v[4:7], v[224:227], v[216:219], v[4:7]
	v_mfma_f32_16x16x32_bf16 v[0:3], v[232:235], v[216:219], v[0:3]
	v_mfma_f32_16x16x32_bf16 v[40:43], v[236:239], v[204:207], v[32:35]
	v_mfma_f32_16x16x32_bf16 v[20:23], v[228:231], v[212:215], v[20:23]
	v_mfma_f32_16x16x32_bf16 v[16:19], v[236:239], v[212:215], v[16:19]
	v_mfma_f32_16x16x32_bf16 v[4:7], v[228:231], v[220:223], v[4:7]
	v_mfma_f32_16x16x32_bf16 v[0:3], v[236:239], v[220:223], v[0:3]
	s_setprio 0
	s_barrier
	s_add_u32 s12, s12, 0x100
	s_addc_u32 s13, s13, 0
	s_add_u32 s62, s62, 0x100
	s_addc_u32 s63, s63, 0
	s_cmp_ge_i32 s88, s1
	s_mov_b32 s73, s88
	s_cbranch_scc0 .LBB0_895
	s_branch .LBB0_897

; #define PG8_STAGE(bufoff, gbase, voff) do { _Pragma("unroll") for (int _i = 0; _i < 2; ++_i) \
;         __builtin_amdgcn_global_load_lds((const unsigned*)((const char*)(gbase) + (voff)[_i]), (LAS unsigned*)(lds + (bufoff) + ldsw + _i * 8192), 16, 0, 0); } while (0)
; #define PG8_LDA(dst, b, h) do { _Pragma("unroll") for (int m = 0; m < 4; ++m) _Pragma("unroll") for (int k = 0; k < 2; ++k) dst[m][k] = *(const LAS bf16x8*)(lds + PG8_SA(b, h) + aoff + m * 2048 + k * 1024); } while (0)
; #define PG8_LDB(dst, b, h) do { _Pragma("unroll") for (int n = 0; n < 2; ++n) _Pragma("unroll") for (int k = 0; k < 2; ++k) dst[n][k] = *(const LAS bf16x8*)(lds + PG8_SB(b, h) + boff + n * 2048 + k * 1024); } while (0)
; #define PG8_MMA(ai, bj, At, Bt) do { __builtin_amdgcn_s_setprio(1); _Pragma("unroll") for (int m = 0; m < 4; ++m) _Pragma("unroll") for (int n = 0; n < 2; ++n) _Pragma("unroll") for (int k = 0; k < 2; ++k) \
;         acc[ai][bj][m][n] = __builtin_amdgcn_mfma_f32_16x16x32_bf16(Bt[n][k], At[m][k], acc[ai][bj][m][n], 0, 0, 0); __builtin_amdgcn_s_setprio(0); } while (0)
; #define PG8_WAIT_L(n) asm volatile("s_waitcnt lgkmcnt(" #n ")" ::: "memory")
; #define PG8_BAR __builtin_amdgcn_s_barrier()
; #define PG8_SCHED __builtin_amdgcn_sched_barrier(0)
; template <class Epi, class Sched, bool ATILE = false>
; __device__ __forceinline__ void gemm_phase(LAS unsigned char* lds, const Gemm g, const Sched& S, const Epi& E) {
;     ...
;             const bool last = (t == nt - 2);
;             const char* a1 = cA + (size_t)(t + 1) * kstepA;
;             const char* a2 = last ? nA : cA + (size_t)(t + 2) * kstepA; const char* b2 = last ? nB : cB + (size_t)(t + 2) * kstep;
;             const char* a3 = a2 + kstepA; const char* b3 = b2 + kstep;
;             PG8_LDB(B0, 0, 0); PG8_SCHED; PG8_LDA(At, 0, 0); PG8_STAGE(PG8_SA(1, 1), a1 + hstepA, voffA);
;             PG8_WAIT_L(8); PG8_BAR; PG8_WAIT_L(0); PG8_MMA(0, 0, At, B0); PG8_BAR; PG8_SCHED;
;             PG8_LDB(B1, 0, 1); PG8_STAGE(PG8_SB(0, 0), b2, voffB);
;             PG8_BAR; PG8_WAIT_L(0); PG8_MMA(0, 1, At, B1); PG8_BAR;
;             PG8_LDA(At, 0, 1); PG8_STAGE(PG8_SA(0, 0), a2, voffA);
;             PG8_BAR; PG8_WAIT_L(0); PG8_MMA(1, 0, At, B0); PG8_BAR; PG8_SCHED;
.LBB0_1426:
	ds_read_b128 v[162:165], v147
	ds_read_b128 v[166:169], v147 offset:1024
	ds_read_b128 v[170:173], v147 offset:2048
	ds_read_b128 v[174:177], v147 offset:3072
	s_add_i32 s58, s18, 2
	s_add_u32 s16, s12, 0x100
	s_addc_u32 s17, s13, 0
	s_cmp_eq_u32 s55, s18
	s_cselect_b32 s18, s10, s56
	s_cselect_b32 s21, s7, s17
	s_cselect_b32 s20, s6, s16
	s_cselect_b32 s19, s11, s57
	s_mov_b32 m0, s30
	v_lshl_add_u64 v[144:145], s[12:13], 0, v[140:141]
	ds_read_b128 v[178:181], v148
	ds_read_b128 v[182:185], v148 offset:1024
	ds_read_b128 v[186:189], v148 offset:2048
	ds_read_b128 v[190:193], v148 offset:3072
	ds_read_b128 v[194:197], v148 offset:4096
	ds_read_b128 v[198:201], v148 offset:5120
	ds_read_b128 v[202:205], v148 offset:6144
	ds_read_b128 v[206:209], v148 offset:7168
	global_load_lds_dwordx4 v[144:145], off
	v_lshl_add_u64 v[144:145], s[12:13], 0, v[142:143]
	s_mov_b32 m0, s31
	s_nop 0
	global_load_lds_dwordx4 v[144:145], off
	s_waitcnt lgkmcnt(8)
	s_barrier
	s_waitcnt lgkmcnt(0)
	s_setprio 1
	s_waitcnt lgkmcnt(0)
	v_mfma_f32_16x16x32_bf16 v[124:127], v[162:165], v[178:181], v[124:127]
	v_mfma_f32_16x16x32_bf16 v[120:123], v[170:173], v[178:181], v[120:123]
	v_mfma_f32_16x16x32_bf16 v[108:111], v[162:165], v[186:189], v[108:111]
	v_mfma_f32_16x16x32_bf16 v[104:107], v[170:173], v[186:189], v[104:107]
	v_mfma_f32_16x16x32_bf16 v[92:95], v[162:165], v[194:197], v[92:95]
	v_mfma_f32_16x16x32_bf16 v[88:91], v[170:173], v[194:197], v[88:91]
	v_mfma_f32_16x16x32_bf16 v[76:79], v[162:165], v[202:205], v[76:79]
	v_mfma_f32_16x16x32_bf16 v[72:75], v[170:173], v[202:205], v[72:75]
	v_mfma_f32_16x16x32_bf16 v[124:127], v[166:169], v[182:185], v[124:127]
	v_mfma_f32_16x16x32_bf16 v[120:123], v[174:177], v[182:185], v[120:123]
	v_mfma_f32_16x16x32_bf16 v[108:111], v[166:169], v[190:193], v[108:111]
	v_mfma_f32_16x16x32_bf16 v[104:107], v[174:177], v[190:193], v[104:107]
	v_mfma_f32_16x16x32_bf16 v[92:95], v[166:169], v[198:201], v[92:95]
	v_mfma_f32_16x16x32_bf16 v[88:91], v[174:177], v[198:201], v[88:91]
	v_mfma_f32_16x16x32_bf16 v[76:79], v[166:169], v[206:209], v[76:79]
	v_mfma_f32_16x16x32_bf16 v[72:75], v[174:177], v[206:209], v[72:75]
	s_setprio 0
	s_barrier
	s_mov_b32 m0, s33
	v_lshl_add_u64 v[144:145], s[18:19], 0, v[132:133]
	ds_read_b128 v[210:213], v149
	ds_read_b128 v[214:217], v149 offset:1024
	ds_read_b128 v[218:221], v149 offset:2048
	ds_read_b128 v[222:225], v149 offset:3072
	global_load_lds_dwordx4 v[144:145], off
	v_lshl_add_u64 v[226:227], s[18:19], 0, v[128:129]
	s_mov_b32 m0, s34
	s_nop 0
	global_load_lds_dwordx4 v[226:227], off
	s_barrier
	s_waitcnt lgkmcnt(0)
	s_setprio 1
	s_waitcnt lgkmcnt(0)
	v_mfma_f32_16x16x32_bf16 v[116:119], v[210:213], v[178:181], v[116:119]
	v_mfma_f32_16x16x32_bf16 v[112:115], v[218:221], v[178:181], v[112:115]
	v_mfma_f32_16x16x32_bf16 v[100:103], v[210:213], v[186:189], v[100:103]
	v_mfma_f32_16x16x32_bf16 v[96:99], v[218:221], v[186:189], v[96:99]
	v_mfma_f32_16x16x32_bf16 v[84:87], v[210:213], v[194:197], v[84:87]
	v_mfma_f32_16x16x32_bf16 v[80:83], v[218:221], v[194:197], v[80:83]
	v_mfma_f32_16x16x32_bf16 v[68:71], v[210:213], v[202:205], v[68:71]
	v_mfma_f32_16x16x32_bf16 v[64:67], v[218:221], v[202:205], v[64:67]
	v_mfma_f32_16x16x32_bf16 v[116:119], v[214:217], v[182:185], v[116:119]
	v_mfma_f32_16x16x32_bf16 v[112:115], v[222:225], v[182:185], v[112:115]
	v_mfma_f32_16x16x32_bf16 v[100:103], v[214:217], v[190:193], v[100:103]
	v_mfma_f32_16x16x32_bf16 v[96:99], v[222:225], v[190:193], v[96:99]
	v_mfma_f32_16x16x32_bf16 v[84:87], v[214:217], v[198:201], v[84:87]
	v_mfma_f32_16x16x32_bf16 v[80:83], v[222:225], v[198:201], v[80:83]
	v_mfma_f32_16x16x32_bf16 v[68:71], v[214:217], v[206:209], v[68:71]
	v_mfma_f32_16x16x32_bf16 v[64:67], v[222:225], v[206:209], v[64:67]
	s_setprio 0
	s_barrier
	s_mov_b32 m0, s22
	v_lshl_add_u64 v[228:229], s[20:21], 0, v[134:135]
	ds_read_b128 v[178:181], v148 offset:16384
	ds_read_b128 v[182:185], v148 offset:17408
	ds_read_b128 v[186:189], v148 offset:18432
	ds_read_b128 v[190:193], v148 offset:19456
	ds_read_b128 v[194:197], v148 offset:20480
	ds_read_b128 v[198:201], v148 offset:21504
	ds_read_b128 v[202:205], v148 offset:22528
	ds_read_b128 v[206:209], v148 offset:23552
	global_load_lds_dwordx4 v[228:229], off
	v_lshl_add_u64 v[230:231], s[20:21], 0, v[130:131]
	s_mov_b32 m0, s23
	s_nop 0
	global_load_lds_dwordx4 v[230:231], off
	s_barrier
	s_waitcnt lgkmcnt(0)
	s_setprio 1
	s_waitcnt lgkmcnt(0)
	v_mfma_f32_16x16x32_bf16 v[60:63], v[162:165], v[178:181], v[60:63]
	v_mfma_f32_16x16x32_bf16 v[56:59], v[170:173], v[178:181], v[56:59]
	v_mfma_f32_16x16x32_bf16 v[44:47], v[162:165], v[186:189], v[44:47]
	v_mfma_f32_16x16x32_bf16 v[40:43], v[170:173], v[186:189], v[40:43]
	v_mfma_f32_16x16x32_bf16 v[28:31], v[162:165], v[194:197], v[28:31]
	v_mfma_f32_16x16x32_bf16 v[24:27], v[170:173], v[194:197], v[24:27]
	v_mfma_f32_16x16x32_bf16 v[12:15], v[162:165], v[202:205], v[12:15]
	v_mfma_f32_16x16x32_bf16 v[8:11], v[170:173], v[202:205], v[8:11]
	v_mfma_f32_16x16x32_bf16 v[60:63], v[166:169], v[182:185], v[60:63]
	v_mfma_f32_16x16x32_bf16 v[56:59], v[174:177], v[182:185], v[56:59]
	v_mfma_f32_16x16x32_bf16 v[44:47], v[166:169], v[190:193], v[44:47]
	v_mfma_f32_16x16x32_bf16 v[40:43], v[174:177], v[190:193], v[40:43]
	v_mfma_f32_16x16x32_bf16 v[28:31], v[166:169], v[198:201], v[28:31]
	v_mfma_f32_16x16x32_bf16 v[24:27], v[174:177], v[198:201], v[24:27]
	v_mfma_f32_16x16x32_bf16 v[12:15], v[166:169], v[206:209], v[12:15]
	v_mfma_f32_16x16x32_bf16 v[8:11], v[174:177], v[206:209], v[8:11]
	s_setprio 0
	s_barrier
; #define PG8_STAGE(bufoff, gbase, voff) do { _Pragma("unroll") for (int _i = 0; _i < 2; ++_i) \
;         __builtin_amdgcn_global_load_lds((const unsigned*)((const char*)(gbase) + (voff)[_i]), (LAS unsigned*)(lds + (bufoff) + ldsw + _i * 8192), 16, 0, 0); } while (0)
; #define PG8_LDA(dst, b, h) do { _Pragma("unroll") for (int m = 0; m < 4; ++m) _Pragma("unroll") for (int k = 0; k < 2; ++k) dst[m][k] = *(const LAS bf16x8*)(lds + PG8_SA(b, h) + aoff + m * 2048 + k * 1024); } while (0)
; #define PG8_LDB(dst, b, h) do { _Pragma("unroll") for (int n = 0; n < 2; ++n) _Pragma("unroll") for (int k = 0; k < 2; ++k) dst[n][k] = *(const LAS bf16x8*)(lds + PG8_SB(b, h) + boff + n * 2048 + k * 1024); } while (0)
; #define PG8_MMA(ai, bj, At, Bt) do { __builtin_amdgcn_s_setprio(1); _Pragma("unroll") for (int m = 0; m < 4; ++m) _Pragma("unroll") for (int n = 0; n < 2; ++n) _Pragma("unroll") for (int k = 0; k < 2; ++k) \
;         acc[ai][bj][m][n] = __builtin_amdgcn_mfma_f32_16x16x32_bf16(Bt[n][k], At[m][k], acc[ai][bj][m][n], 0, 0, 0); __builtin_amdgcn_s_setprio(0); } while (0)
; #define PG8_WAIT_V(n) asm volatile("s_waitcnt vmcnt(" #n ")" ::: "memory")
; #define PG8_WAIT_L(n) asm volatile("s_waitcnt lgkmcnt(" #n ")" ::: "memory")
; #define PG8_BAR __builtin_amdgcn_s_barrier()
; #define PG8_SCHED __builtin_amdgcn_sched_barrier(0)
; template <class Epi, class Sched, bool ATILE = false>
; __device__ __forceinline__ void gemm_phase(LAS unsigned char* lds, const Gemm g, const Sched& S, const Epi& E) {
;     ...
;             PG8_STAGE(PG8_SB(0, 1), b2 + hstepB, voffB);
;             PG8_WAIT_V(6); PG8_BAR; PG8_MMA(1, 1, At, B1); PG8_BAR;
;             PG8_LDB(B0, 1, 0); PG8_SCHED; PG8_LDA(At, 1, 0); PG8_STAGE(PG8_SA(0, 1), a2 + hstepA, voffA);
;             PG8_WAIT_L(8); PG8_BAR; PG8_WAIT_L(0); PG8_MMA(0, 0, At, B0); PG8_BAR; PG8_SCHED;
;             PG8_LDB(B1, 1, 1); PG8_STAGE(PG8_SB(1, 0), b3, voffB);
;             PG8_BAR; PG8_WAIT_L(0); PG8_MMA(0, 1, At, B1); PG8_BAR;
	s_add_u32 s12, s18, 0x18000
	s_addc_u32 s13, s19, 0
	s_mov_b32 m0, s35
	v_lshl_add_u64 v[162:163], s[12:13], 0, v[132:133]
	global_load_lds_dwordx4 v[162:163], off
	v_lshl_add_u64 v[162:163], s[12:13], 0, v[128:129]
	s_mov_b32 m0, s36
	s_nop 0
	global_load_lds_dwordx4 v[162:163], off
	s_waitcnt vmcnt(6)
	s_barrier
	s_setprio 1
	v_mfma_f32_16x16x32_bf16 v[52:55], v[210:213], v[178:181], v[52:55]
	v_mfma_f32_16x16x32_bf16 v[48:51], v[218:221], v[178:181], v[48:51]
	v_mfma_f32_16x16x32_bf16 v[36:39], v[210:213], v[186:189], v[36:39]
	v_mfma_f32_16x16x32_bf16 v[32:35], v[218:221], v[186:189], v[32:35]
	v_mfma_f32_16x16x32_bf16 v[20:23], v[210:213], v[194:197], v[20:23]
	v_mfma_f32_16x16x32_bf16 v[16:19], v[218:221], v[194:197], v[16:19]
	v_mfma_f32_16x16x32_bf16 v[4:7], v[210:213], v[202:205], v[4:7]
	v_mfma_f32_16x16x32_bf16 v[0:3], v[218:221], v[202:205], v[0:3]
	v_mfma_f32_16x16x32_bf16 v[52:55], v[214:217], v[182:185], v[52:55]
	v_mfma_f32_16x16x32_bf16 v[48:51], v[222:225], v[182:185], v[48:51]
	v_mfma_f32_16x16x32_bf16 v[36:39], v[214:217], v[190:193], v[36:39]
	v_mfma_f32_16x16x32_bf16 v[32:35], v[222:225], v[190:193], v[32:35]
	v_mfma_f32_16x16x32_bf16 v[20:23], v[214:217], v[198:201], v[20:23]
	v_mfma_f32_16x16x32_bf16 v[16:19], v[222:225], v[198:201], v[16:19]
	v_mfma_f32_16x16x32_bf16 v[4:7], v[214:217], v[206:209], v[4:7]
	v_mfma_f32_16x16x32_bf16 v[0:3], v[222:225], v[206:209], v[0:3]
	s_setprio 0
	s_barrier
	ds_read_b128 v[162:165], v150
	ds_read_b128 v[166:169], v150 offset:1024
	ds_read_b128 v[170:173], v150 offset:2048
	ds_read_b128 v[174:177], v150 offset:3072
	s_add_u32 s12, s20, 0x18000
	s_addc_u32 s13, s21, 0
	s_mov_b32 m0, s24
	v_lshl_add_u64 v[210:211], s[12:13], 0, v[134:135]
	ds_read_b128 v[178:181], v148 offset:32768
	ds_read_b128 v[182:185], v148 offset:33792
	ds_read_b128 v[186:189], v148 offset:34816
	ds_read_b128 v[190:193], v148 offset:35840
	ds_read_b128 v[194:197], v148 offset:36864
	ds_read_b128 v[198:201], v148 offset:37888
	ds_read_b128 v[202:205], v148 offset:38912
	ds_read_b128 v[206:209], v148 offset:39936
	global_load_lds_dwordx4 v[210:211], off
	v_lshl_add_u64 v[210:211], s[12:13], 0, v[130:131]
	s_mov_b32 m0, s25
	s_nop 0
	global_load_lds_dwordx4 v[210:211], off
	s_waitcnt lgkmcnt(8)
	s_barrier
	s_waitcnt lgkmcnt(0)
	s_setprio 1
	s_waitcnt lgkmcnt(0)
	v_mfma_f32_16x16x32_bf16 v[124:127], v[162:165], v[178:181], v[124:127]
	v_mfma_f32_16x16x32_bf16 v[120:123], v[170:173], v[178:181], v[120:123]
	v_mfma_f32_16x16x32_bf16 v[108:111], v[162:165], v[186:189], v[108:111]
	v_mfma_f32_16x16x32_bf16 v[104:107], v[170:173], v[186:189], v[104:107]
	v_mfma_f32_16x16x32_bf16 v[92:95], v[162:165], v[194:197], v[92:95]
	v_mfma_f32_16x16x32_bf16 v[88:91], v[170:173], v[194:197], v[88:91]
	v_mfma_f32_16x16x32_bf16 v[76:79], v[162:165], v[202:205], v[76:79]
	v_mfma_f32_16x16x32_bf16 v[72:75], v[170:173], v[202:205], v[72:75]
	v_mfma_f32_16x16x32_bf16 v[124:127], v[166:169], v[182:185], v[124:127]
	v_mfma_f32_16x16x32_bf16 v[120:123], v[174:177], v[182:185], v[120:123]
	v_mfma_f32_16x16x32_bf16 v[108:111], v[166:169], v[190:193], v[108:111]
	v_mfma_f32_16x16x32_bf16 v[104:107], v[174:177], v[190:193], v[104:107]
	v_mfma_f32_16x16x32_bf16 v[92:95], v[166:169], v[198:201], v[92:95]
	v_mfma_f32_16x16x32_bf16 v[88:91], v[174:177], v[198:201], v[88:91]
	v_mfma_f32_16x16x32_bf16 v[76:79], v[166:169], v[206:209], v[76:79]
	v_mfma_f32_16x16x32_bf16 v[72:75], v[174:177], v[206:209], v[72:75]
	s_setprio 0
	s_barrier
	s_mov_b32 m0, s40
	v_lshl_add_u64 v[144:145], v[144:145], 0, s[0:1]
	ds_read_b128 v[210:213], v157
	ds_read_b128 v[214:217], v157 offset:1024
	ds_read_b128 v[218:221], v157 offset:2048
	ds_read_b128 v[222:225], v157 offset:3072
	global_load_lds_dwordx4 v[144:145], off
	v_lshl_add_u64 v[144:145], v[226:227], 0, s[0:1]
	s_mov_b32 m0, s41
	s_nop 0
	global_load_lds_dwordx4 v[144:145], off
	s_barrier
; #define PG8_STAGE(bufoff, gbase, voff) do { _Pragma("unroll") for (int _i = 0; _i < 2; ++_i) \
;         __builtin_amdgcn_global_load_lds((const unsigned*)((const char*)(gbase) + (voff)[_i]), (LAS unsigned*)(lds + (bufoff) + ldsw + _i * 8192), 16, 0, 0); } while (0)
; #define PG8_LDA(dst, b, h) do { _Pragma("unroll") for (int m = 0; m < 4; ++m) _Pragma("unroll") for (int k = 0; k < 2; ++k) dst[m][k] = *(const LAS bf16x8*)(lds + PG8_SA(b, h) + aoff + m * 2048 + k * 1024); } while (0)
; #define PG8_MMA(ai, bj, At, Bt) do { __builtin_amdgcn_s_setprio(1); _Pragma("unroll") for (int m = 0; m < 4; ++m) _Pragma("unroll") for (int n = 0; n < 2; ++n) _Pragma("unroll") for (int k = 0; k < 2; ++k) \
;         acc[ai][bj][m][n] = __builtin_amdgcn_mfma_f32_16x16x32_bf16(Bt[n][k], At[m][k], acc[ai][bj][m][n], 0, 0, 0); __builtin_amdgcn_s_setprio(0); } while (0)
; #define PG8_WAIT_V(n) asm volatile("s_waitcnt vmcnt(" #n ")" ::: "memory")
; #define PG8_WAIT_L(n) asm volatile("s_waitcnt lgkmcnt(" #n ")" ::: "memory")
; #define PG8_BAR __builtin_amdgcn_s_barrier()
; #define PG8_SCHED __builtin_amdgcn_sched_barrier(0)
; template <class Epi, class Sched, bool ATILE = false>
; __device__ __forceinline__ void gemm_phase(LAS unsigned char* lds, const Gemm g, const Sched& S, const Epi& E) {
;     ...
;             PG8_BAR; PG8_WAIT_L(0); PG8_MMA(0, 1, At, B1); PG8_BAR;
;             PG8_LDA(At, 1, 1); PG8_STAGE(PG8_SA(1, 0), a3, voffA);
;             PG8_BAR; PG8_WAIT_L(0); PG8_MMA(1, 0, At, B0); PG8_BAR; PG8_SCHED;
;             PG8_STAGE(PG8_SB(1, 1), b3 + hstepB, voffB);
;             PG8_WAIT_V(6); PG8_BAR; PG8_MMA(1, 1, At, B1); PG8_BAR;
	s_waitcnt lgkmcnt(0)
	s_setprio 1
	s_waitcnt lgkmcnt(0)
	v_mfma_f32_16x16x32_bf16 v[116:119], v[210:213], v[178:181], v[116:119]
	v_mfma_f32_16x16x32_bf16 v[112:115], v[218:221], v[178:181], v[112:115]
	v_mfma_f32_16x16x32_bf16 v[100:103], v[210:213], v[186:189], v[100:103]
	v_mfma_f32_16x16x32_bf16 v[96:99], v[218:221], v[186:189], v[96:99]
	v_mfma_f32_16x16x32_bf16 v[84:87], v[210:213], v[194:197], v[84:87]
	v_mfma_f32_16x16x32_bf16 v[80:83], v[218:221], v[194:197], v[80:83]
	v_mfma_f32_16x16x32_bf16 v[68:71], v[210:213], v[202:205], v[68:71]
	v_mfma_f32_16x16x32_bf16 v[64:67], v[218:221], v[202:205], v[64:67]
	v_mfma_f32_16x16x32_bf16 v[116:119], v[214:217], v[182:185], v[116:119]
	v_mfma_f32_16x16x32_bf16 v[112:115], v[222:225], v[182:185], v[112:115]
	v_mfma_f32_16x16x32_bf16 v[100:103], v[214:217], v[190:193], v[100:103]
	v_mfma_f32_16x16x32_bf16 v[96:99], v[222:225], v[190:193], v[96:99]
	v_mfma_f32_16x16x32_bf16 v[84:87], v[214:217], v[198:201], v[84:87]
	v_mfma_f32_16x16x32_bf16 v[80:83], v[222:225], v[198:201], v[80:83]
	v_mfma_f32_16x16x32_bf16 v[68:71], v[214:217], v[206:209], v[68:71]
	v_mfma_f32_16x16x32_bf16 v[64:67], v[222:225], v[206:209], v[64:67]
	s_setprio 0
	s_barrier
	s_mov_b32 m0, s28
	v_lshl_add_u64 v[144:145], v[228:229], 0, s[0:1]
	ds_read_b128 v[178:181], v148 offset:49152
	ds_read_b128 v[182:185], v148 offset:50176
	ds_read_b128 v[186:189], v148 offset:51200
	ds_read_b128 v[190:193], v148 offset:52224
	ds_read_b128 v[194:197], v148 offset:53248
	ds_read_b128 v[198:201], v148 offset:54272
	ds_read_b128 v[202:205], v148 offset:55296
	ds_read_b128 v[206:209], v148 offset:56320
	global_load_lds_dwordx4 v[144:145], off
	v_lshl_add_u64 v[144:145], v[230:231], 0, s[0:1]
	s_mov_b32 m0, s29
	s_nop 0
	global_load_lds_dwordx4 v[144:145], off
	s_barrier
	s_waitcnt lgkmcnt(0)
	s_setprio 1
	s_waitcnt lgkmcnt(0)
	v_mfma_f32_16x16x32_bf16 v[60:63], v[162:165], v[178:181], v[60:63]
	v_mfma_f32_16x16x32_bf16 v[56:59], v[170:173], v[178:181], v[56:59]
	v_mfma_f32_16x16x32_bf16 v[44:47], v[162:165], v[186:189], v[44:47]
	v_mfma_f32_16x16x32_bf16 v[40:43], v[170:173], v[186:189], v[40:43]
	v_mfma_f32_16x16x32_bf16 v[28:31], v[162:165], v[194:197], v[28:31]
	v_mfma_f32_16x16x32_bf16 v[24:27], v[170:173], v[194:197], v[24:27]
	v_mfma_f32_16x16x32_bf16 v[12:15], v[162:165], v[202:205], v[12:15]
	v_mfma_f32_16x16x32_bf16 v[8:11], v[170:173], v[202:205], v[8:11]
	v_mfma_f32_16x16x32_bf16 v[60:63], v[166:169], v[182:185], v[60:63]
	v_mfma_f32_16x16x32_bf16 v[56:59], v[174:177], v[182:185], v[56:59]
	v_mfma_f32_16x16x32_bf16 v[44:47], v[166:169], v[190:193], v[44:47]
	v_mfma_f32_16x16x32_bf16 v[40:43], v[174:177], v[190:193], v[40:43]
	v_mfma_f32_16x16x32_bf16 v[28:31], v[166:169], v[198:201], v[28:31]
	v_mfma_f32_16x16x32_bf16 v[24:27], v[174:177], v[198:201], v[24:27]
	v_mfma_f32_16x16x32_bf16 v[12:15], v[166:169], v[206:209], v[12:15]
	v_mfma_f32_16x16x32_bf16 v[8:11], v[174:177], v[206:209], v[8:11]
	s_setprio 0
	s_barrier
	s_add_u32 s12, s18, 0x18080
	s_addc_u32 s13, s19, 0
	s_mov_b32 m0, s42
	v_lshl_add_u64 v[144:145], s[12:13], 0, v[132:133]
	global_load_lds_dwordx4 v[144:145], off
	v_lshl_add_u64 v[144:145], s[12:13], 0, v[128:129]
	s_mov_b32 m0, s43
	s_nop 0
	global_load_lds_dwordx4 v[144:145], off
	s_waitcnt vmcnt(6)
	s_barrier
	s_setprio 1
	v_mfma_f32_16x16x32_bf16 v[52:55], v[210:213], v[178:181], v[52:55]
	v_mfma_f32_16x16x32_bf16 v[48:51], v[218:221], v[178:181], v[48:51]
	v_mfma_f32_16x16x32_bf16 v[36:39], v[210:213], v[186:189], v[36:39]
	v_mfma_f32_16x16x32_bf16 v[32:35], v[218:221], v[186:189], v[32:35]
	v_mfma_f32_16x16x32_bf16 v[20:23], v[210:213], v[194:197], v[20:23]
	v_mfma_f32_16x16x32_bf16 v[16:19], v[218:221], v[194:197], v[16:19]
	v_mfma_f32_16x16x32_bf16 v[4:7], v[210:213], v[202:205], v[4:7]
	v_mfma_f32_16x16x32_bf16 v[0:3], v[218:221], v[202:205], v[0:3]
	v_mfma_f32_16x16x32_bf16 v[52:55], v[214:217], v[182:185], v[52:55]
	v_mfma_f32_16x16x32_bf16 v[48:51], v[222:225], v[182:185], v[48:51]
	v_mfma_f32_16x16x32_bf16 v[36:39], v[214:217], v[190:193], v[36:39]
	v_mfma_f32_16x16x32_bf16 v[32:35], v[222:225], v[190:193], v[32:35]
	v_mfma_f32_16x16x32_bf16 v[20:23], v[214:217], v[198:201], v[20:23]
	v_mfma_f32_16x16x32_bf16 v[16:19], v[222:225], v[198:201], v[16:19]
	v_mfma_f32_16x16x32_bf16 v[4:7], v[214:217], v[206:209], v[4:7]
	v_mfma_f32_16x16x32_bf16 v[0:3], v[222:225], v[206:209], v[0:3]
	s_setprio 0
	s_barrier
	s_add_u32 s56, s56, 0x100
	s_addc_u32 s57, s57, 0
	s_cmp_ge_i32 s58, s54
	s_mov_b64 s[12:13], s[16:17]
	s_mov_b32 s18, s58
	s_cbranch_scc0 .LBB0_1426
	s_branch .LBB0_1428

; #define PG8_STAGE(bufoff, gbase, voff) do { _Pragma("unroll") for (int _i = 0; _i < 2; ++_i) \
;         __builtin_amdgcn_global_load_lds((const unsigned*)((const char*)(gbase) + (voff)[_i]), (LAS unsigned*)(lds + (bufoff) + ldsw + _i * 8192), 16, 0, 0); } while (0)
; #define PG8_LDA(dst, b, h) do { _Pragma("unroll") for (int m = 0; m < 4; ++m) _Pragma("unroll") for (int k = 0; k < 2; ++k) dst[m][k] = *(const LAS bf16x8*)(lds + PG8_SA(b, h) + aoff + m * 2048 + k * 1024); } while (0)
; #define PG8_LDB(dst, b, h) do { _Pragma("unroll") for (int n = 0; n < 2; ++n) _Pragma("unroll") for (int k = 0; k < 2; ++k) dst[n][k] = *(const LAS bf16x8*)(lds + PG8_SB(b, h) + boff + n * 2048 + k * 1024); } while (0)
; #define PG8_MMA(ai, bj, At, Bt) do { __builtin_amdgcn_s_setprio(1); _Pragma("unroll") for (int m = 0; m < 4; ++m) _Pragma("unroll") for (int n = 0; n < 2; ++n) _Pragma("unroll") for (int k = 0; k < 2; ++k) \
;         acc[ai][bj][m][n] = __builtin_amdgcn_mfma_f32_16x16x32_bf16(Bt[n][k], At[m][k], acc[ai][bj][m][n], 0, 0, 0); __builtin_amdgcn_s_setprio(0); } while (0)
; #define PG8_WAIT_L(n) asm volatile("s_waitcnt lgkmcnt(" #n ")" ::: "memory")
; #define PG8_BAR __builtin_amdgcn_s_barrier()
; #define PG8_SCHED __builtin_amdgcn_sched_barrier(0)
; template <class Epi, class Sched, bool ATILE = false>
; __device__ __forceinline__ void gemm_phase(LAS unsigned char* lds, const Gemm g, const Sched& S, const Epi& E) {
;     ...
;             const bool last = (t == nt - 2);
;             const char* a1 = cA + (size_t)(t + 1) * kstepA;
;             const char* a2 = last ? nA : cA + (size_t)(t + 2) * kstepA; const char* b2 = last ? nB : cB + (size_t)(t + 2) * kstep;
;             const char* a3 = a2 + kstepA; const char* b3 = b2 + kstep;
;             PG8_LDB(B0, 0, 0); PG8_SCHED; PG8_LDA(At, 0, 0); PG8_STAGE(PG8_SA(1, 1), a1 + hstepA, voffA);
;             PG8_WAIT_L(8); PG8_BAR; PG8_WAIT_L(0); PG8_MMA(0, 0, At, B0); PG8_BAR; PG8_SCHED;
;             PG8_LDB(B1, 0, 1); PG8_STAGE(PG8_SB(0, 0), b2, voffB);
;             PG8_BAR; PG8_WAIT_L(0); PG8_MMA(0, 1, At, B1); PG8_BAR;
;             PG8_LDA(At, 0, 1); PG8_STAGE(PG8_SA(0, 0), a2, voffA);
;             PG8_BAR; PG8_WAIT_L(0); PG8_MMA(1, 0, At, B0); PG8_BAR; PG8_SCHED;
.LBB0_1517:
	ds_read_b128 v[96:99], v182
	ds_read_b128 v[100:103], v182 offset:1024
	ds_read_b128 v[112:115], v182 offset:2048
	ds_read_b128 v[116:119], v182 offset:3072
	s_add_i32 s54, s26, 2
	s_add_u32 s27, s24, 0xfffc0080
	s_addc_u32 s28, s25, -1
	s_cmp_eq_u32 s45, s26
	s_cselect_b32 s26, s44, s52
	s_cselect_b32 s29, s17, s28
	s_cselect_b32 s28, s42, s27
	s_cselect_b32 s27, s43, s53
	v_lshl_add_u64 v[206:207], s[24:25], 0, v[166:167]
	s_add_i32 m0, s23, 0xc000
	ds_read_b128 v[144:147], v183
	ds_read_b128 v[174:177], v183 offset:1024
	ds_read_b128 v[178:181], v183 offset:2048
	ds_read_b128 v[186:189], v183 offset:3072
	ds_read_b128 v[190:193], v183 offset:4096
	ds_read_b128 v[194:197], v183 offset:5120
	ds_read_b128 v[198:201], v183 offset:6144
	ds_read_b128 v[202:205], v183 offset:7168
	global_load_lds_dwordx4 v[206:207], off
	v_lshl_add_u64 v[206:207], s[24:25], 0, v[168:169]
	s_add_i32 m0, s23, 0xe000
	s_nop 0
	global_load_lds_dwordx4 v[206:207], off
	s_waitcnt lgkmcnt(8)
	s_barrier
	s_waitcnt lgkmcnt(0)
	s_setprio 1
	s_waitcnt lgkmcnt(0)
	v_mfma_f32_16x16x32_bf16 v[140:143], v[96:99], v[144:147], v[140:143]
	v_mfma_f32_16x16x32_bf16 v[136:139], v[112:115], v[144:147], v[136:139]
	v_mfma_f32_16x16x32_bf16 v[124:127], v[96:99], v[178:181], v[124:127]
	v_mfma_f32_16x16x32_bf16 v[120:123], v[112:115], v[178:181], v[120:123]
	v_mfma_f32_16x16x32_bf16 v[92:95], v[96:99], v[190:193], v[92:95]
	v_mfma_f32_16x16x32_bf16 v[88:91], v[112:115], v[190:193], v[88:91]
	v_mfma_f32_16x16x32_bf16 v[76:79], v[96:99], v[198:201], v[76:79]
	v_mfma_f32_16x16x32_bf16 v[72:75], v[112:115], v[198:201], v[72:75]
	v_mfma_f32_16x16x32_bf16 v[140:143], v[100:103], v[174:177], v[140:143]
	v_mfma_f32_16x16x32_bf16 v[136:139], v[116:119], v[174:177], v[136:139]
	v_mfma_f32_16x16x32_bf16 v[124:127], v[100:103], v[186:189], v[124:127]
	v_mfma_f32_16x16x32_bf16 v[120:123], v[116:119], v[186:189], v[120:123]
	v_mfma_f32_16x16x32_bf16 v[92:95], v[100:103], v[194:197], v[92:95]
	v_mfma_f32_16x16x32_bf16 v[88:91], v[116:119], v[194:197], v[88:91]
	v_mfma_f32_16x16x32_bf16 v[76:79], v[100:103], v[202:205], v[76:79]
	v_mfma_f32_16x16x32_bf16 v[72:75], v[116:119], v[202:205], v[72:75]
	s_setprio 0
	s_barrier
	s_add_i32 s55, s39, s5
	v_lshl_add_u64 v[222:223], s[26:27], 0, v[150:151]
	s_mov_b32 m0, s55
	ds_read_b128 v[206:209], v184
	ds_read_b128 v[210:213], v184 offset:1024
	ds_read_b128 v[214:217], v184 offset:2048
	ds_read_b128 v[218:221], v184 offset:3072
	global_load_lds_dwordx4 v[222:223], off
	v_lshl_add_u64 v[224:225], s[26:27], 0, v[164:165]
	s_add_i32 m0, s55, 0x2000
	s_nop 0
	global_load_lds_dwordx4 v[224:225], off
	s_barrier
	s_waitcnt lgkmcnt(0)
	s_setprio 1
	s_waitcnt lgkmcnt(0)
	v_mfma_f32_16x16x32_bf16 v[132:135], v[206:209], v[144:147], v[132:135]
	v_mfma_f32_16x16x32_bf16 v[128:131], v[214:217], v[144:147], v[128:131]
	v_mfma_f32_16x16x32_bf16 v[108:111], v[206:209], v[178:181], v[108:111]
	v_mfma_f32_16x16x32_bf16 v[104:107], v[214:217], v[178:181], v[104:107]
	v_mfma_f32_16x16x32_bf16 v[84:87], v[206:209], v[190:193], v[84:87]
	v_mfma_f32_16x16x32_bf16 v[80:83], v[214:217], v[190:193], v[80:83]
	v_mfma_f32_16x16x32_bf16 v[68:71], v[206:209], v[198:201], v[68:71]
	v_mfma_f32_16x16x32_bf16 v[64:67], v[214:217], v[198:201], v[64:67]
	v_mfma_f32_16x16x32_bf16 v[132:135], v[210:213], v[174:177], v[132:135]
	v_mfma_f32_16x16x32_bf16 v[128:131], v[218:221], v[174:177], v[128:131]
	v_mfma_f32_16x16x32_bf16 v[108:111], v[210:213], v[186:189], v[108:111]
	v_mfma_f32_16x16x32_bf16 v[104:107], v[218:221], v[186:189], v[104:107]
	v_mfma_f32_16x16x32_bf16 v[84:87], v[210:213], v[194:197], v[84:87]
	v_mfma_f32_16x16x32_bf16 v[80:83], v[218:221], v[194:197], v[80:83]
	v_mfma_f32_16x16x32_bf16 v[68:71], v[210:213], v[202:205], v[68:71]
	v_mfma_f32_16x16x32_bf16 v[64:67], v[218:221], v[202:205], v[64:67]
	s_setprio 0
	s_barrier
	s_mov_b32 m0, s23
	v_lshl_add_u64 v[226:227], s[28:29], 0, v[148:149]
	ds_read_b128 v[144:147], v183 offset:16384
	ds_read_b128 v[174:177], v183 offset:17408
	ds_read_b128 v[178:181], v183 offset:18432
	ds_read_b128 v[186:189], v183 offset:19456
	ds_read_b128 v[190:193], v183 offset:20480
	ds_read_b128 v[194:197], v183 offset:21504
	ds_read_b128 v[198:201], v183 offset:22528
	ds_read_b128 v[202:205], v183 offset:23552
	global_load_lds_dwordx4 v[226:227], off
	v_lshl_add_u64 v[228:229], s[28:29], 0, v[162:163]
	s_mov_b32 m0, s30
	s_nop 0
	global_load_lds_dwordx4 v[228:229], off
	s_barrier
	s_waitcnt lgkmcnt(0)
	s_setprio 1
	s_waitcnt lgkmcnt(0)
	v_mfma_f32_16x16x32_bf16 v[60:63], v[96:99], v[144:147], v[60:63]
	v_mfma_f32_16x16x32_bf16 v[56:59], v[112:115], v[144:147], v[56:59]
	v_mfma_f32_16x16x32_bf16 v[44:47], v[96:99], v[178:181], v[44:47]
	v_mfma_f32_16x16x32_bf16 v[40:43], v[112:115], v[178:181], v[40:43]
	v_mfma_f32_16x16x32_bf16 v[28:31], v[96:99], v[190:193], v[28:31]
	v_mfma_f32_16x16x32_bf16 v[24:27], v[112:115], v[190:193], v[24:27]
	v_mfma_f32_16x16x32_bf16 v[12:15], v[96:99], v[198:201], v[12:15]
	v_mfma_f32_16x16x32_bf16 v[8:11], v[112:115], v[198:201], v[8:11]
	v_mfma_f32_16x16x32_bf16 v[60:63], v[100:103], v[174:177], v[60:63]
	v_mfma_f32_16x16x32_bf16 v[56:59], v[116:119], v[174:177], v[56:59]
	v_mfma_f32_16x16x32_bf16 v[44:47], v[100:103], v[186:189], v[44:47]
	v_mfma_f32_16x16x32_bf16 v[40:43], v[116:119], v[186:189], v[40:43]
	v_mfma_f32_16x16x32_bf16 v[28:31], v[100:103], v[194:197], v[28:31]
	v_mfma_f32_16x16x32_bf16 v[24:27], v[116:119], v[194:197], v[24:27]
	v_mfma_f32_16x16x32_bf16 v[12:15], v[100:103], v[202:205], v[12:15]
	v_mfma_f32_16x16x32_bf16 v[8:11], v[116:119], v[202:205], v[8:11]
	s_setprio 0
	s_barrier
; #define PG8_STAGE(bufoff, gbase, voff) do { _Pragma("unroll") for (int _i = 0; _i < 2; ++_i) \
;         __builtin_amdgcn_global_load_lds((const unsigned*)((const char*)(gbase) + (voff)[_i]), (LAS unsigned*)(lds + (bufoff) + ldsw + _i * 8192), 16, 0, 0); } while (0)
; #define PG8_LDA(dst, b, h) do { _Pragma("unroll") for (int m = 0; m < 4; ++m) _Pragma("unroll") for (int k = 0; k < 2; ++k) dst[m][k] = *(const LAS bf16x8*)(lds + PG8_SA(b, h) + aoff + m * 2048 + k * 1024); } while (0)
; #define PG8_LDB(dst, b, h) do { _Pragma("unroll") for (int n = 0; n < 2; ++n) _Pragma("unroll") for (int k = 0; k < 2; ++k) dst[n][k] = *(const LAS bf16x8*)(lds + PG8_SB(b, h) + boff + n * 2048 + k * 1024); } while (0)
; #define PG8_MMA(ai, bj, At, Bt) do { __builtin_amdgcn_s_setprio(1); _Pragma("unroll") for (int m = 0; m < 4; ++m) _Pragma("unroll") for (int n = 0; n < 2; ++n) _Pragma("unroll") for (int k = 0; k < 2; ++k) \
;         acc[ai][bj][m][n] = __builtin_amdgcn_mfma_f32_16x16x32_bf16(Bt[n][k], At[m][k], acc[ai][bj][m][n], 0, 0, 0); __builtin_amdgcn_s_setprio(0); } while (0)
; #define PG8_WAIT_V(n) asm volatile("s_waitcnt vmcnt(" #n ")" ::: "memory")
; #define PG8_WAIT_L(n) asm volatile("s_waitcnt lgkmcnt(" #n ")" ::: "memory")
; #define PG8_BAR __builtin_amdgcn_s_barrier()
; #define PG8_SCHED __builtin_amdgcn_sched_barrier(0)
; template <class Epi, class Sched, bool ATILE = false>
; __device__ __forceinline__ void gemm_phase(LAS unsigned char* lds, const Gemm g, const Sched& S, const Epi& E) {
;     ...
;             PG8_STAGE(PG8_SB(0, 1), b2 + hstepB, voffB);
;             PG8_WAIT_V(6); PG8_BAR; PG8_MMA(1, 1, At, B1); PG8_BAR;
;             PG8_LDB(B0, 1, 0); PG8_SCHED; PG8_LDA(At, 1, 0); PG8_STAGE(PG8_SA(0, 1), a2 + hstepA, voffA);
;             PG8_WAIT_L(8); PG8_BAR; PG8_WAIT_L(0); PG8_MMA(0, 0, At, B0); PG8_BAR; PG8_SCHED;
;             PG8_LDB(B1, 1, 1); PG8_STAGE(PG8_SB(1, 0), b3, voffB);
;             PG8_BAR; PG8_WAIT_L(0); PG8_MMA(0, 1, At, B1); PG8_BAR;
	s_add_u32 s56, s26, 0x40000
	s_addc_u32 s57, s27, 0
	s_add_i32 s55, s40, s5
	v_lshl_add_u64 v[96:97], s[56:57], 0, v[150:151]
	s_mov_b32 m0, s55
	s_nop 0
	global_load_lds_dwordx4 v[96:97], off
	v_lshl_add_u64 v[96:97], s[56:57], 0, v[164:165]
	s_add_i32 m0, s55, 0x2000
	s_nop 0
	global_load_lds_dwordx4 v[96:97], off
	s_waitcnt vmcnt(6)
	s_barrier
	s_setprio 1
	v_mfma_f32_16x16x32_bf16 v[52:55], v[206:209], v[144:147], v[52:55]
	v_mfma_f32_16x16x32_bf16 v[48:51], v[214:217], v[144:147], v[48:51]
	v_mfma_f32_16x16x32_bf16 v[36:39], v[206:209], v[178:181], v[36:39]
	v_mfma_f32_16x16x32_bf16 v[32:35], v[214:217], v[178:181], v[32:35]
	v_mfma_f32_16x16x32_bf16 v[20:23], v[206:209], v[190:193], v[20:23]
	v_mfma_f32_16x16x32_bf16 v[16:19], v[214:217], v[190:193], v[16:19]
	v_mfma_f32_16x16x32_bf16 v[4:7], v[206:209], v[198:201], v[4:7]
	v_mfma_f32_16x16x32_bf16 v[0:3], v[214:217], v[198:201], v[0:3]
	v_mfma_f32_16x16x32_bf16 v[52:55], v[210:213], v[174:177], v[52:55]
	v_mfma_f32_16x16x32_bf16 v[48:51], v[218:221], v[174:177], v[48:51]
	v_mfma_f32_16x16x32_bf16 v[36:39], v[210:213], v[186:189], v[36:39]
	v_mfma_f32_16x16x32_bf16 v[32:35], v[218:221], v[186:189], v[32:35]
	v_mfma_f32_16x16x32_bf16 v[20:23], v[210:213], v[194:197], v[20:23]
	v_mfma_f32_16x16x32_bf16 v[16:19], v[218:221], v[194:197], v[16:19]
	v_mfma_f32_16x16x32_bf16 v[4:7], v[210:213], v[202:205], v[4:7]
	v_mfma_f32_16x16x32_bf16 v[0:3], v[218:221], v[202:205], v[0:3]
	s_setprio 0
	s_barrier
	s_add_i32 s55, 0, 0x18000
	v_add_u32_e32 v116, s55, v159
	ds_read_b128 v[96:99], v116
	ds_read_b128 v[100:103], v116 offset:1024
	ds_read_b128 v[112:115], v116 offset:2048
	ds_read_b128 v[116:119], v116 offset:3072
	s_add_u32 s28, s28, 0x40000
	s_addc_u32 s29, s29, 0
	s_mov_b32 m0, s31
	v_lshl_add_u64 v[206:207], s[28:29], 0, v[148:149]
	ds_read_b128 v[144:147], v183 offset:32768
	ds_read_b128 v[174:177], v183 offset:33792
	ds_read_b128 v[178:181], v183 offset:34816
	ds_read_b128 v[186:189], v183 offset:35840
	ds_read_b128 v[190:193], v183 offset:36864
	ds_read_b128 v[194:197], v183 offset:37888
	ds_read_b128 v[198:201], v183 offset:38912
	ds_read_b128 v[202:205], v183 offset:39936
	global_load_lds_dwordx4 v[206:207], off
	v_lshl_add_u64 v[206:207], s[28:29], 0, v[162:163]
	s_mov_b32 m0, s33
	s_nop 0
	global_load_lds_dwordx4 v[206:207], off
	s_waitcnt lgkmcnt(8)
	s_barrier
	s_waitcnt lgkmcnt(0)
	s_setprio 1
	s_waitcnt lgkmcnt(0)
	v_mfma_f32_16x16x32_bf16 v[140:143], v[96:99], v[144:147], v[140:143]
	v_mfma_f32_16x16x32_bf16 v[136:139], v[112:115], v[144:147], v[136:139]
	v_mfma_f32_16x16x32_bf16 v[124:127], v[96:99], v[178:181], v[124:127]
	v_mfma_f32_16x16x32_bf16 v[120:123], v[112:115], v[178:181], v[120:123]
	v_mfma_f32_16x16x32_bf16 v[92:95], v[96:99], v[190:193], v[92:95]
	v_mfma_f32_16x16x32_bf16 v[88:91], v[112:115], v[190:193], v[88:91]
	v_mfma_f32_16x16x32_bf16 v[76:79], v[96:99], v[198:201], v[76:79]
	v_mfma_f32_16x16x32_bf16 v[72:75], v[112:115], v[198:201], v[72:75]
	v_mfma_f32_16x16x32_bf16 v[140:143], v[100:103], v[174:177], v[140:143]
	v_mfma_f32_16x16x32_bf16 v[136:139], v[116:119], v[174:177], v[136:139]
	v_mfma_f32_16x16x32_bf16 v[124:127], v[100:103], v[186:189], v[124:127]
	v_mfma_f32_16x16x32_bf16 v[120:123], v[116:119], v[186:189], v[120:123]
	v_mfma_f32_16x16x32_bf16 v[92:95], v[100:103], v[194:197], v[92:95]
	v_mfma_f32_16x16x32_bf16 v[88:91], v[116:119], v[194:197], v[88:91]
	v_mfma_f32_16x16x32_bf16 v[76:79], v[100:103], v[202:205], v[76:79]
	v_mfma_f32_16x16x32_bf16 v[72:75], v[116:119], v[202:205], v[72:75]
	s_setprio 0
	s_barrier
	s_add_i32 s28, 0, 0x1c000
	s_add_i32 s29, s55, s5
	v_add_u32_e32 v185, s28, v159
	v_lshl_add_u64 v[222:223], v[222:223], 0, s[10:11]
	s_mov_b32 m0, s29
	ds_read_b128 v[206:209], v185
	ds_read_b128 v[210:213], v185 offset:1024
	ds_read_b128 v[214:217], v185 offset:2048
	ds_read_b128 v[218:221], v185 offset:3072
	global_load_lds_dwordx4 v[222:223], off
	v_lshl_add_u64 v[222:223], v[224:225], 0, s[10:11]
	s_add_i32 m0, s29, 0x2000
	s_nop 0
	global_load_lds_dwordx4 v[222:223], off
	s_barrier
; #define PG8_STAGE(bufoff, gbase, voff) do { _Pragma("unroll") for (int _i = 0; _i < 2; ++_i) \
;         __builtin_amdgcn_global_load_lds((const unsigned*)((const char*)(gbase) + (voff)[_i]), (LAS unsigned*)(lds + (bufoff) + ldsw + _i * 8192), 16, 0, 0); } while (0)
; #define PG8_LDA(dst, b, h) do { _Pragma("unroll") for (int m = 0; m < 4; ++m) _Pragma("unroll") for (int k = 0; k < 2; ++k) dst[m][k] = *(const LAS bf16x8*)(lds + PG8_SA(b, h) + aoff + m * 2048 + k * 1024); } while (0)
; #define PG8_MMA(ai, bj, At, Bt) do { __builtin_amdgcn_s_setprio(1); _Pragma("unroll") for (int m = 0; m < 4; ++m) _Pragma("unroll") for (int n = 0; n < 2; ++n) _Pragma("unroll") for (int k = 0; k < 2; ++k) \
;         acc[ai][bj][m][n] = __builtin_amdgcn_mfma_f32_16x16x32_bf16(Bt[n][k], At[m][k], acc[ai][bj][m][n], 0, 0, 0); __builtin_amdgcn_s_setprio(0); } while (0)
; #define PG8_WAIT_V(n) asm volatile("s_waitcnt vmcnt(" #n ")" ::: "memory")
; #define PG8_WAIT_L(n) asm volatile("s_waitcnt lgkmcnt(" #n ")" ::: "memory")
; #define PG8_BAR __builtin_amdgcn_s_barrier()
; #define PG8_SCHED __builtin_amdgcn_sched_barrier(0)
; template <class Epi, class Sched, bool ATILE = false>
; __device__ __forceinline__ void gemm_phase(LAS unsigned char* lds, const Gemm g, const Sched& S, const Epi& E) {
;     ...
;             PG8_BAR; PG8_WAIT_L(0); PG8_MMA(0, 1, At, B1); PG8_BAR;
;             PG8_LDA(At, 1, 1); PG8_STAGE(PG8_SA(1, 0), a3, voffA);
;             PG8_BAR; PG8_WAIT_L(0); PG8_MMA(1, 0, At, B0); PG8_BAR; PG8_SCHED;
;             PG8_STAGE(PG8_SB(1, 1), b3 + hstepB, voffB);
;             PG8_WAIT_V(6); PG8_BAR; PG8_MMA(1, 1, At, B1); PG8_BAR;
	s_waitcnt lgkmcnt(0)
	s_setprio 1
	s_waitcnt lgkmcnt(0)
	v_mfma_f32_16x16x32_bf16 v[132:135], v[206:209], v[144:147], v[132:135]
	v_mfma_f32_16x16x32_bf16 v[128:131], v[214:217], v[144:147], v[128:131]
	v_mfma_f32_16x16x32_bf16 v[108:111], v[206:209], v[178:181], v[108:111]
	v_mfma_f32_16x16x32_bf16 v[104:107], v[214:217], v[178:181], v[104:107]
	v_mfma_f32_16x16x32_bf16 v[84:87], v[206:209], v[190:193], v[84:87]
	v_mfma_f32_16x16x32_bf16 v[80:83], v[214:217], v[190:193], v[80:83]
	v_mfma_f32_16x16x32_bf16 v[68:71], v[206:209], v[198:201], v[68:71]
	v_mfma_f32_16x16x32_bf16 v[64:67], v[214:217], v[198:201], v[64:67]
	v_mfma_f32_16x16x32_bf16 v[132:135], v[210:213], v[174:177], v[132:135]
	v_mfma_f32_16x16x32_bf16 v[128:131], v[218:221], v[174:177], v[128:131]
	v_mfma_f32_16x16x32_bf16 v[108:111], v[210:213], v[186:189], v[108:111]
	v_mfma_f32_16x16x32_bf16 v[104:107], v[218:221], v[186:189], v[104:107]
	v_mfma_f32_16x16x32_bf16 v[84:87], v[210:213], v[194:197], v[84:87]
	v_mfma_f32_16x16x32_bf16 v[80:83], v[218:221], v[194:197], v[80:83]
	v_mfma_f32_16x16x32_bf16 v[68:71], v[210:213], v[202:205], v[68:71]
	v_mfma_f32_16x16x32_bf16 v[64:67], v[218:221], v[202:205], v[64:67]
	s_setprio 0
	s_barrier
	s_mov_b32 m0, s35
	v_lshl_add_u64 v[222:223], v[226:227], 0, s[10:11]
	ds_read_b128 v[144:147], v183 offset:49152
	ds_read_b128 v[174:177], v183 offset:50176
	ds_read_b128 v[178:181], v183 offset:51200
	ds_read_b128 v[186:189], v183 offset:52224
	ds_read_b128 v[190:193], v183 offset:53248
	ds_read_b128 v[194:197], v183 offset:54272
	ds_read_b128 v[198:201], v183 offset:55296
	ds_read_b128 v[202:205], v183 offset:56320
	global_load_lds_dwordx4 v[222:223], off
	v_lshl_add_u64 v[222:223], v[228:229], 0, s[10:11]
	s_mov_b32 m0, s36
	s_nop 0
	global_load_lds_dwordx4 v[222:223], off
	s_barrier
	s_waitcnt lgkmcnt(0)
	s_setprio 1
	s_waitcnt lgkmcnt(0)
	v_mfma_f32_16x16x32_bf16 v[60:63], v[96:99], v[144:147], v[60:63]
	v_mfma_f32_16x16x32_bf16 v[56:59], v[112:115], v[144:147], v[56:59]
	v_mfma_f32_16x16x32_bf16 v[44:47], v[96:99], v[178:181], v[44:47]
	v_mfma_f32_16x16x32_bf16 v[40:43], v[112:115], v[178:181], v[40:43]
	v_mfma_f32_16x16x32_bf16 v[28:31], v[96:99], v[190:193], v[28:31]
	v_mfma_f32_16x16x32_bf16 v[24:27], v[112:115], v[190:193], v[24:27]
	v_mfma_f32_16x16x32_bf16 v[12:15], v[96:99], v[198:201], v[12:15]
	v_mfma_f32_16x16x32_bf16 v[8:11], v[112:115], v[198:201], v[8:11]
	v_mfma_f32_16x16x32_bf16 v[60:63], v[100:103], v[174:177], v[60:63]
	v_mfma_f32_16x16x32_bf16 v[56:59], v[116:119], v[174:177], v[56:59]
	v_mfma_f32_16x16x32_bf16 v[44:47], v[100:103], v[186:189], v[44:47]
	v_mfma_f32_16x16x32_bf16 v[40:43], v[116:119], v[186:189], v[40:43]
	v_mfma_f32_16x16x32_bf16 v[28:31], v[100:103], v[194:197], v[28:31]
	v_mfma_f32_16x16x32_bf16 v[24:27], v[116:119], v[194:197], v[24:27]
	v_mfma_f32_16x16x32_bf16 v[12:15], v[100:103], v[202:205], v[12:15]
	v_mfma_f32_16x16x32_bf16 v[8:11], v[116:119], v[202:205], v[8:11]
	s_setprio 0
	s_barrier
	s_add_u32 s26, s26, 0x40080
	s_addc_u32 s27, s27, 0
	s_add_i32 s28, s28, s5
	v_lshl_add_u64 v[96:97], s[26:27], 0, v[150:151]
	s_mov_b32 m0, s28
	s_nop 0
	global_load_lds_dwordx4 v[96:97], off
	v_lshl_add_u64 v[96:97], s[26:27], 0, v[164:165]
	s_add_i32 m0, s28, 0x2000
	s_nop 0
	global_load_lds_dwordx4 v[96:97], off
	s_waitcnt vmcnt(6)
	s_barrier
	s_setprio 1
	v_mfma_f32_16x16x32_bf16 v[52:55], v[206:209], v[144:147], v[52:55]
	v_mfma_f32_16x16x32_bf16 v[48:51], v[214:217], v[144:147], v[48:51]
	v_mfma_f32_16x16x32_bf16 v[36:39], v[206:209], v[178:181], v[36:39]
	v_mfma_f32_16x16x32_bf16 v[32:35], v[214:217], v[178:181], v[32:35]
	v_mfma_f32_16x16x32_bf16 v[20:23], v[206:209], v[190:193], v[20:23]
	v_mfma_f32_16x16x32_bf16 v[16:19], v[214:217], v[190:193], v[16:19]
	v_mfma_f32_16x16x32_bf16 v[4:7], v[206:209], v[198:201], v[4:7]
	v_mfma_f32_16x16x32_bf16 v[0:3], v[214:217], v[198:201], v[0:3]
	v_mfma_f32_16x16x32_bf16 v[52:55], v[210:213], v[174:177], v[52:55]
	v_mfma_f32_16x16x32_bf16 v[48:51], v[218:221], v[174:177], v[48:51]
	v_mfma_f32_16x16x32_bf16 v[36:39], v[210:213], v[186:189], v[36:39]
	v_mfma_f32_16x16x32_bf16 v[32:35], v[218:221], v[186:189], v[32:35]
	v_mfma_f32_16x16x32_bf16 v[20:23], v[210:213], v[194:197], v[20:23]
	v_mfma_f32_16x16x32_bf16 v[16:19], v[218:221], v[194:197], v[16:19]
	v_mfma_f32_16x16x32_bf16 v[4:7], v[210:213], v[202:205], v[4:7]
	v_mfma_f32_16x16x32_bf16 v[0:3], v[218:221], v[202:205], v[0:3]
	s_setprio 0
	s_barrier
	s_add_u32 s24, s24, 0x100
	s_addc_u32 s25, s25, 0
	s_add_u32 s52, s52, 0x100
	s_addc_u32 s53, s53, 0
	s_cmp_ge_i32 s54, s13
	s_mov_b32 s26, s54
	s_cbranch_scc0 .LBB0_1517
	s_branch .LBB0_1508

; #define PG8_STAGE(bufoff, gbase, voff) do { _Pragma("unroll") for (int _i = 0; _i < 2; ++_i) \
;         __builtin_amdgcn_global_load_lds((const unsigned*)((const char*)(gbase) + (voff)[_i]), (LAS unsigned*)(lds + (bufoff) + ldsw + _i * 8192), 16, 0, 0); } while (0)
; #define PG8_LDA(dst, b, h) do { _Pragma("unroll") for (int m = 0; m < 4; ++m) _Pragma("unroll") for (int k = 0; k < 2; ++k) dst[m][k] = *(const LAS bf16x8*)(lds + PG8_SA(b, h) + aoff + m * 2048 + k * 1024); } while (0)
; #define PG8_LDB(dst, b, h) do { _Pragma("unroll") for (int n = 0; n < 2; ++n) _Pragma("unroll") for (int k = 0; k < 2; ++k) dst[n][k] = *(const LAS bf16x8*)(lds + PG8_SB(b, h) + boff + n * 2048 + k * 1024); } while (0)
; #define PG8_MMA(ai, bj, At, Bt) do { __builtin_amdgcn_s_setprio(1); _Pragma("unroll") for (int m = 0; m < 4; ++m) _Pragma("unroll") for (int n = 0; n < 2; ++n) _Pragma("unroll") for (int k = 0; k < 2; ++k) \
;         acc[ai][bj][m][n] = __builtin_amdgcn_mfma_f32_16x16x32_bf16(Bt[n][k], At[m][k], acc[ai][bj][m][n], 0, 0, 0); __builtin_amdgcn_s_setprio(0); } while (0)
; #define PG8_WAIT_L(n) asm volatile("s_waitcnt lgkmcnt(" #n ")" ::: "memory")
; #define PG8_BAR __builtin_amdgcn_s_barrier()
; #define PG8_SCHED __builtin_amdgcn_sched_barrier(0)
; template <class Epi, class Sched, bool ATILE = false>
; __device__ __forceinline__ void gemm_phase(LAS unsigned char* lds, const Gemm g, const Sched& S, const Epi& E) {
;     ...
;             const bool last = (t == nt - 2);
;             const char* a1 = cA + (size_t)(t + 1) * kstepA;
;             const char* a2 = last ? nA : cA + (size_t)(t + 2) * kstepA; const char* b2 = last ? nB : cB + (size_t)(t + 2) * kstep;
;             const char* a3 = a2 + kstepA; const char* b3 = b2 + kstep;
;             PG8_LDB(B0, 0, 0); PG8_SCHED; PG8_LDA(At, 0, 0); PG8_STAGE(PG8_SA(1, 1), a1 + hstepA, voffA);
;             PG8_WAIT_L(8); PG8_BAR; PG8_WAIT_L(0); PG8_MMA(0, 0, At, B0); PG8_BAR; PG8_SCHED;
;             PG8_LDB(B1, 0, 1); PG8_STAGE(PG8_SB(0, 0), b2, voffB);
;             PG8_BAR; PG8_WAIT_L(0); PG8_MMA(0, 1, At, B1); PG8_BAR;
;             PG8_LDA(At, 0, 1); PG8_STAGE(PG8_SA(0, 0), a2, voffA);
;             PG8_BAR; PG8_WAIT_L(0); PG8_MMA(1, 0, At, B0); PG8_BAR; PG8_SCHED;
.LBB0_1658:
	s_waitcnt lgkmcnt(0)
	ds_read_b128 v[128:131], v169
	ds_read_b128 v[132:135], v169 offset:1024
	ds_read_b128 v[136:139], v169 offset:2048
	ds_read_b128 v[140:143], v169 offset:3072
	s_add_i32 s29, s27, 2
	s_add_u32 s34, s30, 0x4000
	s_addc_u32 s35, s31, 0
	s_cmp_eq_u32 s11, s27
	s_cselect_b32 s38, s22, s34
	s_cselect_b32 s39, s23, s35
	s_cselect_b32 s34, s24, s13
	s_cselect_b32 s35, s25, s17
	s_add_u32 s36, s38, 0x8000
	s_addc_u32 s37, s39, 0
	v_lshl_add_u64 v[208:209], s[30:31], 0, v[186:187]
	s_add_i32 m0, s5, 0xc000
	ds_read_b128 v[144:147], v210
	ds_read_b128 v[148:151], v210 offset:1024
	ds_read_b128 v[192:195], v210 offset:2048
	ds_read_b128 v[196:199], v210 offset:3072
	ds_read_b128 v[200:203], v210 offset:4096
	ds_read_b128 v[204:207], v210 offset:5120
	ds_read_b128 v[214:217], v210 offset:6144
	ds_read_b128 v[218:221], v210 offset:7168
	global_load_lds_dwordx4 v[208:209], off
	v_lshl_add_u64 v[208:209], s[30:31], 0, v[188:189]
	s_add_i32 m0, s5, 0xe000
	s_nop 0
	global_load_lds_dwordx4 v[208:209], off
	s_waitcnt lgkmcnt(8)
	s_barrier
	s_waitcnt lgkmcnt(0)
	s_setprio 1
	s_waitcnt lgkmcnt(0)
	v_mfma_f32_16x16x32_bf16 v[120:123], v[128:131], v[144:147], v[120:123]
	v_mfma_f32_16x16x32_bf16 v[116:119], v[136:139], v[144:147], v[116:119]
	v_mfma_f32_16x16x32_bf16 v[108:111], v[128:131], v[192:195], v[108:111]
	v_mfma_f32_16x16x32_bf16 v[100:103], v[136:139], v[192:195], v[100:103]
	v_mfma_f32_16x16x32_bf16 v[92:95], v[128:131], v[200:203], v[92:95]
	v_mfma_f32_16x16x32_bf16 v[84:87], v[136:139], v[200:203], v[84:87]
	v_mfma_f32_16x16x32_bf16 v[76:79], v[128:131], v[214:217], v[76:79]
	v_mfma_f32_16x16x32_bf16 v[68:71], v[136:139], v[214:217], v[68:71]
	v_mfma_f32_16x16x32_bf16 v[120:123], v[132:135], v[148:151], v[120:123]
	v_mfma_f32_16x16x32_bf16 v[116:119], v[140:143], v[148:151], v[116:119]
	v_mfma_f32_16x16x32_bf16 v[108:111], v[132:135], v[196:199], v[108:111]
	v_mfma_f32_16x16x32_bf16 v[100:103], v[140:143], v[196:199], v[100:103]
	v_mfma_f32_16x16x32_bf16 v[92:95], v[132:135], v[204:207], v[92:95]
	v_mfma_f32_16x16x32_bf16 v[84:87], v[140:143], v[204:207], v[84:87]
	v_mfma_f32_16x16x32_bf16 v[76:79], v[132:135], v[218:221], v[76:79]
	v_mfma_f32_16x16x32_bf16 v[68:71], v[140:143], v[218:221], v[68:71]
	s_setprio 0
	s_barrier
	s_add_i32 s27, s52, s4
	v_lshl_add_u64 v[208:209], s[34:35], 0, v[162:163]
	s_mov_b32 m0, s27
	ds_read_b128 v[222:225], v211
	ds_read_b128 v[226:229], v211 offset:1024
	ds_read_b128 v[230:233], v211 offset:2048
	ds_read_b128 v[234:237], v211 offset:3072
	global_load_lds_dwordx4 v[208:209], off
	v_lshl_add_u64 v[238:239], s[34:35], 0, v[166:167]
	s_add_i32 m0, s27, 0x2000
	s_nop 0
	global_load_lds_dwordx4 v[238:239], off
	s_barrier
	s_waitcnt lgkmcnt(0)
	s_setprio 1
	s_waitcnt lgkmcnt(0)
	v_mfma_f32_16x16x32_bf16 v[124:127], v[222:225], v[144:147], v[124:127]
	v_mfma_f32_16x16x32_bf16 v[112:115], v[230:233], v[144:147], v[112:115]
	v_mfma_f32_16x16x32_bf16 v[104:107], v[222:225], v[192:195], v[104:107]
	v_mfma_f32_16x16x32_bf16 v[96:99], v[230:233], v[192:195], v[96:99]
	v_mfma_f32_16x16x32_bf16 v[88:91], v[222:225], v[200:203], v[88:91]
	v_mfma_f32_16x16x32_bf16 v[80:83], v[230:233], v[200:203], v[80:83]
	v_mfma_f32_16x16x32_bf16 v[72:75], v[222:225], v[214:217], v[72:75]
	v_mfma_f32_16x16x32_bf16 v[64:67], v[230:233], v[214:217], v[64:67]
	v_mfma_f32_16x16x32_bf16 v[124:127], v[226:229], v[148:151], v[124:127]
	v_mfma_f32_16x16x32_bf16 v[112:115], v[234:237], v[148:151], v[112:115]
	v_mfma_f32_16x16x32_bf16 v[104:107], v[226:229], v[196:199], v[104:107]
	v_mfma_f32_16x16x32_bf16 v[96:99], v[234:237], v[196:199], v[96:99]
	v_mfma_f32_16x16x32_bf16 v[88:91], v[226:229], v[204:207], v[88:91]
	v_mfma_f32_16x16x32_bf16 v[80:83], v[234:237], v[204:207], v[80:83]
	v_mfma_f32_16x16x32_bf16 v[72:75], v[226:229], v[218:221], v[72:75]
	v_mfma_f32_16x16x32_bf16 v[64:67], v[234:237], v[218:221], v[64:67]
	s_setprio 0
	s_barrier
	s_mov_b32 m0, s5
	v_lshl_add_u64 v[240:241], s[38:39], 0, v[160:161]
	ds_read_b128 v[144:147], v210 offset:16384
	ds_read_b128 v[148:151], v210 offset:17408
	ds_read_b128 v[192:195], v210 offset:18432
	ds_read_b128 v[196:199], v210 offset:19456
	ds_read_b128 v[200:203], v210 offset:20480
	ds_read_b128 v[204:207], v210 offset:21504
	ds_read_b128 v[214:217], v210 offset:22528
	ds_read_b128 v[218:221], v210 offset:23552
	global_load_lds_dwordx4 v[240:241], off
	v_lshl_add_u64 v[240:241], s[38:39], 0, v[164:165]
	s_mov_b32 m0, s33
	s_nop 0
	global_load_lds_dwordx4 v[240:241], off
	s_barrier
	s_waitcnt lgkmcnt(0)
	s_setprio 1
	s_waitcnt lgkmcnt(0)
	v_mfma_f32_16x16x32_bf16 v[60:63], v[128:131], v[144:147], v[60:63]
	v_mfma_f32_16x16x32_bf16 v[56:59], v[136:139], v[144:147], v[56:59]
	v_mfma_f32_16x16x32_bf16 v[44:47], v[128:131], v[192:195], v[44:47]
	v_mfma_f32_16x16x32_bf16 v[40:43], v[136:139], v[192:195], v[40:43]
	v_mfma_f32_16x16x32_bf16 v[28:31], v[128:131], v[200:203], v[28:31]
	v_mfma_f32_16x16x32_bf16 v[24:27], v[136:139], v[200:203], v[24:27]
	v_mfma_f32_16x16x32_bf16 v[12:15], v[128:131], v[214:217], v[12:15]
	v_mfma_f32_16x16x32_bf16 v[8:11], v[136:139], v[214:217], v[8:11]
	v_mfma_f32_16x16x32_bf16 v[60:63], v[132:135], v[148:151], v[60:63]
	v_mfma_f32_16x16x32_bf16 v[56:59], v[140:143], v[148:151], v[56:59]
	v_mfma_f32_16x16x32_bf16 v[44:47], v[132:135], v[196:199], v[44:47]
	v_mfma_f32_16x16x32_bf16 v[40:43], v[140:143], v[196:199], v[40:43]
	v_mfma_f32_16x16x32_bf16 v[28:31], v[132:135], v[204:207], v[28:31]
	v_mfma_f32_16x16x32_bf16 v[24:27], v[140:143], v[204:207], v[24:27]
	v_mfma_f32_16x16x32_bf16 v[12:15], v[132:135], v[218:221], v[12:15]
	v_mfma_f32_16x16x32_bf16 v[8:11], v[140:143], v[218:221], v[8:11]
	s_setprio 0
	s_barrier
; #define PG8_STAGE(bufoff, gbase, voff) do { _Pragma("unroll") for (int _i = 0; _i < 2; ++_i) \
;         __builtin_amdgcn_global_load_lds((const unsigned*)((const char*)(gbase) + (voff)[_i]), (LAS unsigned*)(lds + (bufoff) + ldsw + _i * 8192), 16, 0, 0); } while (0)
; #define PG8_LDA(dst, b, h) do { _Pragma("unroll") for (int m = 0; m < 4; ++m) _Pragma("unroll") for (int k = 0; k < 2; ++k) dst[m][k] = *(const LAS bf16x8*)(lds + PG8_SA(b, h) + aoff + m * 2048 + k * 1024); } while (0)
; #define PG8_LDB(dst, b, h) do { _Pragma("unroll") for (int n = 0; n < 2; ++n) _Pragma("unroll") for (int k = 0; k < 2; ++k) dst[n][k] = *(const LAS bf16x8*)(lds + PG8_SB(b, h) + boff + n * 2048 + k * 1024); } while (0)
; #define PG8_MMA(ai, bj, At, Bt) do { __builtin_amdgcn_s_setprio(1); _Pragma("unroll") for (int m = 0; m < 4; ++m) _Pragma("unroll") for (int n = 0; n < 2; ++n) _Pragma("unroll") for (int k = 0; k < 2; ++k) \
;         acc[ai][bj][m][n] = __builtin_amdgcn_mfma_f32_16x16x32_bf16(Bt[n][k], At[m][k], acc[ai][bj][m][n], 0, 0, 0); __builtin_amdgcn_s_setprio(0); } while (0)
; #define PG8_WAIT_V(n) asm volatile("s_waitcnt vmcnt(" #n ")" ::: "memory")
; #define PG8_WAIT_L(n) asm volatile("s_waitcnt lgkmcnt(" #n ")" ::: "memory")
; #define PG8_BAR __builtin_amdgcn_s_barrier()
; #define PG8_SCHED __builtin_amdgcn_sched_barrier(0)
; template <class Epi, class Sched, bool ATILE = false>
; __device__ __forceinline__ void gemm_phase(LAS unsigned char* lds, const Gemm g, const Sched& S, const Epi& E) {
;     ...
;             PG8_STAGE(PG8_SB(0, 1), b2 + hstepB, voffB);
;             PG8_WAIT_V(6); PG8_BAR; PG8_MMA(1, 1, At, B1); PG8_BAR;
;             PG8_LDB(B0, 1, 0); PG8_SCHED; PG8_LDA(At, 1, 0); PG8_STAGE(PG8_SA(0, 1), a2 + hstepA, voffA);
;             PG8_WAIT_L(8); PG8_BAR; PG8_WAIT_L(0); PG8_MMA(0, 0, At, B0); PG8_BAR; PG8_SCHED;
;             PG8_LDB(B1, 1, 1); PG8_STAGE(PG8_SB(1, 0), b3, voffB);
;             PG8_BAR; PG8_WAIT_L(0); PG8_MMA(0, 1, At, B1); PG8_BAR;
	s_add_u32 s56, s34, 0x80000
	s_addc_u32 s57, s35, 0
	s_add_i32 s27, s53, s4
	v_lshl_add_u64 v[128:129], s[56:57], 0, v[162:163]
	s_mov_b32 m0, s27
	s_nop 0
	global_load_lds_dwordx4 v[128:129], off
	v_lshl_add_u64 v[128:129], s[56:57], 0, v[166:167]
	s_add_i32 m0, s27, 0x2000
	s_nop 0
	global_load_lds_dwordx4 v[128:129], off
	s_waitcnt vmcnt(6)
	s_barrier
	s_setprio 1
	v_mfma_f32_16x16x32_bf16 v[52:55], v[222:225], v[144:147], v[52:55]
	v_mfma_f32_16x16x32_bf16 v[48:51], v[230:233], v[144:147], v[48:51]
	v_mfma_f32_16x16x32_bf16 v[36:39], v[222:225], v[192:195], v[36:39]
	v_mfma_f32_16x16x32_bf16 v[32:35], v[230:233], v[192:195], v[32:35]
	v_mfma_f32_16x16x32_bf16 v[20:23], v[222:225], v[200:203], v[20:23]
	v_mfma_f32_16x16x32_bf16 v[16:19], v[230:233], v[200:203], v[16:19]
	v_mfma_f32_16x16x32_bf16 v[4:7], v[222:225], v[214:217], v[4:7]
	v_mfma_f32_16x16x32_bf16 v[0:3], v[230:233], v[214:217], v[0:3]
	v_mfma_f32_16x16x32_bf16 v[52:55], v[226:229], v[148:151], v[52:55]
	v_mfma_f32_16x16x32_bf16 v[48:51], v[234:237], v[148:151], v[48:51]
	v_mfma_f32_16x16x32_bf16 v[36:39], v[226:229], v[196:199], v[36:39]
	v_mfma_f32_16x16x32_bf16 v[32:35], v[234:237], v[196:199], v[32:35]
	v_mfma_f32_16x16x32_bf16 v[20:23], v[226:229], v[204:207], v[20:23]
	v_mfma_f32_16x16x32_bf16 v[16:19], v[234:237], v[204:207], v[16:19]
	v_mfma_f32_16x16x32_bf16 v[4:7], v[226:229], v[218:221], v[4:7]
	v_mfma_f32_16x16x32_bf16 v[0:3], v[234:237], v[218:221], v[0:3]
	s_setprio 0
	s_barrier
	s_add_i32 s27, 0, 0x18000
	v_add_u32_e32 v140, s27, v157
	ds_read_b128 v[128:131], v140
	ds_read_b128 v[132:135], v140 offset:1024
	ds_read_b128 v[136:139], v140 offset:2048
	ds_read_b128 v[140:143], v140 offset:3072
	s_add_u32 s38, s38, 0x4000
	s_addc_u32 s39, s39, 0
	s_mov_b32 m0, s40
	v_lshl_add_u64 v[222:223], s[38:39], 0, v[160:161]
	ds_read_b128 v[144:147], v210 offset:32768
	ds_read_b128 v[148:151], v210 offset:33792
	ds_read_b128 v[192:195], v210 offset:34816
	ds_read_b128 v[196:199], v210 offset:35840
	ds_read_b128 v[200:203], v210 offset:36864
	ds_read_b128 v[204:207], v210 offset:37888
	ds_read_b128 v[214:217], v210 offset:38912
	ds_read_b128 v[218:221], v210 offset:39936
	global_load_lds_dwordx4 v[222:223], off
	v_lshl_add_u64 v[222:223], s[38:39], 0, v[164:165]
	s_mov_b32 m0, s41
	s_nop 0
	global_load_lds_dwordx4 v[222:223], off
	s_waitcnt lgkmcnt(8)
	s_barrier
	s_waitcnt lgkmcnt(0)
	s_setprio 1
	s_waitcnt lgkmcnt(0)
	v_mfma_f32_16x16x32_bf16 v[120:123], v[128:131], v[144:147], v[120:123]
	v_mfma_f32_16x16x32_bf16 v[116:119], v[136:139], v[144:147], v[116:119]
	v_mfma_f32_16x16x32_bf16 v[108:111], v[128:131], v[192:195], v[108:111]
	v_mfma_f32_16x16x32_bf16 v[100:103], v[136:139], v[192:195], v[100:103]
	v_mfma_f32_16x16x32_bf16 v[92:95], v[128:131], v[200:203], v[92:95]
	v_mfma_f32_16x16x32_bf16 v[84:87], v[136:139], v[200:203], v[84:87]
	v_mfma_f32_16x16x32_bf16 v[76:79], v[128:131], v[214:217], v[76:79]
	v_mfma_f32_16x16x32_bf16 v[68:71], v[136:139], v[214:217], v[68:71]
	v_mfma_f32_16x16x32_bf16 v[120:123], v[132:135], v[148:151], v[120:123]
	v_mfma_f32_16x16x32_bf16 v[116:119], v[140:143], v[148:151], v[116:119]
	v_mfma_f32_16x16x32_bf16 v[108:111], v[132:135], v[196:199], v[108:111]
	v_mfma_f32_16x16x32_bf16 v[100:103], v[140:143], v[196:199], v[100:103]
	v_mfma_f32_16x16x32_bf16 v[92:95], v[132:135], v[204:207], v[92:95]
	v_mfma_f32_16x16x32_bf16 v[84:87], v[140:143], v[204:207], v[84:87]
	v_mfma_f32_16x16x32_bf16 v[76:79], v[132:135], v[218:221], v[76:79]
	v_mfma_f32_16x16x32_bf16 v[68:71], v[140:143], v[218:221], v[68:71]
	s_setprio 0
	s_barrier
	s_add_i32 s38, 0, 0x1c000
	s_add_i32 s27, s27, s4
	v_add_u32_e32 v213, s38, v157
	v_lshl_add_u64 v[208:209], v[208:209], 0, s[8:9]
	s_mov_b32 m0, s27
	ds_read_b128 v[222:225], v213
	ds_read_b128 v[226:229], v213 offset:1024
	ds_read_b128 v[230:233], v213 offset:2048
	ds_read_b128 v[234:237], v213 offset:3072
	global_load_lds_dwordx4 v[208:209], off
	v_lshl_add_u64 v[208:209], v[238:239], 0, s[8:9]
	s_add_i32 m0, s27, 0x2000
	s_nop 0
	global_load_lds_dwordx4 v[208:209], off
	s_barrier
; #define PG8_STAGE(bufoff, gbase, voff) do { _Pragma("unroll") for (int _i = 0; _i < 2; ++_i) \
;         __builtin_amdgcn_global_load_lds((const unsigned*)((const char*)(gbase) + (voff)[_i]), (LAS unsigned*)(lds + (bufoff) + ldsw + _i * 8192), 16, 0, 0); } while (0)
; #define PG8_LDA(dst, b, h) do { _Pragma("unroll") for (int m = 0; m < 4; ++m) _Pragma("unroll") for (int k = 0; k < 2; ++k) dst[m][k] = *(const LAS bf16x8*)(lds + PG8_SA(b, h) + aoff + m * 2048 + k * 1024); } while (0)
; #define PG8_MMA(ai, bj, At, Bt) do { __builtin_amdgcn_s_setprio(1); _Pragma("unroll") for (int m = 0; m < 4; ++m) _Pragma("unroll") for (int n = 0; n < 2; ++n) _Pragma("unroll") for (int k = 0; k < 2; ++k) \
;         acc[ai][bj][m][n] = __builtin_amdgcn_mfma_f32_16x16x32_bf16(Bt[n][k], At[m][k], acc[ai][bj][m][n], 0, 0, 0); __builtin_amdgcn_s_setprio(0); } while (0)
; #define PG8_WAIT_V(n) asm volatile("s_waitcnt vmcnt(" #n ")" ::: "memory")
; #define PG8_WAIT_L(n) asm volatile("s_waitcnt lgkmcnt(" #n ")" ::: "memory")
; #define PG8_BAR __builtin_amdgcn_s_barrier()
; #define PG8_SCHED __builtin_amdgcn_sched_barrier(0)
; template <class Epi, class Sched, bool ATILE = false>
; __device__ __forceinline__ void gemm_phase(LAS unsigned char* lds, const Gemm g, const Sched& S, const Epi& E) {
;     ...
;             PG8_BAR; PG8_WAIT_L(0); PG8_MMA(0, 1, At, B1); PG8_BAR;
;             PG8_LDA(At, 1, 1); PG8_STAGE(PG8_SA(1, 0), a3, voffA);
;             PG8_BAR; PG8_WAIT_L(0); PG8_MMA(1, 0, At, B0); PG8_BAR; PG8_SCHED;
;             PG8_STAGE(PG8_SB(1, 1), b3 + hstepB, voffB);
;             PG8_WAIT_V(6); PG8_BAR; PG8_MMA(1, 1, At, B1); PG8_BAR;
	s_waitcnt lgkmcnt(0)
	s_setprio 1
	s_waitcnt lgkmcnt(0)
	v_mfma_f32_16x16x32_bf16 v[124:127], v[222:225], v[144:147], v[124:127]
	v_mfma_f32_16x16x32_bf16 v[112:115], v[230:233], v[144:147], v[112:115]
	v_mfma_f32_16x16x32_bf16 v[104:107], v[222:225], v[192:195], v[104:107]
	v_mfma_f32_16x16x32_bf16 v[96:99], v[230:233], v[192:195], v[96:99]
	v_mfma_f32_16x16x32_bf16 v[88:91], v[222:225], v[200:203], v[88:91]
	v_mfma_f32_16x16x32_bf16 v[80:83], v[230:233], v[200:203], v[80:83]
	v_mfma_f32_16x16x32_bf16 v[72:75], v[222:225], v[214:217], v[72:75]
	v_mfma_f32_16x16x32_bf16 v[64:67], v[230:233], v[214:217], v[64:67]
	v_mfma_f32_16x16x32_bf16 v[124:127], v[226:229], v[148:151], v[124:127]
	v_mfma_f32_16x16x32_bf16 v[112:115], v[234:237], v[148:151], v[112:115]
	v_mfma_f32_16x16x32_bf16 v[104:107], v[226:229], v[196:199], v[104:107]
	v_mfma_f32_16x16x32_bf16 v[96:99], v[234:237], v[196:199], v[96:99]
	v_mfma_f32_16x16x32_bf16 v[88:91], v[226:229], v[204:207], v[88:91]
	v_mfma_f32_16x16x32_bf16 v[80:83], v[234:237], v[204:207], v[80:83]
	v_mfma_f32_16x16x32_bf16 v[72:75], v[226:229], v[218:221], v[72:75]
	v_mfma_f32_16x16x32_bf16 v[64:67], v[234:237], v[218:221], v[64:67]
	s_setprio 0
	s_barrier
	s_mov_b32 m0, s43
	v_lshl_add_u64 v[208:209], s[36:37], 0, v[160:161]
	ds_read_b128 v[144:147], v210 offset:49152
	ds_read_b128 v[148:151], v210 offset:50176
	ds_read_b128 v[192:195], v210 offset:51200
	ds_read_b128 v[196:199], v210 offset:52224
	ds_read_b128 v[200:203], v210 offset:53248
	ds_read_b128 v[204:207], v210 offset:54272
	ds_read_b128 v[214:217], v210 offset:55296
	ds_read_b128 v[218:221], v210 offset:56320
	global_load_lds_dwordx4 v[208:209], off
	v_lshl_add_u64 v[208:209], s[36:37], 0, v[164:165]
	s_mov_b32 m0, s44
	s_nop 0
	global_load_lds_dwordx4 v[208:209], off
	s_barrier
	s_waitcnt lgkmcnt(0)
	s_setprio 1
	s_waitcnt lgkmcnt(0)
	v_mfma_f32_16x16x32_bf16 v[60:63], v[128:131], v[144:147], v[60:63]
	v_mfma_f32_16x16x32_bf16 v[56:59], v[136:139], v[144:147], v[56:59]
	v_mfma_f32_16x16x32_bf16 v[44:47], v[128:131], v[192:195], v[44:47]
	v_mfma_f32_16x16x32_bf16 v[40:43], v[136:139], v[192:195], v[40:43]
	v_mfma_f32_16x16x32_bf16 v[28:31], v[128:131], v[200:203], v[28:31]
	v_mfma_f32_16x16x32_bf16 v[24:27], v[136:139], v[200:203], v[24:27]
	v_mfma_f32_16x16x32_bf16 v[12:15], v[128:131], v[214:217], v[12:15]
	v_mfma_f32_16x16x32_bf16 v[8:11], v[136:139], v[214:217], v[8:11]
	v_mfma_f32_16x16x32_bf16 v[60:63], v[132:135], v[148:151], v[60:63]
	v_mfma_f32_16x16x32_bf16 v[56:59], v[140:143], v[148:151], v[56:59]
	v_mfma_f32_16x16x32_bf16 v[44:47], v[132:135], v[196:199], v[44:47]
	v_mfma_f32_16x16x32_bf16 v[40:43], v[140:143], v[196:199], v[40:43]
	v_mfma_f32_16x16x32_bf16 v[28:31], v[132:135], v[204:207], v[28:31]
	v_mfma_f32_16x16x32_bf16 v[24:27], v[140:143], v[204:207], v[24:27]
	v_mfma_f32_16x16x32_bf16 v[12:15], v[132:135], v[218:221], v[12:15]
	v_mfma_f32_16x16x32_bf16 v[8:11], v[140:143], v[218:221], v[8:11]
	s_setprio 0
	s_barrier
	s_add_u32 s34, s34, 0x80080
	s_addc_u32 s35, s35, 0
	s_add_i32 s27, s38, s4
	v_lshl_add_u64 v[128:129], s[34:35], 0, v[162:163]
	s_mov_b32 m0, s27
	s_nop 0
	global_load_lds_dwordx4 v[128:129], off
	v_lshl_add_u64 v[128:129], s[34:35], 0, v[166:167]
	s_add_i32 m0, s27, 0x2000
	s_nop 0
	global_load_lds_dwordx4 v[128:129], off
	s_waitcnt vmcnt(6)
	s_barrier
	s_setprio 1
	v_mfma_f32_16x16x32_bf16 v[52:55], v[222:225], v[144:147], v[52:55]
	v_mfma_f32_16x16x32_bf16 v[48:51], v[230:233], v[144:147], v[48:51]
	v_mfma_f32_16x16x32_bf16 v[36:39], v[222:225], v[192:195], v[36:39]
	v_mfma_f32_16x16x32_bf16 v[32:35], v[230:233], v[192:195], v[32:35]
	v_mfma_f32_16x16x32_bf16 v[20:23], v[222:225], v[200:203], v[20:23]
	v_mfma_f32_16x16x32_bf16 v[16:19], v[230:233], v[200:203], v[16:19]
	v_mfma_f32_16x16x32_bf16 v[4:7], v[222:225], v[214:217], v[4:7]
	v_mfma_f32_16x16x32_bf16 v[0:3], v[230:233], v[214:217], v[0:3]
	v_mfma_f32_16x16x32_bf16 v[52:55], v[226:229], v[148:151], v[52:55]
	v_mfma_f32_16x16x32_bf16 v[48:51], v[234:237], v[148:151], v[48:51]
	v_mfma_f32_16x16x32_bf16 v[36:39], v[226:229], v[196:199], v[36:39]
	v_mfma_f32_16x16x32_bf16 v[32:35], v[234:237], v[196:199], v[32:35]
	v_mfma_f32_16x16x32_bf16 v[20:23], v[226:229], v[204:207], v[20:23]
	v_mfma_f32_16x16x32_bf16 v[16:19], v[234:237], v[204:207], v[16:19]
	v_mfma_f32_16x16x32_bf16 v[4:7], v[226:229], v[218:221], v[4:7]
	v_mfma_f32_16x16x32_bf16 v[0:3], v[234:237], v[218:221], v[0:3]
	s_setprio 0
	s_barrier
	s_add_u32 s13, s13, 0x100
	s_addc_u32 s17, s17, 0
	s_add_u32 s30, s30, 0x10000
	s_addc_u32 s31, s31, 0
	s_cmp_ge_i32 s29, s1
	s_mov_b32 s27, s29
	s_cbranch_scc0 .LBB0_1658
	s_branch .LBB0_1662

; #define PG8_STAGE(bufoff, gbase, voff) do { _Pragma("unroll") for (int _i = 0; _i < 2; ++_i) \
;         __builtin_amdgcn_global_load_lds((const unsigned*)((const char*)(gbase) + (voff)[_i]), (LAS unsigned*)(lds + (bufoff) + ldsw + _i * 8192), 16, 0, 0); } while (0)
; #define PG8_LDA(dst, b, h) do { _Pragma("unroll") for (int m = 0; m < 4; ++m) _Pragma("unroll") for (int k = 0; k < 2; ++k) dst[m][k] = *(const LAS bf16x8*)(lds + PG8_SA(b, h) + aoff + m * 2048 + k * 1024); } while (0)
; #define PG8_LDB(dst, b, h) do { _Pragma("unroll") for (int n = 0; n < 2; ++n) _Pragma("unroll") for (int k = 0; k < 2; ++k) dst[n][k] = *(const LAS bf16x8*)(lds + PG8_SB(b, h) + boff + n * 2048 + k * 1024); } while (0)
; #define PG8_MMA(ai, bj, At, Bt) do { __builtin_amdgcn_s_setprio(1); _Pragma("unroll") for (int m = 0; m < 4; ++m) _Pragma("unroll") for (int n = 0; n < 2; ++n) _Pragma("unroll") for (int k = 0; k < 2; ++k) \
;         acc[ai][bj][m][n] = __builtin_amdgcn_mfma_f32_16x16x32_bf16(Bt[n][k], At[m][k], acc[ai][bj][m][n], 0, 0, 0); __builtin_amdgcn_s_setprio(0); } while (0)
; #define PG8_WAIT_L(n) asm volatile("s_waitcnt lgkmcnt(" #n ")" ::: "memory")
; #define PG8_BAR __builtin_amdgcn_s_barrier()
; #define PG8_SCHED __builtin_amdgcn_sched_barrier(0)
; template <class Epi, class Sched, bool ATILE = false>
; __device__ __forceinline__ void gemm_phase(LAS unsigned char* lds, const Gemm g, const Sched& S, const Epi& E) {
;     ...
;             const bool last = (t == nt - 2);
;             const char* a1 = cA + (size_t)(t + 1) * kstepA;
;             const char* a2 = last ? nA : cA + (size_t)(t + 2) * kstepA; const char* b2 = last ? nB : cB + (size_t)(t + 2) * kstep;
;             const char* a3 = a2 + kstepA; const char* b3 = b2 + kstep;
;             PG8_LDB(B0, 0, 0); PG8_SCHED; PG8_LDA(At, 0, 0); PG8_STAGE(PG8_SA(1, 1), a1 + hstepA, voffA);
;             PG8_WAIT_L(8); PG8_BAR; PG8_WAIT_L(0); PG8_MMA(0, 0, At, B0); PG8_BAR; PG8_SCHED;
;             PG8_LDB(B1, 0, 1); PG8_STAGE(PG8_SB(0, 0), b2, voffB);
;             PG8_BAR; PG8_WAIT_L(0); PG8_MMA(0, 1, At, B1); PG8_BAR;
;             PG8_LDA(At, 0, 1); PG8_STAGE(PG8_SA(0, 0), a2, voffA);
;             PG8_BAR; PG8_WAIT_L(0); PG8_MMA(1, 0, At, B0); PG8_BAR; PG8_SCHED;
.LBB0_1812:
	ds_read_b128 v[176:179], v139
	ds_read_b128 v[180:183], v139 offset:1024
	ds_read_b128 v[184:187], v139 offset:2048
	ds_read_b128 v[188:191], v139 offset:3072
	s_add_i32 s34, s8, 2
	s_add_u32 s9, s6, 0xfff80080
	s_addc_u32 s10, s7, -1
	s_cmp_eq_u32 s19, s8
	s_cselect_b32 s8, s18, s25
	s_cselect_b32 s11, s13, s10
	s_cselect_b32 s10, s16, s9
	s_cselect_b32 s9, s17, s27
	v_lshl_add_u64 v[224:225], s[6:7], 0, v[164:165]
	s_add_i32 m0, s37, 0xc000
	ds_read_b128 v[192:195], v159
	ds_read_b128 v[196:199], v159 offset:1024
	ds_read_b128 v[200:203], v159 offset:2048
	ds_read_b128 v[204:207], v159 offset:3072
	ds_read_b128 v[208:211], v159 offset:4096
	ds_read_b128 v[212:215], v159 offset:5120
	ds_read_b128 v[216:219], v159 offset:6144
	ds_read_b128 v[220:223], v159 offset:7168
	global_load_lds_dwordx4 v[224:225], off
	v_lshl_add_u64 v[224:225], s[6:7], 0, v[166:167]
	s_add_i32 m0, s37, 0xe000
	s_nop 0
	global_load_lds_dwordx4 v[224:225], off
	s_waitcnt lgkmcnt(8)
	s_barrier
	s_waitcnt lgkmcnt(0)
	s_setprio 1
	s_waitcnt lgkmcnt(0)
	v_mfma_f32_16x16x32_bf16 v[120:123], v[176:179], v[192:195], v[120:123]
	v_mfma_f32_16x16x32_bf16 v[112:115], v[184:187], v[192:195], v[112:115]
	v_mfma_f32_16x16x32_bf16 v[104:107], v[176:179], v[200:203], v[104:107]
	v_mfma_f32_16x16x32_bf16 v[96:99], v[184:187], v[200:203], v[96:99]
	v_mfma_f32_16x16x32_bf16 v[88:91], v[176:179], v[208:211], v[88:91]
	v_mfma_f32_16x16x32_bf16 v[80:83], v[184:187], v[208:211], v[80:83]
	v_mfma_f32_16x16x32_bf16 v[72:75], v[176:179], v[216:219], v[72:75]
	v_mfma_f32_16x16x32_bf16 v[64:67], v[184:187], v[216:219], v[64:67]
	v_mfma_f32_16x16x32_bf16 v[120:123], v[180:183], v[196:199], v[120:123]
	v_mfma_f32_16x16x32_bf16 v[112:115], v[188:191], v[196:199], v[112:115]
	v_mfma_f32_16x16x32_bf16 v[104:107], v[180:183], v[204:207], v[104:107]
	v_mfma_f32_16x16x32_bf16 v[96:99], v[188:191], v[204:207], v[96:99]
	v_mfma_f32_16x16x32_bf16 v[88:91], v[180:183], v[212:215], v[88:91]
	v_mfma_f32_16x16x32_bf16 v[80:83], v[188:191], v[212:215], v[80:83]
	v_mfma_f32_16x16x32_bf16 v[72:75], v[180:183], v[220:223], v[72:75]
	v_mfma_f32_16x16x32_bf16 v[64:67], v[188:191], v[220:223], v[64:67]
	s_setprio 0
	s_barrier
	s_add_i32 s35, s51, s36
	v_lshl_add_u64 v[240:241], s[8:9], 0, v[130:131]
	s_mov_b32 m0, s35
	ds_read_b128 v[224:227], v173
	ds_read_b128 v[228:231], v173 offset:1024
	ds_read_b128 v[232:235], v173 offset:2048
	ds_read_b128 v[236:239], v173 offset:3072
	global_load_lds_dwordx4 v[240:241], off
	v_lshl_add_u64 v[242:243], s[8:9], 0, v[134:135]
	s_add_i32 m0, s35, 0x2000
	s_nop 0
	global_load_lds_dwordx4 v[242:243], off
	s_barrier
	s_waitcnt lgkmcnt(0)
	s_setprio 1
	s_waitcnt lgkmcnt(0)
	v_mfma_f32_16x16x32_bf16 v[124:127], v[224:227], v[192:195], v[124:127]
	v_mfma_f32_16x16x32_bf16 v[116:119], v[232:235], v[192:195], v[116:119]
	v_mfma_f32_16x16x32_bf16 v[108:111], v[224:227], v[200:203], v[108:111]
	v_mfma_f32_16x16x32_bf16 v[100:103], v[232:235], v[200:203], v[100:103]
	v_mfma_f32_16x16x32_bf16 v[92:95], v[224:227], v[208:211], v[92:95]
	v_mfma_f32_16x16x32_bf16 v[84:87], v[232:235], v[208:211], v[84:87]
	v_mfma_f32_16x16x32_bf16 v[76:79], v[224:227], v[216:219], v[76:79]
	v_mfma_f32_16x16x32_bf16 v[68:71], v[232:235], v[216:219], v[68:71]
	v_mfma_f32_16x16x32_bf16 v[124:127], v[228:231], v[196:199], v[124:127]
	v_mfma_f32_16x16x32_bf16 v[116:119], v[236:239], v[196:199], v[116:119]
	v_mfma_f32_16x16x32_bf16 v[108:111], v[228:231], v[204:207], v[108:111]
	v_mfma_f32_16x16x32_bf16 v[100:103], v[236:239], v[204:207], v[100:103]
	v_mfma_f32_16x16x32_bf16 v[92:95], v[228:231], v[212:215], v[92:95]
	v_mfma_f32_16x16x32_bf16 v[84:87], v[236:239], v[212:215], v[84:87]
	v_mfma_f32_16x16x32_bf16 v[76:79], v[228:231], v[220:223], v[76:79]
	v_mfma_f32_16x16x32_bf16 v[68:71], v[236:239], v[220:223], v[68:71]
	s_setprio 0
	s_barrier
	s_mov_b32 m0, s37
	v_lshl_add_u64 v[244:245], s[10:11], 0, v[128:129]
	ds_read_b128 v[192:195], v159 offset:16384
	ds_read_b128 v[196:199], v159 offset:17408
	ds_read_b128 v[200:203], v159 offset:18432
	ds_read_b128 v[204:207], v159 offset:19456
	ds_read_b128 v[208:211], v159 offset:20480
	ds_read_b128 v[212:215], v159 offset:21504
	ds_read_b128 v[216:219], v159 offset:22528
	ds_read_b128 v[220:223], v159 offset:23552
	global_load_lds_dwordx4 v[244:245], off
	v_lshl_add_u64 v[246:247], s[10:11], 0, v[132:133]
	s_mov_b32 m0, s38
	s_nop 0
	global_load_lds_dwordx4 v[246:247], off
	s_barrier
	s_waitcnt lgkmcnt(0)
	s_setprio 1
	s_waitcnt lgkmcnt(0)
	v_mfma_f32_16x16x32_bf16 v[56:59], v[176:179], v[192:195], v[56:59]
	v_mfma_f32_16x16x32_bf16 v[48:51], v[184:187], v[192:195], v[48:51]
	v_mfma_f32_16x16x32_bf16 v[40:43], v[176:179], v[200:203], v[40:43]
	v_mfma_f32_16x16x32_bf16 v[32:35], v[184:187], v[200:203], v[32:35]
	v_mfma_f32_16x16x32_bf16 v[24:27], v[176:179], v[208:211], v[24:27]
	v_mfma_f32_16x16x32_bf16 v[16:19], v[184:187], v[208:211], v[16:19]
	v_mfma_f32_16x16x32_bf16 v[8:11], v[176:179], v[216:219], v[8:11]
	v_mfma_f32_16x16x32_bf16 v[4:7], v[184:187], v[216:219], v[4:7]
	v_mfma_f32_16x16x32_bf16 v[56:59], v[180:183], v[196:199], v[56:59]
	v_mfma_f32_16x16x32_bf16 v[48:51], v[188:191], v[196:199], v[48:51]
	v_mfma_f32_16x16x32_bf16 v[40:43], v[180:183], v[204:207], v[40:43]
	v_mfma_f32_16x16x32_bf16 v[32:35], v[188:191], v[204:207], v[32:35]
	v_mfma_f32_16x16x32_bf16 v[24:27], v[180:183], v[212:215], v[24:27]
	v_mfma_f32_16x16x32_bf16 v[16:19], v[188:191], v[212:215], v[16:19]
	v_mfma_f32_16x16x32_bf16 v[8:11], v[180:183], v[220:223], v[8:11]
	v_mfma_f32_16x16x32_bf16 v[4:7], v[188:191], v[220:223], v[4:7]
	s_setprio 0
	s_barrier
; #define PG8_STAGE(bufoff, gbase, voff) do { _Pragma("unroll") for (int _i = 0; _i < 2; ++_i) \
;         __builtin_amdgcn_global_load_lds((const unsigned*)((const char*)(gbase) + (voff)[_i]), (LAS unsigned*)(lds + (bufoff) + ldsw + _i * 8192), 16, 0, 0); } while (0)
; #define PG8_LDA(dst, b, h) do { _Pragma("unroll") for (int m = 0; m < 4; ++m) _Pragma("unroll") for (int k = 0; k < 2; ++k) dst[m][k] = *(const LAS bf16x8*)(lds + PG8_SA(b, h) + aoff + m * 2048 + k * 1024); } while (0)
; #define PG8_LDB(dst, b, h) do { _Pragma("unroll") for (int n = 0; n < 2; ++n) _Pragma("unroll") for (int k = 0; k < 2; ++k) dst[n][k] = *(const LAS bf16x8*)(lds + PG8_SB(b, h) + boff + n * 2048 + k * 1024); } while (0)
; #define PG8_MMA(ai, bj, At, Bt) do { __builtin_amdgcn_s_setprio(1); _Pragma("unroll") for (int m = 0; m < 4; ++m) _Pragma("unroll") for (int n = 0; n < 2; ++n) _Pragma("unroll") for (int k = 0; k < 2; ++k) \
;         acc[ai][bj][m][n] = __builtin_amdgcn_mfma_f32_16x16x32_bf16(Bt[n][k], At[m][k], acc[ai][bj][m][n], 0, 0, 0); __builtin_amdgcn_s_setprio(0); } while (0)
; #define PG8_WAIT_V(n) asm volatile("s_waitcnt vmcnt(" #n ")" ::: "memory")
; #define PG8_WAIT_L(n) asm volatile("s_waitcnt lgkmcnt(" #n ")" ::: "memory")
; #define PG8_BAR __builtin_amdgcn_s_barrier()
; #define PG8_SCHED __builtin_amdgcn_sched_barrier(0)
; template <class Epi, class Sched, bool ATILE = false>
; __device__ __forceinline__ void gemm_phase(LAS unsigned char* lds, const Gemm g, const Sched& S, const Epi& E) {
;     ...
;             PG8_STAGE(PG8_SB(0, 1), b2 + hstepB, voffB);
;             PG8_WAIT_V(6); PG8_BAR; PG8_MMA(1, 1, At, B1); PG8_BAR;
;             PG8_LDB(B0, 1, 0); PG8_SCHED; PG8_LDA(At, 1, 0); PG8_STAGE(PG8_SA(0, 1), a2 + hstepA, voffA);
;             PG8_WAIT_L(8); PG8_BAR; PG8_WAIT_L(0); PG8_MMA(0, 0, At, B0); PG8_BAR; PG8_SCHED;
;             PG8_LDB(B1, 1, 1); PG8_STAGE(PG8_SB(1, 0), b3, voffB);
;             PG8_BAR; PG8_WAIT_L(0); PG8_MMA(0, 1, At, B1); PG8_BAR;
	s_add_u32 s54, s8, 0x80000
	s_addc_u32 s55, s9, 0
	s_add_i32 s35, s52, s36
	v_lshl_add_u64 v[176:177], s[54:55], 0, v[130:131]
	s_mov_b32 m0, s35
	s_nop 0
	global_load_lds_dwordx4 v[176:177], off
	v_lshl_add_u64 v[176:177], s[54:55], 0, v[134:135]
	s_add_i32 m0, s35, 0x2000
	s_nop 0
	global_load_lds_dwordx4 v[176:177], off
	s_waitcnt vmcnt(6)
	s_barrier
	s_setprio 1
	v_mfma_f32_16x16x32_bf16 v[60:63], v[224:227], v[192:195], v[60:63]
	v_mfma_f32_16x16x32_bf16 v[52:55], v[232:235], v[192:195], v[52:55]
	v_mfma_f32_16x16x32_bf16 v[44:47], v[224:227], v[200:203], v[44:47]
	v_mfma_f32_16x16x32_bf16 v[36:39], v[232:235], v[200:203], v[36:39]
	v_mfma_f32_16x16x32_bf16 v[28:31], v[224:227], v[208:211], v[28:31]
	v_mfma_f32_16x16x32_bf16 v[20:23], v[232:235], v[208:211], v[20:23]
	v_mfma_f32_16x16x32_bf16 v[12:15], v[224:227], v[216:219], v[12:15]
	v_mfma_f32_16x16x32_bf16 v[0:3], v[232:235], v[216:219], v[0:3]
	v_mfma_f32_16x16x32_bf16 v[60:63], v[228:231], v[196:199], v[60:63]
	v_mfma_f32_16x16x32_bf16 v[52:55], v[236:239], v[196:199], v[52:55]
	v_mfma_f32_16x16x32_bf16 v[44:47], v[228:231], v[204:207], v[44:47]
	v_mfma_f32_16x16x32_bf16 v[36:39], v[236:239], v[204:207], v[36:39]
	v_mfma_f32_16x16x32_bf16 v[28:31], v[228:231], v[212:215], v[28:31]
	v_mfma_f32_16x16x32_bf16 v[20:23], v[236:239], v[212:215], v[20:23]
	v_mfma_f32_16x16x32_bf16 v[12:15], v[228:231], v[220:223], v[12:15]
	v_mfma_f32_16x16x32_bf16 v[0:3], v[236:239], v[220:223], v[0:3]
	s_setprio 0
	s_barrier
	s_add_i32 s35, 0, 0x18000
	v_add_u32_e32 v172, s35, v157
	ds_read_b128 v[176:179], v172
	ds_read_b128 v[180:183], v172 offset:1024
	ds_read_b128 v[184:187], v172 offset:2048
	ds_read_b128 v[188:191], v172 offset:3072
	s_add_u32 s10, s10, 0x80000
	s_addc_u32 s11, s11, 0
	s_mov_b32 m0, s39
	v_lshl_add_u64 v[224:225], s[10:11], 0, v[128:129]
	ds_read_b128 v[192:195], v159 offset:32768
	ds_read_b128 v[196:199], v159 offset:33792
	ds_read_b128 v[200:203], v159 offset:34816
	ds_read_b128 v[204:207], v159 offset:35840
	ds_read_b128 v[208:211], v159 offset:36864
	ds_read_b128 v[212:215], v159 offset:37888
	ds_read_b128 v[216:219], v159 offset:38912
	ds_read_b128 v[220:223], v159 offset:39936
	global_load_lds_dwordx4 v[224:225], off
	v_lshl_add_u64 v[224:225], s[10:11], 0, v[132:133]
	s_mov_b32 m0, s40
	s_nop 0
	global_load_lds_dwordx4 v[224:225], off
	s_waitcnt lgkmcnt(8)
	s_barrier
	s_waitcnt lgkmcnt(0)
	s_setprio 1
	s_waitcnt lgkmcnt(0)
	v_mfma_f32_16x16x32_bf16 v[120:123], v[176:179], v[192:195], v[120:123]
	v_mfma_f32_16x16x32_bf16 v[112:115], v[184:187], v[192:195], v[112:115]
	v_mfma_f32_16x16x32_bf16 v[104:107], v[176:179], v[200:203], v[104:107]
	v_mfma_f32_16x16x32_bf16 v[96:99], v[184:187], v[200:203], v[96:99]
	v_mfma_f32_16x16x32_bf16 v[88:91], v[176:179], v[208:211], v[88:91]
	v_mfma_f32_16x16x32_bf16 v[80:83], v[184:187], v[208:211], v[80:83]
	v_mfma_f32_16x16x32_bf16 v[72:75], v[176:179], v[216:219], v[72:75]
	v_mfma_f32_16x16x32_bf16 v[64:67], v[184:187], v[216:219], v[64:67]
	v_mfma_f32_16x16x32_bf16 v[120:123], v[180:183], v[196:199], v[120:123]
	v_mfma_f32_16x16x32_bf16 v[112:115], v[188:191], v[196:199], v[112:115]
	v_mfma_f32_16x16x32_bf16 v[104:107], v[180:183], v[204:207], v[104:107]
	v_mfma_f32_16x16x32_bf16 v[96:99], v[188:191], v[204:207], v[96:99]
	v_mfma_f32_16x16x32_bf16 v[88:91], v[180:183], v[212:215], v[88:91]
	v_mfma_f32_16x16x32_bf16 v[80:83], v[188:191], v[212:215], v[80:83]
	v_mfma_f32_16x16x32_bf16 v[72:75], v[180:183], v[220:223], v[72:75]
	v_mfma_f32_16x16x32_bf16 v[64:67], v[188:191], v[220:223], v[64:67]
	s_setprio 0
	s_barrier
	s_add_i32 s10, 0, 0x1c000
	s_add_i32 s11, s35, s36
	v_add_u32_e32 v172, s10, v157
	v_lshl_add_u64 v[240:241], v[240:241], 0, s[22:23]
	s_mov_b32 m0, s11
	ds_read_b128 v[224:227], v172
	ds_read_b128 v[228:231], v172 offset:1024
	ds_read_b128 v[232:235], v172 offset:2048
	ds_read_b128 v[236:239], v172 offset:3072
	global_load_lds_dwordx4 v[240:241], off
	v_lshl_add_u64 v[240:241], v[242:243], 0, s[22:23]
	s_add_i32 m0, s11, 0x2000
	s_nop 0
	global_load_lds_dwordx4 v[240:241], off
	s_barrier
; #define PG8_STAGE(bufoff, gbase, voff) do { _Pragma("unroll") for (int _i = 0; _i < 2; ++_i) \
;         __builtin_amdgcn_global_load_lds((const unsigned*)((const char*)(gbase) + (voff)[_i]), (LAS unsigned*)(lds + (bufoff) + ldsw + _i * 8192), 16, 0, 0); } while (0)
; #define PG8_LDA(dst, b, h) do { _Pragma("unroll") for (int m = 0; m < 4; ++m) _Pragma("unroll") for (int k = 0; k < 2; ++k) dst[m][k] = *(const LAS bf16x8*)(lds + PG8_SA(b, h) + aoff + m * 2048 + k * 1024); } while (0)
; #define PG8_MMA(ai, bj, At, Bt) do { __builtin_amdgcn_s_setprio(1); _Pragma("unroll") for (int m = 0; m < 4; ++m) _Pragma("unroll") for (int n = 0; n < 2; ++n) _Pragma("unroll") for (int k = 0; k < 2; ++k) \
;         acc[ai][bj][m][n] = __builtin_amdgcn_mfma_f32_16x16x32_bf16(Bt[n][k], At[m][k], acc[ai][bj][m][n], 0, 0, 0); __builtin_amdgcn_s_setprio(0); } while (0)
; #define PG8_WAIT_V(n) asm volatile("s_waitcnt vmcnt(" #n ")" ::: "memory")
; #define PG8_WAIT_L(n) asm volatile("s_waitcnt lgkmcnt(" #n ")" ::: "memory")
; #define PG8_BAR __builtin_amdgcn_s_barrier()
; #define PG8_SCHED __builtin_amdgcn_sched_barrier(0)
; template <class Epi, class Sched, bool ATILE = false>
; __device__ __forceinline__ void gemm_phase(LAS unsigned char* lds, const Gemm g, const Sched& S, const Epi& E) {
;     ...
;             PG8_BAR; PG8_WAIT_L(0); PG8_MMA(0, 1, At, B1); PG8_BAR;
;             PG8_LDA(At, 1, 1); PG8_STAGE(PG8_SA(1, 0), a3, voffA);
;             PG8_BAR; PG8_WAIT_L(0); PG8_MMA(1, 0, At, B0); PG8_BAR; PG8_SCHED;
;             PG8_STAGE(PG8_SB(1, 1), b3 + hstepB, voffB);
;             PG8_WAIT_V(6); PG8_BAR; PG8_MMA(1, 1, At, B1); PG8_BAR;
	s_waitcnt lgkmcnt(0)
	s_setprio 1
	s_waitcnt lgkmcnt(0)
	v_mfma_f32_16x16x32_bf16 v[124:127], v[224:227], v[192:195], v[124:127]
	v_mfma_f32_16x16x32_bf16 v[116:119], v[232:235], v[192:195], v[116:119]
	v_mfma_f32_16x16x32_bf16 v[108:111], v[224:227], v[200:203], v[108:111]
	v_mfma_f32_16x16x32_bf16 v[100:103], v[232:235], v[200:203], v[100:103]
	v_mfma_f32_16x16x32_bf16 v[92:95], v[224:227], v[208:211], v[92:95]
	v_mfma_f32_16x16x32_bf16 v[84:87], v[232:235], v[208:211], v[84:87]
	v_mfma_f32_16x16x32_bf16 v[76:79], v[224:227], v[216:219], v[76:79]
	v_mfma_f32_16x16x32_bf16 v[68:71], v[232:235], v[216:219], v[68:71]
	v_mfma_f32_16x16x32_bf16 v[124:127], v[228:231], v[196:199], v[124:127]
	v_mfma_f32_16x16x32_bf16 v[116:119], v[236:239], v[196:199], v[116:119]
	v_mfma_f32_16x16x32_bf16 v[108:111], v[228:231], v[204:207], v[108:111]
	v_mfma_f32_16x16x32_bf16 v[100:103], v[236:239], v[204:207], v[100:103]
	v_mfma_f32_16x16x32_bf16 v[92:95], v[228:231], v[212:215], v[92:95]
	v_mfma_f32_16x16x32_bf16 v[84:87], v[236:239], v[212:215], v[84:87]
	v_mfma_f32_16x16x32_bf16 v[76:79], v[228:231], v[220:223], v[76:79]
	v_mfma_f32_16x16x32_bf16 v[68:71], v[236:239], v[220:223], v[68:71]
	s_setprio 0
	s_barrier
	s_mov_b32 m0, s43
	v_lshl_add_u64 v[240:241], v[244:245], 0, s[22:23]
	ds_read_b128 v[192:195], v159 offset:49152
	ds_read_b128 v[196:199], v159 offset:50176
	ds_read_b128 v[200:203], v159 offset:51200
	ds_read_b128 v[204:207], v159 offset:52224
	ds_read_b128 v[208:211], v159 offset:53248
	ds_read_b128 v[212:215], v159 offset:54272
	ds_read_b128 v[216:219], v159 offset:55296
	ds_read_b128 v[220:223], v159 offset:56320
	global_load_lds_dwordx4 v[240:241], off
	v_lshl_add_u64 v[240:241], v[246:247], 0, s[22:23]
	s_mov_b32 m0, s44
	s_nop 0
	global_load_lds_dwordx4 v[240:241], off
	s_barrier
	s_waitcnt lgkmcnt(0)
	s_setprio 1
	s_waitcnt lgkmcnt(0)
	v_mfma_f32_16x16x32_bf16 v[56:59], v[176:179], v[192:195], v[56:59]
	v_mfma_f32_16x16x32_bf16 v[48:51], v[184:187], v[192:195], v[48:51]
	v_mfma_f32_16x16x32_bf16 v[40:43], v[176:179], v[200:203], v[40:43]
	v_mfma_f32_16x16x32_bf16 v[32:35], v[184:187], v[200:203], v[32:35]
	v_mfma_f32_16x16x32_bf16 v[24:27], v[176:179], v[208:211], v[24:27]
	v_mfma_f32_16x16x32_bf16 v[16:19], v[184:187], v[208:211], v[16:19]
	v_mfma_f32_16x16x32_bf16 v[8:11], v[176:179], v[216:219], v[8:11]
	v_mfma_f32_16x16x32_bf16 v[4:7], v[184:187], v[216:219], v[4:7]
	v_mfma_f32_16x16x32_bf16 v[56:59], v[180:183], v[196:199], v[56:59]
	v_mfma_f32_16x16x32_bf16 v[48:51], v[188:191], v[196:199], v[48:51]
	v_mfma_f32_16x16x32_bf16 v[40:43], v[180:183], v[204:207], v[40:43]
	v_mfma_f32_16x16x32_bf16 v[32:35], v[188:191], v[204:207], v[32:35]
	v_mfma_f32_16x16x32_bf16 v[24:27], v[180:183], v[212:215], v[24:27]
	v_mfma_f32_16x16x32_bf16 v[16:19], v[188:191], v[212:215], v[16:19]
	v_mfma_f32_16x16x32_bf16 v[8:11], v[180:183], v[220:223], v[8:11]
	v_mfma_f32_16x16x32_bf16 v[4:7], v[188:191], v[220:223], v[4:7]
	s_setprio 0
	s_barrier
	s_add_u32 s8, s8, 0x80080
	s_addc_u32 s9, s9, 0
	s_add_i32 s10, s10, s36
	v_lshl_add_u64 v[176:177], s[8:9], 0, v[130:131]
	s_mov_b32 m0, s10
	s_nop 0
	global_load_lds_dwordx4 v[176:177], off
	v_lshl_add_u64 v[176:177], s[8:9], 0, v[134:135]
	s_add_i32 m0, s10, 0x2000
	s_nop 0
	global_load_lds_dwordx4 v[176:177], off
	s_waitcnt vmcnt(6)
	s_barrier
	s_setprio 1
	v_mfma_f32_16x16x32_bf16 v[60:63], v[224:227], v[192:195], v[60:63]
	v_mfma_f32_16x16x32_bf16 v[52:55], v[232:235], v[192:195], v[52:55]
	v_mfma_f32_16x16x32_bf16 v[44:47], v[224:227], v[200:203], v[44:47]
	v_mfma_f32_16x16x32_bf16 v[36:39], v[232:235], v[200:203], v[36:39]
	v_mfma_f32_16x16x32_bf16 v[28:31], v[224:227], v[208:211], v[28:31]
	v_mfma_f32_16x16x32_bf16 v[20:23], v[232:235], v[208:211], v[20:23]
	v_mfma_f32_16x16x32_bf16 v[12:15], v[224:227], v[216:219], v[12:15]
	v_mfma_f32_16x16x32_bf16 v[0:3], v[232:235], v[216:219], v[0:3]
	v_mfma_f32_16x16x32_bf16 v[60:63], v[228:231], v[196:199], v[60:63]
	v_mfma_f32_16x16x32_bf16 v[52:55], v[236:239], v[196:199], v[52:55]
	v_mfma_f32_16x16x32_bf16 v[44:47], v[228:231], v[204:207], v[44:47]
	v_mfma_f32_16x16x32_bf16 v[36:39], v[236:239], v[204:207], v[36:39]
	v_mfma_f32_16x16x32_bf16 v[28:31], v[228:231], v[212:215], v[28:31]
	v_mfma_f32_16x16x32_bf16 v[20:23], v[236:239], v[212:215], v[20:23]
	v_mfma_f32_16x16x32_bf16 v[12:15], v[228:231], v[220:223], v[12:15]
	v_mfma_f32_16x16x32_bf16 v[0:3], v[236:239], v[220:223], v[0:3]
	s_setprio 0
	s_barrier
	s_add_u32 s6, s6, 0x100
	s_addc_u32 s7, s7, 0
	s_add_u32 s25, s25, 0x100
	s_addc_u32 s27, s27, 0
	s_cmp_ge_i32 s34, s12
	s_mov_b32 s8, s34
	s_cbranch_scc0 .LBB0_1812
	s_branch .LBB0_1803

; #define PG8_STAGE(bufoff, gbase, voff) do { _Pragma("unroll") for (int _i = 0; _i < 2; ++_i) \
;         __builtin_amdgcn_global_load_lds((const unsigned*)((const char*)(gbase) + (voff)[_i]), (LAS unsigned*)(lds + (bufoff) + ldsw + _i * 8192), 16, 0, 0); } while (0)
; #define PG8_LDA(dst, b, h) do { _Pragma("unroll") for (int m = 0; m < 4; ++m) _Pragma("unroll") for (int k = 0; k < 2; ++k) dst[m][k] = *(const LAS bf16x8*)(lds + PG8_SA(b, h) + aoff + m * 2048 + k * 1024); } while (0)
; #define PG8_LDB(dst, b, h) do { _Pragma("unroll") for (int n = 0; n < 2; ++n) _Pragma("unroll") for (int k = 0; k < 2; ++k) dst[n][k] = *(const LAS bf16x8*)(lds + PG8_SB(b, h) + boff + n * 2048 + k * 1024); } while (0)
; #define PG8_MMA(ai, bj, At, Bt) do { __builtin_amdgcn_s_setprio(1); _Pragma("unroll") for (int m = 0; m < 4; ++m) _Pragma("unroll") for (int n = 0; n < 2; ++n) _Pragma("unroll") for (int k = 0; k < 2; ++k) \
;         acc[ai][bj][m][n] = __builtin_amdgcn_mfma_f32_16x16x32_bf16(Bt[n][k], At[m][k], acc[ai][bj][m][n], 0, 0, 0); __builtin_amdgcn_s_setprio(0); } while (0)
; #define PG8_WAIT_L(n) asm volatile("s_waitcnt lgkmcnt(" #n ")" ::: "memory")
; #define PG8_BAR __builtin_amdgcn_s_barrier()
; #define PG8_SCHED __builtin_amdgcn_sched_barrier(0)
; template <class Epi, class Sched, bool ATILE = false>
; __device__ __forceinline__ void gemm_phase(LAS unsigned char* lds, const Gemm g, const Sched& S, const Epi& E) {
;     ...
;             const bool last = (t == nt - 2);
;             const char* a1 = cA + (size_t)(t + 1) * kstepA;
;             const char* a2 = last ? nA : cA + (size_t)(t + 2) * kstepA; const char* b2 = last ? nB : cB + (size_t)(t + 2) * kstep;
;             const char* a3 = a2 + kstepA; const char* b3 = b2 + kstep;
;             PG8_LDB(B0, 0, 0); PG8_SCHED; PG8_LDA(At, 0, 0); PG8_STAGE(PG8_SA(1, 1), a1 + hstepA, voffA);
;             PG8_WAIT_L(8); PG8_BAR; PG8_WAIT_L(0); PG8_MMA(0, 0, At, B0); PG8_BAR; PG8_SCHED;
;             PG8_LDB(B1, 0, 1); PG8_STAGE(PG8_SB(0, 0), b2, voffB);
;             PG8_BAR; PG8_WAIT_L(0); PG8_MMA(0, 1, At, B1); PG8_BAR;
;             PG8_LDA(At, 0, 1); PG8_STAGE(PG8_SA(0, 0), a2, voffA);
;             PG8_BAR; PG8_WAIT_L(0); PG8_MMA(1, 0, At, B0); PG8_BAR; PG8_SCHED;
.LBB0_1898:
	ds_read_b128 v[20:23], v180
	ds_read_b128 v[28:31], v180 offset:1024
	ds_read_b128 v[174:177], v180 offset:2048
	ds_read_b128 v[184:187], v180 offset:3072
	s_add_i32 s58, s26, 2
	s_add_u32 s27, s24, 0x4000
	s_addc_u32 s28, s25, 0
	s_cmp_eq_u32 s17, s26
	s_cselect_b32 s30, s20, s27
	s_cselect_b32 s31, s21, s28
	s_cselect_b32 s26, s22, s56
	s_cselect_b32 s27, s23, s57
	s_add_u32 s28, s30, 0x8000
	s_addc_u32 s29, s31, 0
	v_lshl_add_u64 v[178:179], s[24:25], 0, v[168:169]
	s_add_i32 m0, s34, 0xc000
	ds_read_b128 v[188:191], v181
	ds_read_b128 v[192:195], v181 offset:1024
	ds_read_b128 v[196:199], v181 offset:2048
	ds_read_b128 v[200:203], v181 offset:3072
	ds_read_b128 v[204:207], v181 offset:4096
	ds_read_b128 v[208:211], v181 offset:5120
	ds_read_b128 v[212:215], v181 offset:6144
	ds_read_b128 v[216:219], v181 offset:7168
	global_load_lds_dwordx4 v[178:179], off
	v_lshl_add_u64 v[178:179], s[24:25], 0, v[170:171]
	s_add_i32 m0, s34, 0xe000
	s_nop 0
	global_load_lds_dwordx4 v[178:179], off
	s_waitcnt lgkmcnt(8)
	s_barrier
	s_waitcnt lgkmcnt(0)
	s_setprio 1
	s_waitcnt lgkmcnt(0)
	v_mfma_f32_16x16x32_bf16 v[0:3], v[20:23], v[188:191], v[0:3]
	v_mfma_f32_16x16x32_bf16 v[4:7], v[174:177], v[188:191], v[4:7]
	v_mfma_f32_16x16x32_bf16 v[44:47], v[20:23], v[196:199], v[44:47]
	v_mfma_f32_16x16x32_bf16 v[36:39], v[174:177], v[196:199], v[36:39]
	v_mfma_f32_16x16x32_bf16 v[52:55], v[20:23], v[204:207], v[52:55]
	v_mfma_f32_16x16x32_bf16 v[48:51], v[174:177], v[204:207], v[48:51]
	v_mfma_f32_16x16x32_bf16 v[92:95], v[20:23], v[212:215], v[92:95]
	v_mfma_f32_16x16x32_bf16 v[84:87], v[174:177], v[212:215], v[84:87]
	v_mfma_f32_16x16x32_bf16 v[0:3], v[28:31], v[192:195], v[0:3]
	v_mfma_f32_16x16x32_bf16 v[4:7], v[184:187], v[192:195], v[4:7]
	v_mfma_f32_16x16x32_bf16 v[44:47], v[28:31], v[200:203], v[44:47]
	v_mfma_f32_16x16x32_bf16 v[36:39], v[184:187], v[200:203], v[36:39]
	v_mfma_f32_16x16x32_bf16 v[52:55], v[28:31], v[208:211], v[52:55]
	v_mfma_f32_16x16x32_bf16 v[48:51], v[184:187], v[208:211], v[48:51]
	v_mfma_f32_16x16x32_bf16 v[92:95], v[28:31], v[216:219], v[92:95]
	v_mfma_f32_16x16x32_bf16 v[84:87], v[184:187], v[216:219], v[84:87]
	s_setprio 0
	s_barrier
	s_add_i32 s59, s44, s33
	v_lshl_add_u64 v[178:179], s[26:27], 0, v[138:139]
	s_mov_b32 m0, s59
	ds_read_b128 v[220:223], v182
	ds_read_b128 v[224:227], v182 offset:1024
	ds_read_b128 v[228:231], v182 offset:2048
	ds_read_b128 v[232:235], v182 offset:3072
	global_load_lds_dwordx4 v[178:179], off
	v_lshl_add_u64 v[236:237], s[26:27], 0, v[142:143]
	s_add_i32 m0, s59, 0x2000
	s_nop 0
	global_load_lds_dwordx4 v[236:237], off
	s_barrier
	s_waitcnt lgkmcnt(0)
	s_setprio 1
	s_waitcnt lgkmcnt(0)
	v_mfma_f32_16x16x32_bf16 v[12:15], v[220:223], v[188:191], v[12:15]
	v_mfma_f32_16x16x32_bf16 v[8:11], v[228:231], v[188:191], v[8:11]
	v_mfma_f32_16x16x32_bf16 v[24:27], v[220:223], v[196:199], v[24:27]
	v_mfma_f32_16x16x32_bf16 v[16:19], v[228:231], v[196:199], v[16:19]
	v_mfma_f32_16x16x32_bf16 v[40:43], v[220:223], v[204:207], v[40:43]
	v_mfma_f32_16x16x32_bf16 v[32:35], v[228:231], v[204:207], v[32:35]
	v_mfma_f32_16x16x32_bf16 v[56:59], v[220:223], v[212:215], v[56:59]
	v_mfma_f32_16x16x32_bf16 v[60:63], v[228:231], v[212:215], v[60:63]
	v_mfma_f32_16x16x32_bf16 v[12:15], v[224:227], v[192:195], v[12:15]
	v_mfma_f32_16x16x32_bf16 v[8:11], v[232:235], v[192:195], v[8:11]
	v_mfma_f32_16x16x32_bf16 v[24:27], v[224:227], v[200:203], v[24:27]
	v_mfma_f32_16x16x32_bf16 v[16:19], v[232:235], v[200:203], v[16:19]
	v_mfma_f32_16x16x32_bf16 v[40:43], v[224:227], v[208:211], v[40:43]
	v_mfma_f32_16x16x32_bf16 v[32:35], v[232:235], v[208:211], v[32:35]
	v_mfma_f32_16x16x32_bf16 v[56:59], v[224:227], v[216:219], v[56:59]
	v_mfma_f32_16x16x32_bf16 v[60:63], v[232:235], v[216:219], v[60:63]
	s_setprio 0
	s_barrier
	s_mov_b32 m0, s34
	v_lshl_add_u64 v[238:239], s[30:31], 0, v[136:137]
	ds_read_b128 v[188:191], v181 offset:16384
	ds_read_b128 v[192:195], v181 offset:17408
	ds_read_b128 v[196:199], v181 offset:18432
	ds_read_b128 v[200:203], v181 offset:19456
	ds_read_b128 v[204:207], v181 offset:20480
	ds_read_b128 v[208:211], v181 offset:21504
	ds_read_b128 v[212:215], v181 offset:22528
	ds_read_b128 v[216:219], v181 offset:23552
	global_load_lds_dwordx4 v[238:239], off
	v_lshl_add_u64 v[238:239], s[30:31], 0, v[140:141]
	s_mov_b32 m0, s35
	s_nop 0
	global_load_lds_dwordx4 v[238:239], off
	s_barrier
	s_waitcnt lgkmcnt(0)
	s_setprio 1
	s_waitcnt lgkmcnt(0)
	v_mfma_f32_16x16x32_bf16 v[64:67], v[20:23], v[188:191], v[64:67]
	v_mfma_f32_16x16x32_bf16 v[68:71], v[174:177], v[188:191], v[68:71]
	v_mfma_f32_16x16x32_bf16 v[108:111], v[20:23], v[196:199], v[108:111]
	v_mfma_f32_16x16x32_bf16 v[100:103], v[174:177], v[196:199], v[100:103]
	v_mfma_f32_16x16x32_bf16 v[116:119], v[20:23], v[204:207], v[116:119]
	v_mfma_f32_16x16x32_bf16 v[112:115], v[174:177], v[204:207], v[112:115]
	v_mfma_f32_16x16x32_bf16 v[20:23], v[20:23], v[212:215], v[132:135]
	v_mfma_f32_16x16x32_bf16 v[64:67], v[28:31], v[192:195], v[64:67]
	v_mfma_f32_16x16x32_bf16 v[68:71], v[184:187], v[192:195], v[68:71]
	v_mfma_f32_16x16x32_bf16 v[108:111], v[28:31], v[200:203], v[108:111]
	v_mfma_f32_16x16x32_bf16 v[100:103], v[184:187], v[200:203], v[100:103]
	v_mfma_f32_16x16x32_bf16 v[116:119], v[28:31], v[208:211], v[116:119]
	v_mfma_f32_16x16x32_bf16 v[112:115], v[184:187], v[208:211], v[112:115]
	v_mfma_f32_16x16x32_bf16 v[20:23], v[28:31], v[216:219], v[20:23]
	v_mfma_f32_16x16x32_bf16 v[28:31], v[174:177], v[212:215], v[128:131]
	v_mfma_f32_16x16x32_bf16 v[28:31], v[184:187], v[216:219], v[28:31]
	s_setprio 0
	s_barrier
; #define PG8_STAGE(bufoff, gbase, voff) do { _Pragma("unroll") for (int _i = 0; _i < 2; ++_i) \
;         __builtin_amdgcn_global_load_lds((const unsigned*)((const char*)(gbase) + (voff)[_i]), (LAS unsigned*)(lds + (bufoff) + ldsw + _i * 8192), 16, 0, 0); } while (0)
; #define PG8_LDA(dst, b, h) do { _Pragma("unroll") for (int m = 0; m < 4; ++m) _Pragma("unroll") for (int k = 0; k < 2; ++k) dst[m][k] = *(const LAS bf16x8*)(lds + PG8_SA(b, h) + aoff + m * 2048 + k * 1024); } while (0)
; #define PG8_LDB(dst, b, h) do { _Pragma("unroll") for (int n = 0; n < 2; ++n) _Pragma("unroll") for (int k = 0; k < 2; ++k) dst[n][k] = *(const LAS bf16x8*)(lds + PG8_SB(b, h) + boff + n * 2048 + k * 1024); } while (0)
; #define PG8_MMA(ai, bj, At, Bt) do { __builtin_amdgcn_s_setprio(1); _Pragma("unroll") for (int m = 0; m < 4; ++m) _Pragma("unroll") for (int n = 0; n < 2; ++n) _Pragma("unroll") for (int k = 0; k < 2; ++k) \
;         acc[ai][bj][m][n] = __builtin_amdgcn_mfma_f32_16x16x32_bf16(Bt[n][k], At[m][k], acc[ai][bj][m][n], 0, 0, 0); __builtin_amdgcn_s_setprio(0); } while (0)
; #define PG8_WAIT_V(n) asm volatile("s_waitcnt vmcnt(" #n ")" ::: "memory")
; #define PG8_WAIT_L(n) asm volatile("s_waitcnt lgkmcnt(" #n ")" ::: "memory")
; #define PG8_BAR __builtin_amdgcn_s_barrier()
; #define PG8_SCHED __builtin_amdgcn_sched_barrier(0)
; template <class Epi, class Sched, bool ATILE = false>
; __device__ __forceinline__ void gemm_phase(LAS unsigned char* lds, const Gemm g, const Sched& S, const Epi& E) {
;     ...
;             PG8_STAGE(PG8_SB(0, 1), b2 + hstepB, voffB);
;             PG8_WAIT_V(6); PG8_BAR; PG8_MMA(1, 1, At, B1); PG8_BAR;
;             PG8_LDB(B0, 1, 0); PG8_SCHED; PG8_LDA(At, 1, 0); PG8_STAGE(PG8_SA(0, 1), a2 + hstepA, voffA);
;             PG8_WAIT_L(8); PG8_BAR; PG8_WAIT_L(0); PG8_MMA(0, 0, At, B0); PG8_BAR; PG8_SCHED;
;             PG8_LDB(B1, 1, 1); PG8_STAGE(PG8_SB(1, 0), b3, voffB);
;             PG8_BAR; PG8_WAIT_L(0); PG8_MMA(0, 1, At, B1); PG8_BAR;
;             PG8_LDA(At, 1, 1); PG8_STAGE(PG8_SA(1, 0), a3, voffA);
	s_add_u32 s60, s26, 0x158000
	s_addc_u32 s61, s27, 0
	s_add_i32 s59, s45, s33
	v_lshl_add_u64 v[128:129], s[60:61], 0, v[138:139]
	s_mov_b32 m0, s59
	s_nop 0
	global_load_lds_dwordx4 v[128:129], off
	v_lshl_add_u64 v[128:129], s[60:61], 0, v[142:143]
	s_add_i32 m0, s59, 0x2000
	s_nop 0
	global_load_lds_dwordx4 v[128:129], off
	s_waitcnt vmcnt(6)
	s_barrier
	s_setprio 1
	v_mfma_f32_16x16x32_bf16 v[76:79], v[220:223], v[188:191], v[76:79]
	v_mfma_f32_16x16x32_bf16 v[72:75], v[228:231], v[188:191], v[72:75]
	v_mfma_f32_16x16x32_bf16 v[88:91], v[220:223], v[196:199], v[88:91]
	v_mfma_f32_16x16x32_bf16 v[80:83], v[228:231], v[196:199], v[80:83]
	v_mfma_f32_16x16x32_bf16 v[104:107], v[220:223], v[204:207], v[104:107]
	v_mfma_f32_16x16x32_bf16 v[96:99], v[228:231], v[204:207], v[96:99]
	v_mfma_f32_16x16x32_bf16 v[120:123], v[220:223], v[212:215], v[120:123]
	v_mfma_f32_16x16x32_bf16 v[124:127], v[228:231], v[212:215], v[124:127]
	v_mfma_f32_16x16x32_bf16 v[76:79], v[224:227], v[192:195], v[76:79]
	v_mfma_f32_16x16x32_bf16 v[72:75], v[232:235], v[192:195], v[72:75]
	v_mfma_f32_16x16x32_bf16 v[88:91], v[224:227], v[200:203], v[88:91]
	v_mfma_f32_16x16x32_bf16 v[80:83], v[232:235], v[200:203], v[80:83]
	v_mfma_f32_16x16x32_bf16 v[104:107], v[224:227], v[208:211], v[104:107]
	v_mfma_f32_16x16x32_bf16 v[96:99], v[232:235], v[208:211], v[96:99]
	v_mfma_f32_16x16x32_bf16 v[120:123], v[224:227], v[216:219], v[120:123]
	v_mfma_f32_16x16x32_bf16 v[124:127], v[232:235], v[216:219], v[124:127]
	s_setprio 0
	s_barrier
	s_add_i32 s59, 0, 0x18000
	v_add_u32_e32 v183, s59, v157
	ds_read_b128 v[128:131], v183
	ds_read_b128 v[132:135], v183 offset:1024
	ds_read_b128 v[174:177], v183 offset:2048
	ds_read_b128 v[184:187], v183 offset:3072
	s_add_u32 s30, s30, 0x4000
	s_addc_u32 s31, s31, 0
	s_mov_b32 m0, s36
	v_lshl_add_u64 v[220:221], s[30:31], 0, v[136:137]
	ds_read_b128 v[188:191], v181 offset:32768
	ds_read_b128 v[192:195], v181 offset:33792
	ds_read_b128 v[196:199], v181 offset:34816
	ds_read_b128 v[200:203], v181 offset:35840
	ds_read_b128 v[204:207], v181 offset:36864
	ds_read_b128 v[208:211], v181 offset:37888
	ds_read_b128 v[212:215], v181 offset:38912
	ds_read_b128 v[216:219], v181 offset:39936
	global_load_lds_dwordx4 v[220:221], off
	v_lshl_add_u64 v[220:221], s[30:31], 0, v[140:141]
	s_mov_b32 m0, s37
	s_nop 0
	global_load_lds_dwordx4 v[220:221], off
	s_waitcnt lgkmcnt(8)
	s_barrier
	s_waitcnt lgkmcnt(0)
	s_setprio 1
	s_waitcnt lgkmcnt(0)
	v_mfma_f32_16x16x32_bf16 v[0:3], v[128:131], v[188:191], v[0:3]
	v_mfma_f32_16x16x32_bf16 v[4:7], v[174:177], v[188:191], v[4:7]
	v_mfma_f32_16x16x32_bf16 v[44:47], v[128:131], v[196:199], v[44:47]
	v_mfma_f32_16x16x32_bf16 v[36:39], v[174:177], v[196:199], v[36:39]
	v_mfma_f32_16x16x32_bf16 v[52:55], v[128:131], v[204:207], v[52:55]
	v_mfma_f32_16x16x32_bf16 v[48:51], v[174:177], v[204:207], v[48:51]
	v_mfma_f32_16x16x32_bf16 v[92:95], v[128:131], v[212:215], v[92:95]
	v_mfma_f32_16x16x32_bf16 v[84:87], v[174:177], v[212:215], v[84:87]
	v_mfma_f32_16x16x32_bf16 v[0:3], v[132:135], v[192:195], v[0:3]
	v_mfma_f32_16x16x32_bf16 v[4:7], v[184:187], v[192:195], v[4:7]
	v_mfma_f32_16x16x32_bf16 v[44:47], v[132:135], v[200:203], v[44:47]
	v_mfma_f32_16x16x32_bf16 v[36:39], v[184:187], v[200:203], v[36:39]
	v_mfma_f32_16x16x32_bf16 v[52:55], v[132:135], v[208:211], v[52:55]
	v_mfma_f32_16x16x32_bf16 v[48:51], v[184:187], v[208:211], v[48:51]
	v_mfma_f32_16x16x32_bf16 v[92:95], v[132:135], v[216:219], v[92:95]
	v_mfma_f32_16x16x32_bf16 v[84:87], v[184:187], v[216:219], v[84:87]
	s_setprio 0
	s_barrier
	s_add_i32 s30, 0, 0x1c000
	s_add_i32 s31, s59, s33
	v_add_u32_e32 v183, s30, v157
	v_lshl_add_u64 v[178:179], v[178:179], 0, s[4:5]
	s_mov_b32 m0, s31
	ds_read_b128 v[220:223], v183
	ds_read_b128 v[224:227], v183 offset:1024
	ds_read_b128 v[228:231], v183 offset:2048
	ds_read_b128 v[232:235], v183 offset:3072
	global_load_lds_dwordx4 v[178:179], off
	v_lshl_add_u64 v[178:179], v[236:237], 0, s[4:5]
	s_add_i32 m0, s31, 0x2000
	s_nop 0
	global_load_lds_dwordx4 v[178:179], off
	s_barrier
	s_waitcnt lgkmcnt(0)
	s_setprio 1
	s_waitcnt lgkmcnt(0)
	v_mfma_f32_16x16x32_bf16 v[12:15], v[220:223], v[188:191], v[12:15]
	v_mfma_f32_16x16x32_bf16 v[8:11], v[228:231], v[188:191], v[8:11]
	v_mfma_f32_16x16x32_bf16 v[24:27], v[220:223], v[196:199], v[24:27]
	v_mfma_f32_16x16x32_bf16 v[16:19], v[228:231], v[196:199], v[16:19]
	v_mfma_f32_16x16x32_bf16 v[40:43], v[220:223], v[204:207], v[40:43]
	v_mfma_f32_16x16x32_bf16 v[32:35], v[228:231], v[204:207], v[32:35]
	v_mfma_f32_16x16x32_bf16 v[56:59], v[220:223], v[212:215], v[56:59]
	v_mfma_f32_16x16x32_bf16 v[60:63], v[228:231], v[212:215], v[60:63]
	v_mfma_f32_16x16x32_bf16 v[12:15], v[224:227], v[192:195], v[12:15]
	v_mfma_f32_16x16x32_bf16 v[8:11], v[232:235], v[192:195], v[8:11]
	v_mfma_f32_16x16x32_bf16 v[24:27], v[224:227], v[200:203], v[24:27]
	v_mfma_f32_16x16x32_bf16 v[16:19], v[232:235], v[200:203], v[16:19]
	v_mfma_f32_16x16x32_bf16 v[40:43], v[224:227], v[208:211], v[40:43]
	v_mfma_f32_16x16x32_bf16 v[32:35], v[232:235], v[208:211], v[32:35]
	v_mfma_f32_16x16x32_bf16 v[56:59], v[224:227], v[216:219], v[56:59]
	v_mfma_f32_16x16x32_bf16 v[60:63], v[232:235], v[216:219], v[60:63]
	s_setprio 0
	s_barrier
	s_mov_b32 m0, s39
	v_lshl_add_u64 v[178:179], s[28:29], 0, v[136:137]
	ds_read_b128 v[188:191], v181 offset:49152
	ds_read_b128 v[192:195], v181 offset:50176
	ds_read_b128 v[196:199], v181 offset:51200
	ds_read_b128 v[200:203], v181 offset:52224
	ds_read_b128 v[204:207], v181 offset:53248
	ds_read_b128 v[208:211], v181 offset:54272
	ds_read_b128 v[212:215], v181 offset:55296
	ds_read_b128 v[216:219], v181 offset:56320
	global_load_lds_dwordx4 v[178:179], off
	v_lshl_add_u64 v[178:179], s[28:29], 0, v[140:141]
	s_mov_b32 m0, s40
	s_nop 0
	global_load_lds_dwordx4 v[178:179], off
	s_barrier
; __device__ __forceinline__ float bflo(unsigned w) { return __uint_as_float(w << 16); }
; __device__ __forceinline__ float bfhi(unsigned w) { return __uint_as_float(w & 0xffff0000u); }
; #define PG8_STAGE(bufoff, gbase, voff) do { _Pragma("unroll") for (int _i = 0; _i < 2; ++_i) \
;         __builtin_amdgcn_global_load_lds((const unsigned*)((const char*)(gbase) + (voff)[_i]), (LAS unsigned*)(lds + (bufoff) + ldsw + _i * 8192), 16, 0, 0); } while (0)
; #define PG8_MMA(ai, bj, At, Bt) do { __builtin_amdgcn_s_setprio(1); _Pragma("unroll") for (int m = 0; m < 4; ++m) _Pragma("unroll") for (int n = 0; n < 2; ++n) _Pragma("unroll") for (int k = 0; k < 2; ++k) \
;         acc[ai][bj][m][n] = __builtin_amdgcn_mfma_f32_16x16x32_bf16(Bt[n][k], At[m][k], acc[ai][bj][m][n], 0, 0, 0); __builtin_amdgcn_s_setprio(0); } while (0)
; #define PG8_WAIT_V(n) asm volatile("s_waitcnt vmcnt(" #n ")" ::: "memory")
; #define PG8_WAIT_L(n) asm volatile("s_waitcnt lgkmcnt(" #n ")" ::: "memory")
; #define PG8_BAR __builtin_amdgcn_s_barrier()
; #define PG8_SCHED __builtin_amdgcn_sched_barrier(0)
; template <class Epi, class Sched, bool ATILE = false>
; __device__ __forceinline__ void gemm_phase(LAS unsigned char* lds, const Gemm g, const Sched& S, const Epi& E) {
;     ...
;             PG8_BAR; PG8_WAIT_L(0); PG8_MMA(1, 0, At, B0); PG8_BAR; PG8_SCHED;
;             PG8_STAGE(PG8_SB(1, 1), b3 + hstepB, voffB);
;             PG8_WAIT_V(6); PG8_BAR; PG8_MMA(1, 1, At, B1); PG8_BAR;
;     __device__ __forceinline__ void operator()(const f32x4 (&acc)[2][2][4][2], const Unit& u, int wr, int wc, int fr, int fq) const {
;     ...
;                     const f32x4 v0 = (f32x4){bflo(x.x), bfhi(x.x), bflo(x.y), bfhi(x.y)} + alpha * acc[ai][bj][m][0];
;                     const f32x4 v1 = (f32x4){bflo(x.z), bfhi(x.z), bflo(x.w), bfhi(x.w)} + alpha * acc[ai][bj][m][1];
	s_waitcnt lgkmcnt(0)
	s_setprio 1
	s_waitcnt lgkmcnt(0)
	v_mfma_f32_16x16x32_bf16 v[64:67], v[128:131], v[188:191], v[64:67]
	v_mfma_f32_16x16x32_bf16 v[108:111], v[128:131], v[196:199], v[108:111]
	v_mfma_f32_16x16x32_bf16 v[116:119], v[128:131], v[204:207], v[116:119]
	v_mfma_f32_16x16x32_bf16 v[20:23], v[128:131], v[212:215], v[20:23]
	v_mfma_f32_16x16x32_bf16 v[64:67], v[132:135], v[192:195], v[64:67]
	v_mfma_f32_16x16x32_bf16 v[68:71], v[174:177], v[188:191], v[68:71]
	v_mfma_f32_16x16x32_bf16 v[108:111], v[132:135], v[200:203], v[108:111]
	v_mfma_f32_16x16x32_bf16 v[100:103], v[174:177], v[196:199], v[100:103]
	v_mfma_f32_16x16x32_bf16 v[116:119], v[132:135], v[208:211], v[116:119]
	v_mfma_f32_16x16x32_bf16 v[112:115], v[174:177], v[204:207], v[112:115]
	v_mfma_f32_16x16x32_bf16 v[132:135], v[132:135], v[216:219], v[20:23]
	v_mfma_f32_16x16x32_bf16 v[20:23], v[174:177], v[212:215], v[28:31]
	v_mfma_f32_16x16x32_bf16 v[68:71], v[184:187], v[192:195], v[68:71]
	v_mfma_f32_16x16x32_bf16 v[100:103], v[184:187], v[200:203], v[100:103]
	v_mfma_f32_16x16x32_bf16 v[112:115], v[184:187], v[208:211], v[112:115]
	v_mfma_f32_16x16x32_bf16 v[128:131], v[184:187], v[216:219], v[20:23]
	s_setprio 0
	s_barrier
	s_add_u32 s26, s26, 0x158080
	s_addc_u32 s27, s27, 0
	s_add_i32 s28, s30, s33
	v_lshl_add_u64 v[20:21], s[26:27], 0, v[138:139]
	s_mov_b32 m0, s28
	s_nop 0
	global_load_lds_dwordx4 v[20:21], off
	v_lshl_add_u64 v[20:21], s[26:27], 0, v[142:143]
	s_add_i32 m0, s28, 0x2000
	s_nop 0
	global_load_lds_dwordx4 v[20:21], off
	s_waitcnt vmcnt(6)
	s_barrier
	s_setprio 1
	v_mfma_f32_16x16x32_bf16 v[20:23], v[220:223], v[188:191], v[76:79]
	v_mfma_f32_16x16x32_bf16 v[76:79], v[224:227], v[192:195], v[20:23]
	v_mfma_f32_16x16x32_bf16 v[20:23], v[228:231], v[188:191], v[72:75]
	v_mfma_f32_16x16x32_bf16 v[72:75], v[232:235], v[192:195], v[20:23]
	v_mfma_f32_16x16x32_bf16 v[20:23], v[220:223], v[196:199], v[88:91]
	v_mfma_f32_16x16x32_bf16 v[88:91], v[224:227], v[200:203], v[20:23]
	v_mfma_f32_16x16x32_bf16 v[20:23], v[228:231], v[196:199], v[80:83]
	v_mfma_f32_16x16x32_bf16 v[80:83], v[232:235], v[200:203], v[20:23]
	v_mfma_f32_16x16x32_bf16 v[20:23], v[220:223], v[204:207], v[104:107]
	v_mfma_f32_16x16x32_bf16 v[104:107], v[224:227], v[208:211], v[20:23]
	v_mfma_f32_16x16x32_bf16 v[20:23], v[228:231], v[204:207], v[96:99]
	v_mfma_f32_16x16x32_bf16 v[96:99], v[232:235], v[208:211], v[20:23]
	v_mfma_f32_16x16x32_bf16 v[20:23], v[220:223], v[212:215], v[120:123]
	v_mfma_f32_16x16x32_bf16 v[120:123], v[224:227], v[216:219], v[20:23]
	v_mfma_f32_16x16x32_bf16 v[20:23], v[228:231], v[212:215], v[124:127]
	v_mfma_f32_16x16x32_bf16 v[124:127], v[232:235], v[216:219], v[20:23]
	s_setprio 0
	s_barrier
	s_add_u32 s56, s56, 0x100
	s_addc_u32 s57, s57, 0
	s_add_u32 s24, s24, 0x10000
	s_addc_u32 s25, s25, 0
	s_cmp_ge_i32 s58, s55
	s_mov_b32 s26, s58
	s_cbranch_scc0 .LBB0_1898
	v_pk_mul_f32 v[2:3], v[2:3], 0.5 op_sel_hi:[1,0]
	v_pk_mul_f32 v[0:1], v[0:1], 0.5 op_sel_hi:[1,0]
	v_pk_mul_f32 v[6:7], v[6:7], 0.5 op_sel_hi:[1,0]
	v_pk_mul_f32 v[4:5], v[4:5], 0.5 op_sel_hi:[1,0]
	v_pk_mul_f32 v[22:23], v[14:15], 0.5 op_sel_hi:[1,0]
	v_pk_mul_f32 v[20:21], v[12:13], 0.5 op_sel_hi:[1,0]
	v_pk_mul_f32 v[30:31], v[10:11], 0.5 op_sel_hi:[1,0]
	v_pk_mul_f32 v[28:29], v[8:9], 0.5 op_sel_hi:[1,0]
	v_pk_mul_f32 v[10:11], v[46:47], 0.5 op_sel_hi:[1,0]
	v_pk_mul_f32 v[8:9], v[44:45], 0.5 op_sel_hi:[1,0]
	v_pk_mul_f32 v[14:15], v[38:39], 0.5 op_sel_hi:[1,0]
	v_pk_mul_f32 v[12:13], v[36:37], 0.5 op_sel_hi:[1,0]
	v_pk_mul_f32 v[38:39], v[26:27], 0.5 op_sel_hi:[1,0]
	v_pk_mul_f32 v[36:37], v[24:25], 0.5 op_sel_hi:[1,0]
	v_pk_mul_f32 v[46:47], v[18:19], 0.5 op_sel_hi:[1,0]
	v_pk_mul_f32 v[44:45], v[16:17], 0.5 op_sel_hi:[1,0]
	v_pk_mul_f32 v[18:19], v[54:55], 0.5 op_sel_hi:[1,0]
	v_pk_mul_f32 v[16:17], v[52:53], 0.5 op_sel_hi:[1,0]
	v_pk_mul_f32 v[26:27], v[50:51], 0.5 op_sel_hi:[1,0]
	v_pk_mul_f32 v[24:25], v[48:49], 0.5 op_sel_hi:[1,0]
	v_pk_mul_f32 v[50:51], v[42:43], 0.5 op_sel_hi:[1,0]
	v_pk_mul_f32 v[48:49], v[40:41], 0.5 op_sel_hi:[1,0]
	v_pk_mul_f32 v[54:55], v[34:35], 0.5 op_sel_hi:[1,0]
	v_pk_mul_f32 v[52:53], v[32:33], 0.5 op_sel_hi:[1,0]
	v_pk_mul_f32 v[34:35], v[94:95], 0.5 op_sel_hi:[1,0]
	v_pk_mul_f32 v[32:33], v[92:93], 0.5 op_sel_hi:[1,0]
	v_pk_mul_f32 v[42:43], v[86:87], 0.5 op_sel_hi:[1,0]
	v_pk_mul_f32 v[40:41], v[84:85], 0.5 op_sel_hi:[1,0]
	v_pk_mul_f32 v[58:59], v[58:59], 0.5 op_sel_hi:[1,0]
	v_pk_mul_f32 v[56:57], v[56:57], 0.5 op_sel_hi:[1,0]
	v_pk_mul_f32 v[62:63], v[62:63], 0.5 op_sel_hi:[1,0]
	v_pk_mul_f32 v[60:61], v[60:61], 0.5 op_sel_hi:[1,0]
	v_pk_mul_f32 v[66:67], v[66:67], 0.5 op_sel_hi:[1,0]
	v_pk_mul_f32 v[64:65], v[64:65], 0.5 op_sel_hi:[1,0]
	v_pk_mul_f32 v[70:71], v[70:71], 0.5 op_sel_hi:[1,0]
	v_pk_mul_f32 v[68:69], v[68:69], 0.5 op_sel_hi:[1,0]
	v_pk_mul_f32 v[86:87], v[78:79], 0.5 op_sel_hi:[1,0]
	v_pk_mul_f32 v[84:85], v[76:77], 0.5 op_sel_hi:[1,0]
	v_pk_mul_f32 v[94:95], v[74:75], 0.5 op_sel_hi:[1,0]
	v_pk_mul_f32 v[92:93], v[72:73], 0.5 op_sel_hi:[1,0]
	v_pk_mul_f32 v[74:75], v[110:111], 0.5 op_sel_hi:[1,0]
	v_pk_mul_f32 v[72:73], v[108:109], 0.5 op_sel_hi:[1,0]
	v_pk_mul_f32 v[78:79], v[102:103], 0.5 op_sel_hi:[1,0]
	v_pk_mul_f32 v[76:77], v[100:101], 0.5 op_sel_hi:[1,0]
	v_pk_mul_f32 v[102:103], v[90:91], 0.5 op_sel_hi:[1,0]
	v_pk_mul_f32 v[100:101], v[88:89], 0.5 op_sel_hi:[1,0]
	v_pk_mul_f32 v[110:111], v[82:83], 0.5 op_sel_hi:[1,0]
	v_pk_mul_f32 v[108:109], v[80:81], 0.5 op_sel_hi:[1,0]
	v_pk_mul_f32 v[82:83], v[118:119], 0.5 op_sel_hi:[1,0]
	v_pk_mul_f32 v[80:81], v[116:117], 0.5 op_sel_hi:[1,0]
	v_pk_mul_f32 v[90:91], v[114:115], 0.5 op_sel_hi:[1,0]
	v_pk_mul_f32 v[88:89], v[112:113], 0.5 op_sel_hi:[1,0]
	v_pk_mul_f32 v[114:115], v[106:107], 0.5 op_sel_hi:[1,0]
	v_pk_mul_f32 v[112:113], v[104:105], 0.5 op_sel_hi:[1,0]
	v_pk_mul_f32 v[118:119], v[98:99], 0.5 op_sel_hi:[1,0]
	v_pk_mul_f32 v[116:117], v[96:97], 0.5 op_sel_hi:[1,0]
	v_pk_mul_f32 v[98:99], v[134:135], 0.5 op_sel_hi:[1,0]
	v_pk_mul_f32 v[96:97], v[132:133], 0.5 op_sel_hi:[1,0]
	v_pk_mul_f32 v[106:107], v[130:131], 0.5 op_sel_hi:[1,0]
	v_pk_mul_f32 v[104:105], v[128:129], 0.5 op_sel_hi:[1,0]
	v_pk_mul_f32 v[122:123], v[122:123], 0.5 op_sel_hi:[1,0]
	v_pk_mul_f32 v[120:121], v[120:121], 0.5 op_sel_hi:[1,0]
	v_pk_mul_f32 v[126:127], v[126:127], 0.5 op_sel_hi:[1,0]
	v_pk_mul_f32 v[124:125], v[124:125], 0.5 op_sel_hi:[1,0]
	s_branch .LBB0_1903
